# v13 + H tile loads of the residual epilogues (down1/out/down2) issued up front instead of one round trip per row
# speedup vs baseline: 1.0031x; 1.0031x over previous
; __device__ __forceinline__ unsigned cvt_pk_bf16(float lo, float hi) { unsigned r; asm volatile("v_cvt_pk_bf16_f32 %0, %1, %2" : "=v"(r) : "v"(lo), "v"(hi)); return r; }
;     __device__ __forceinline__ void operator()(const f32x4 (&acc)[2][2][4][2], const Unit& u, int wr, int wc, int fr, int fq) const {
;     ...
;             for (int m = 0; m < 4; ++m) { const int row = row0 + ai * HALF + m * 16; const size_t ro = (size_t)row * ldc + col0;
;                 float rs = 1.0f; if (GATED) rs = rs_of(rsq_in, row);
;                 float ss = 0.f;
; #pragma unroll
;                 for (int bj = 0; bj < 2; ++bj) { u32x4* p = (u32x4*)(H + ro + bj * HALF); const u32x4 hw = *p; const f32x4 a0 = acc[ai][bj][m][0], a1 = acc[ai][bj][m][1];
;                     float h[8] = {bf_lo(hw.x), bf_hi(hw.x), bf_lo(hw.y), bf_hi(hw.y), bf_lo(hw.z), bf_hi(hw.z), bf_lo(hw.w), bf_hi(hw.w)};
;                     if (GATED) { const u32x4 pw = *(const u32x4*)(PP + ro + bj * HALF);
;                         const float pp[8] = {bf_lo(pw.x), bf_hi(pw.x), bf_lo(pw.y), bf_hi(pw.y), bf_lo(pw.z), bf_hi(pw.z), bf_lo(pw.w), bf_hi(pw.w)};
; #pragma unroll
;                         for (int j = 0; j < 4; ++j) { h[j] += __builtin_amdgcn_rcpf(1.0f + __builtin_amdgcn_exp2f(-1.4426950408889634f * rs * a0[j])) * pp[j];
;                                                       h[4 + j] += __builtin_amdgcn_rcpf(1.0f + __builtin_amdgcn_exp2f(-1.4426950408889634f * rs * a1[j])) * pp[4 + j]; } }
;                     else {
; #pragma unroll
;                         for (int j = 0; j < 4; ++j) { h[j] += a0[j] * scale; h[4 + j] += a1[j] * scale; } }
;                     u32x4 w; w.x = cvt_pk_bf16(h[0], h[1]); w.y = cvt_pk_bf16(h[2], h[3]); w.z = cvt_pk_bf16(h[4], h[5]); w.w = cvt_pk_bf16(h[6], h[7]);
;                     *p = w; if (CP) *(u32x4*)(CP + ro + bj * HALF) = w;
;                     if (rsq_out) { const float r0 = bf_lo(w.x), r1 = bf_hi(w.x), r2 = bf_lo(w.y), r3 = bf_hi(w.y), r4 = bf_lo(w.z), r5 = bf_hi(w.z), r6 = bf_lo(w.w), r7 = bf_hi(w.w);
;                         ss += ((r0 * r0 + r1 * r1) + (r2 * r2 + r3 * r3)) + ((r4 * r4 + r5 * r5) + (r6 * r6 + r7 * r7)); } }
;                 if (rsq_out) { ss = sum_fq(ss); if (fq == 0) __hip_atomic_fetch_add(rsq_out + row, rsq_fix(ss), __ATOMIC_RELAXED, __HIP_MEMORY_SCOPE_AGENT); } }
.LBB0_654:
	v_lshl_add_u32 v144, s1, 8, v146
	v_ashrrev_i32_e32 v145, 31, v144
	v_lshl_add_u32 v142, s42, 8, v148
	v_lshlrev_b64 v[140:141], 12, v[144:145]
	v_ashrrev_i32_e32 v143, 31, v142
	v_lshl_add_u64 v[140:141], s[20:21], 0, v[140:141]
	v_lshl_add_u64 v[140:141], v[142:143], 1, v[140:141]
	global_load_dwordx4 v[150:153], v[140:141], off
	v_mov_b32_e32 v224, 0x10000
	v_mov_b32_e32 v225, 0
	global_load_dwordx4 v[208:211], v[140:141], off offset:256
	v_lshl_add_u64 v[226:227], v[224:225], 0, v[140:141]
	global_load_dwordx4 v[158:161], v[226:227], off
	global_load_dwordx4 v[212:215], v[226:227], off offset:256
	v_lshl_add_u64 v[226:227], v[224:225], 0, v[226:227]
	global_load_dwordx4 v[162:165], v[226:227], off
	global_load_dwordx4 v[216:219], v[226:227], off offset:256
	v_lshl_add_u64 v[226:227], v[224:225], 0, v[226:227]
	global_load_dwordx4 v[166:169], v[226:227], off
	global_load_dwordx4 v[220:223], v[226:227], off offset:256
	v_lshl_add_u64 v[226:227], v[224:225], 3, v[140:141]
	global_load_dwordx4 v[170:173], v[226:227], off
	v_lshl_add_u64 v[226:227], v[224:225], 0, v[226:227]
	global_load_dwordx4 v[174:177], v[226:227], off
	v_lshl_add_u64 v[226:227], v[224:225], 0, v[226:227]
	global_load_dwordx4 v[190:193], v[226:227], off
	v_lshl_add_u64 v[226:227], v[224:225], 0, v[226:227]
	global_load_dwordx4 v[194:197], v[226:227], off
	s_waitcnt vmcnt(0)
	v_lshlrev_b32_e32 v154, 16, v150
	v_and_b32_e32 v150, 0xffff0000, v150
	v_lshlrev_b32_e32 v155, 16, v151
	v_and_b32_e32 v151, 0xffff0000, v151
	v_lshlrev_b32_e32 v156, 16, v152
	v_and_b32_e32 v152, 0xffff0000, v152
	v_lshlrev_b32_e32 v157, 16, v153
	v_and_b32_e32 v153, 0xffff0000, v153
	v_fmac_f32_e32 v154, 0.5, v126
	v_fmac_f32_e32 v156, 0.5, v122
	v_fmac_f32_e32 v150, 0.5, v127
	v_fmac_f32_e32 v152, 0.5, v123
	v_fmac_f32_e32 v155, 0.5, v128
	v_fmac_f32_e32 v157, 0.5, v124
	v_fmac_f32_e32 v151, 0.5, v129
	v_fmac_f32_e32 v153, 0.5, v125
	v_cvt_pk_bf16_f32 v122, v154, v150
	v_cvt_pk_bf16_f32 v123, v155, v151
	v_cvt_pk_bf16_f32 v124, v156, v152
	v_cvt_pk_bf16_f32 v125, v157, v153
	v_mov_b32_e32 v126, v208
	v_mov_b32_e32 v127, v209
	v_mov_b32_e32 v128, v210
	v_mov_b32_e32 v129, v211
	v_lshlrev_b32_e32 v150, 16, v122
	global_store_dwordx4 v[140:141], v[122:125], off
	v_lshlrev_b32_e32 v151, 16, v123
	v_lshlrev_b32_e32 v152, 16, v124
	v_and_b32_e32 v122, 0xffff0000, v122
	v_and_b32_e32 v123, 0xffff0000, v123
	v_and_b32_e32 v124, 0xffff0000, v124
	v_lshlrev_b32_e32 v153, 16, v125
	v_and_b32_e32 v125, 0xffff0000, v125
	v_mul_f32_e32 v122, v122, v122
	v_mul_f32_e32 v123, v123, v123
	v_mul_f32_e32 v124, v124, v124
	v_mul_f32_e32 v125, v125, v125
	v_fmac_f32_e32 v122, v150, v150
	v_fmac_f32_e32 v123, v151, v151
	v_fmac_f32_e32 v124, v152, v152
	v_fmac_f32_e32 v125, v153, v153
	v_add_f32_e32 v122, v122, v123
	v_add_f32_e32 v123, v124, v125
	v_add_f32_e32 v122, v122, v123
	v_lshlrev_b32_e32 v123, 16, v126
	v_and_b32_e32 v124, 0xffff0000, v126
	v_lshlrev_b32_e32 v125, 16, v127
	v_and_b32_e32 v126, 0xffff0000, v127
	v_lshlrev_b32_e32 v127, 16, v128
	v_and_b32_e32 v128, 0xffff0000, v128
	v_lshlrev_b32_e32 v150, 16, v129
	v_and_b32_e32 v129, 0xffff0000, v129
	v_fmac_f32_e32 v123, 0.5, v118
	v_fmac_f32_e32 v127, 0.5, v114
	v_fmac_f32_e32 v124, 0.5, v119
	v_fmac_f32_e32 v128, 0.5, v115
	v_fmac_f32_e32 v125, 0.5, v120
	v_fmac_f32_e32 v150, 0.5, v116
	v_fmac_f32_e32 v126, 0.5, v121
	v_fmac_f32_e32 v129, 0.5, v117
	v_cvt_pk_bf16_f32 v114, v123, v124
	v_cvt_pk_bf16_f32 v115, v125, v126
	v_cvt_pk_bf16_f32 v116, v127, v128
	v_cvt_pk_bf16_f32 v117, v150, v129
	global_store_dwordx4 v[140:141], v[114:117], off offset:256
	v_lshlrev_b32_e32 v118, 16, v114
	v_lshlrev_b32_e32 v119, 16, v115
	v_and_b32_e32 v114, 0xffff0000, v114
	v_and_b32_e32 v115, 0xffff0000, v115
	v_lshlrev_b32_e32 v120, 16, v116
	v_and_b32_e32 v116, 0xffff0000, v116
	v_lshlrev_b32_e32 v121, 16, v117
	v_and_b32_e32 v117, 0xffff0000, v117
	v_mul_f32_e32 v114, v114, v114
	v_mul_f32_e32 v115, v115, v115
	v_mul_f32_e32 v116, v116, v116
	v_mul_f32_e32 v117, v117, v117
	v_fmac_f32_e32 v114, v118, v118
	v_fmac_f32_e32 v115, v119, v119
	v_fmac_f32_e32 v116, v120, v120
	v_fmac_f32_e32 v117, v121, v121
	v_add_f32_e32 v114, v114, v115
	v_add_f32_e32 v115, v116, v117
	v_add_f32_e32 v114, v114, v115
	v_add_f32_e32 v114, v122, v114
	v_mov_b32_e32 v115, v114
	s_nop 1
	v_permlane16_swap_b32_e32 v114, v115
	v_add_f32_e32 v116, v114, v115
	v_mov_b32_e32 v117, v116
	s_nop 1
	v_permlane32_swap_b32_e32 v116, v117
	v_lshl_add_u64 v[114:115], v[144:145], 3, s[22:23]
	s_and_saveexec_b64 s[2:3], s[8:9]
	s_cbranch_execz .LBB0_656
	v_add_f32_e32 v116, v116, v117
	s_mov_b32 s1, 0x49800000
	v_fma_f32 v116, v116, s1, 0.5
	v_trunc_f32_e32 v116, v116
	v_mul_f32_e32 v117, 0x2f800000, v116
	v_floor_f32_e32 v117, v117
	v_fmac_f32_e32 v116, 0xcf800000, v117
	v_cvt_u32_f32_e32 v116, v116
	v_cvt_u32_f32_e32 v117, v117
	global_atomic_add_x2 v[114:115], v[116:117], off
; __device__ __forceinline__ unsigned cvt_pk_bf16(float lo, float hi) { unsigned r; asm volatile("v_cvt_pk_bf16_f32 %0, %1, %2" : "=v"(r) : "v"(lo), "v"(hi)); return r; }
;     __device__ __forceinline__ void operator()(const f32x4 (&acc)[2][2][4][2], const Unit& u, int wr, int wc, int fr, int fq) const {
;     ...
;             for (int m = 0; m < 4; ++m) { const int row = row0 + ai * HALF + m * 16; const size_t ro = (size_t)row * ldc + col0;
;                 float rs = 1.0f; if (GATED) rs = rs_of(rsq_in, row);
;                 float ss = 0.f;
; #pragma unroll
;                 for (int bj = 0; bj < 2; ++bj) { u32x4* p = (u32x4*)(H + ro + bj * HALF); const u32x4 hw = *p; const f32x4 a0 = acc[ai][bj][m][0], a1 = acc[ai][bj][m][1];
;                     float h[8] = {bf_lo(hw.x), bf_hi(hw.x), bf_lo(hw.y), bf_hi(hw.y), bf_lo(hw.z), bf_hi(hw.z), bf_lo(hw.w), bf_hi(hw.w)};
;                     if (GATED) { const u32x4 pw = *(const u32x4*)(PP + ro + bj * HALF);
;                         const float pp[8] = {bf_lo(pw.x), bf_hi(pw.x), bf_lo(pw.y), bf_hi(pw.y), bf_lo(pw.z), bf_hi(pw.z), bf_lo(pw.w), bf_hi(pw.w)};
; #pragma unroll
;                         for (int j = 0; j < 4; ++j) { h[j] += __builtin_amdgcn_rcpf(1.0f + __builtin_amdgcn_exp2f(-1.4426950408889634f * rs * a0[j])) * pp[j];
;                                                       h[4 + j] += __builtin_amdgcn_rcpf(1.0f + __builtin_amdgcn_exp2f(-1.4426950408889634f * rs * a1[j])) * pp[4 + j]; } }
;                     else {
; #pragma unroll
;                         for (int j = 0; j < 4; ++j) { h[j] += a0[j] * scale; h[4 + j] += a1[j] * scale; } }
;                     u32x4 w; w.x = cvt_pk_bf16(h[0], h[1]); w.y = cvt_pk_bf16(h[2], h[3]); w.z = cvt_pk_bf16(h[4], h[5]); w.w = cvt_pk_bf16(h[6], h[7]);
;                     *p = w; if (CP) *(u32x4*)(CP + ro + bj * HALF) = w;
;                     if (rsq_out) { const float r0 = bf_lo(w.x), r1 = bf_hi(w.x), r2 = bf_lo(w.y), r3 = bf_hi(w.y), r4 = bf_lo(w.z), r5 = bf_hi(w.z), r6 = bf_lo(w.w), r7 = bf_hi(w.w);
;                         ss += ((r0 * r0 + r1 * r1) + (r2 * r2 + r3 * r3)) + ((r4 * r4 + r5 * r5) + (r6 * r6 + r7 * r7)); } }
;                 if (rsq_out) { ss = sum_fq(ss); if (fq == 0) __hip_atomic_fetch_add(rsq_out + row, rsq_fix(ss), __ATOMIC_RELAXED, __HIP_MEMORY_SCOPE_AGENT); } }
.LBB0_656:
	s_or_b64 exec, exec, s[2:3]
	v_or_b32_e32 v116, 16, v144
	v_ashrrev_i32_e32 v117, 31, v116
	v_lshlrev_b64 v[116:117], 12, v[116:117]
	v_lshl_add_u64 v[116:117], s[20:21], 0, v[116:117]
	v_lshl_add_u64 v[120:121], v[142:143], 1, v[116:117]
	v_mov_b32_e32 v116, v158
	v_mov_b32_e32 v117, v159
	v_mov_b32_e32 v118, v160
	v_mov_b32_e32 v119, v161
	v_lshlrev_b32_e32 v122, 16, v116
	v_and_b32_e32 v116, 0xffff0000, v116
	v_lshlrev_b32_e32 v123, 16, v117
	v_and_b32_e32 v117, 0xffff0000, v117
	v_lshlrev_b32_e32 v124, 16, v118
	v_and_b32_e32 v118, 0xffff0000, v118
	v_lshlrev_b32_e32 v125, 16, v119
	v_and_b32_e32 v119, 0xffff0000, v119
	v_fmac_f32_e32 v122, 0.5, v110
	v_fmac_f32_e32 v124, 0.5, v106
	v_fmac_f32_e32 v116, 0.5, v111
	v_fmac_f32_e32 v118, 0.5, v107
	v_fmac_f32_e32 v123, 0.5, v112
	v_fmac_f32_e32 v125, 0.5, v108
	v_fmac_f32_e32 v117, 0.5, v113
	v_fmac_f32_e32 v119, 0.5, v109
	v_cvt_pk_bf16_f32 v106, v122, v116
	v_cvt_pk_bf16_f32 v107, v123, v117
	v_cvt_pk_bf16_f32 v108, v124, v118
	v_cvt_pk_bf16_f32 v109, v125, v119
	v_mov_b32_e32 v110, v212
	v_mov_b32_e32 v111, v213
	v_mov_b32_e32 v112, v214
	v_mov_b32_e32 v113, v215
	v_lshlrev_b32_e32 v116, 16, v106
	global_store_dwordx4 v[120:121], v[106:109], off
	v_lshlrev_b32_e32 v117, 16, v107
	v_lshlrev_b32_e32 v118, 16, v108
	v_and_b32_e32 v106, 0xffff0000, v106
	v_and_b32_e32 v107, 0xffff0000, v107
	v_and_b32_e32 v108, 0xffff0000, v108
	v_lshlrev_b32_e32 v119, 16, v109
	v_and_b32_e32 v109, 0xffff0000, v109
	v_mul_f32_e32 v106, v106, v106
	v_mul_f32_e32 v107, v107, v107
	v_mul_f32_e32 v108, v108, v108
	v_mul_f32_e32 v109, v109, v109
	v_fmac_f32_e32 v106, v116, v116
	v_fmac_f32_e32 v107, v117, v117
	v_fmac_f32_e32 v108, v118, v118
	v_fmac_f32_e32 v109, v119, v119
	v_add_f32_e32 v106, v106, v107
	v_add_f32_e32 v107, v108, v109
	v_add_f32_e32 v106, v106, v107
	v_lshlrev_b32_e32 v107, 16, v110
	v_and_b32_e32 v108, 0xffff0000, v110
	v_lshlrev_b32_e32 v109, 16, v111
	v_and_b32_e32 v110, 0xffff0000, v111
	v_lshlrev_b32_e32 v111, 16, v112
	v_and_b32_e32 v112, 0xffff0000, v112
	v_lshlrev_b32_e32 v116, 16, v113
	v_and_b32_e32 v113, 0xffff0000, v113
	v_fmac_f32_e32 v107, 0.5, v102
	v_fmac_f32_e32 v111, 0.5, v98
	v_fmac_f32_e32 v108, 0.5, v103
	v_fmac_f32_e32 v112, 0.5, v99
	v_fmac_f32_e32 v109, 0.5, v104
	v_fmac_f32_e32 v116, 0.5, v100
	v_fmac_f32_e32 v110, 0.5, v105
	v_fmac_f32_e32 v113, 0.5, v101
	v_cvt_pk_bf16_f32 v98, v107, v108
	v_cvt_pk_bf16_f32 v99, v109, v110
	v_cvt_pk_bf16_f32 v100, v111, v112
	v_cvt_pk_bf16_f32 v101, v116, v113
	global_store_dwordx4 v[120:121], v[98:101], off offset:256
	v_lshlrev_b32_e32 v102, 16, v98
	v_lshlrev_b32_e32 v103, 16, v99
	v_and_b32_e32 v98, 0xffff0000, v98
	v_and_b32_e32 v99, 0xffff0000, v99
	v_lshlrev_b32_e32 v104, 16, v100
	v_and_b32_e32 v100, 0xffff0000, v100
	v_lshlrev_b32_e32 v105, 16, v101
	v_and_b32_e32 v101, 0xffff0000, v101
	v_mul_f32_e32 v98, v98, v98
	v_mul_f32_e32 v99, v99, v99
	v_mul_f32_e32 v100, v100, v100
	v_mul_f32_e32 v101, v101, v101
	v_fmac_f32_e32 v98, v102, v102
	v_fmac_f32_e32 v99, v103, v103
	v_fmac_f32_e32 v100, v104, v104
	v_fmac_f32_e32 v101, v105, v105
	v_add_f32_e32 v98, v98, v99
	v_add_f32_e32 v99, v100, v101
	v_add_f32_e32 v98, v98, v99
	v_add_f32_e32 v98, v106, v98
	v_mov_b32_e32 v99, v98
	s_nop 1
	v_permlane16_swap_b32_e32 v98, v99
	v_add_f32_e32 v98, v98, v99
	v_mov_b32_e32 v99, v98
	s_nop 1
	v_permlane32_swap_b32_e32 v98, v99
	s_and_saveexec_b64 s[2:3], s[8:9]
	s_cbranch_execz .LBB0_658
	v_add_f32_e32 v98, v98, v99
	s_mov_b32 s1, 0x49800000
	v_fma_f32 v98, v98, s1, 0.5
	v_trunc_f32_e32 v98, v98
	v_mul_f32_e32 v99, 0x2f800000, v98
	v_floor_f32_e32 v99, v99
	v_fmac_f32_e32 v98, 0xcf800000, v99
	v_cvt_u32_f32_e32 v98, v98
	v_cvt_u32_f32_e32 v99, v99
	global_atomic_add_x2 v[114:115], v[98:99], off offset:128
.LBB0_658:
	s_or_b64 exec, exec, s[2:3]
	v_or_b32_e32 v98, 32, v144
	v_ashrrev_i32_e32 v99, 31, v98
	v_lshlrev_b64 v[98:99], 12, v[98:99]
	v_lshl_add_u64 v[98:99], s[20:21], 0, v[98:99]
	v_lshl_add_u64 v[102:103], v[142:143], 1, v[98:99]
	v_mov_b32_e32 v98, v162
	v_mov_b32_e32 v99, v163
	v_mov_b32_e32 v100, v164
	v_mov_b32_e32 v101, v165
	v_lshlrev_b32_e32 v104, 16, v98
	v_and_b32_e32 v98, 0xffff0000, v98
	v_lshlrev_b32_e32 v105, 16, v99
	v_and_b32_e32 v99, 0xffff0000, v99
	v_lshlrev_b32_e32 v106, 16, v100
	v_and_b32_e32 v100, 0xffff0000, v100
	v_lshlrev_b32_e32 v107, 16, v101
	v_and_b32_e32 v101, 0xffff0000, v101
	v_fmac_f32_e32 v104, 0.5, v94
	v_fmac_f32_e32 v106, 0.5, v90
	v_fmac_f32_e32 v98, 0.5, v95
	v_fmac_f32_e32 v100, 0.5, v91
	v_fmac_f32_e32 v105, 0.5, v96
	v_fmac_f32_e32 v107, 0.5, v92
	v_fmac_f32_e32 v99, 0.5, v97
	v_fmac_f32_e32 v101, 0.5, v93
	v_cvt_pk_bf16_f32 v90, v104, v98
	v_cvt_pk_bf16_f32 v91, v105, v99
	v_cvt_pk_bf16_f32 v92, v106, v100
	v_cvt_pk_bf16_f32 v93, v107, v101
	v_mov_b32_e32 v94, v216
	v_mov_b32_e32 v95, v217
	v_mov_b32_e32 v96, v218
	v_mov_b32_e32 v97, v219
	v_lshlrev_b32_e32 v98, 16, v90
	global_store_dwordx4 v[102:103], v[90:93], off
	v_lshlrev_b32_e32 v99, 16, v91
	v_lshlrev_b32_e32 v100, 16, v92
	v_and_b32_e32 v90, 0xffff0000, v90
	v_and_b32_e32 v91, 0xffff0000, v91
	v_and_b32_e32 v92, 0xffff0000, v92
	v_lshlrev_b32_e32 v101, 16, v93
	v_and_b32_e32 v93, 0xffff0000, v93
	v_mul_f32_e32 v90, v90, v90
	v_mul_f32_e32 v91, v91, v91
	v_mul_f32_e32 v92, v92, v92
	v_mul_f32_e32 v93, v93, v93
	v_fmac_f32_e32 v90, v98, v98
	v_fmac_f32_e32 v91, v99, v99
	v_fmac_f32_e32 v92, v100, v100
	v_fmac_f32_e32 v93, v101, v101
	v_add_f32_e32 v90, v90, v91
	v_add_f32_e32 v91, v92, v93
	v_add_f32_e32 v90, v90, v91
	v_lshlrev_b32_e32 v91, 16, v94
	v_and_b32_e32 v92, 0xffff0000, v94
	v_lshlrev_b32_e32 v93, 16, v95
; __device__ __forceinline__ unsigned cvt_pk_bf16(float lo, float hi) { unsigned r; asm volatile("v_cvt_pk_bf16_f32 %0, %1, %2" : "=v"(r) : "v"(lo), "v"(hi)); return r; }
;     __device__ __forceinline__ void operator()(const f32x4 (&acc)[2][2][4][2], const Unit& u, int wr, int wc, int fr, int fq) const {
;     ...
;             for (int m = 0; m < 4; ++m) { const int row = row0 + ai * HALF + m * 16; const size_t ro = (size_t)row * ldc + col0;
;                 float rs = 1.0f; if (GATED) rs = rs_of(rsq_in, row);
;                 float ss = 0.f;
; #pragma unroll
;                 for (int bj = 0; bj < 2; ++bj) { u32x4* p = (u32x4*)(H + ro + bj * HALF); const u32x4 hw = *p; const f32x4 a0 = acc[ai][bj][m][0], a1 = acc[ai][bj][m][1];
;                     float h[8] = {bf_lo(hw.x), bf_hi(hw.x), bf_lo(hw.y), bf_hi(hw.y), bf_lo(hw.z), bf_hi(hw.z), bf_lo(hw.w), bf_hi(hw.w)};
;                     if (GATED) { const u32x4 pw = *(const u32x4*)(PP + ro + bj * HALF);
;                         const float pp[8] = {bf_lo(pw.x), bf_hi(pw.x), bf_lo(pw.y), bf_hi(pw.y), bf_lo(pw.z), bf_hi(pw.z), bf_lo(pw.w), bf_hi(pw.w)};
; #pragma unroll
;                         for (int j = 0; j < 4; ++j) { h[j] += __builtin_amdgcn_rcpf(1.0f + __builtin_amdgcn_exp2f(-1.4426950408889634f * rs * a0[j])) * pp[j];
;                                                       h[4 + j] += __builtin_amdgcn_rcpf(1.0f + __builtin_amdgcn_exp2f(-1.4426950408889634f * rs * a1[j])) * pp[4 + j]; } }
;                     else {
; #pragma unroll
;                         for (int j = 0; j < 4; ++j) { h[j] += a0[j] * scale; h[4 + j] += a1[j] * scale; } }
;                     u32x4 w; w.x = cvt_pk_bf16(h[0], h[1]); w.y = cvt_pk_bf16(h[2], h[3]); w.z = cvt_pk_bf16(h[4], h[5]); w.w = cvt_pk_bf16(h[6], h[7]);
;                     *p = w; if (CP) *(u32x4*)(CP + ro + bj * HALF) = w;
;                     if (rsq_out) { const float r0 = bf_lo(w.x), r1 = bf_hi(w.x), r2 = bf_lo(w.y), r3 = bf_hi(w.y), r4 = bf_lo(w.z), r5 = bf_hi(w.z), r6 = bf_lo(w.w), r7 = bf_hi(w.w);
;                         ss += ((r0 * r0 + r1 * r1) + (r2 * r2 + r3 * r3)) + ((r4 * r4 + r5 * r5) + (r6 * r6 + r7 * r7)); } }
;                 if (rsq_out) { ss = sum_fq(ss); if (fq == 0) __hip_atomic_fetch_add(rsq_out + row, rsq_fix(ss), __ATOMIC_RELAXED, __HIP_MEMORY_SCOPE_AGENT); } }
	v_and_b32_e32 v94, 0xffff0000, v95
	v_lshlrev_b32_e32 v95, 16, v96
	v_and_b32_e32 v96, 0xffff0000, v96
	v_lshlrev_b32_e32 v98, 16, v97
	v_and_b32_e32 v97, 0xffff0000, v97
	v_fmac_f32_e32 v91, 0.5, v86
	v_fmac_f32_e32 v95, 0.5, v82
	v_fmac_f32_e32 v92, 0.5, v87
	v_fmac_f32_e32 v96, 0.5, v83
	v_fmac_f32_e32 v93, 0.5, v88
	v_fmac_f32_e32 v98, 0.5, v84
	v_fmac_f32_e32 v94, 0.5, v89
	v_fmac_f32_e32 v97, 0.5, v85
	v_cvt_pk_bf16_f32 v82, v91, v92
	v_cvt_pk_bf16_f32 v83, v93, v94
	v_cvt_pk_bf16_f32 v84, v95, v96
	v_cvt_pk_bf16_f32 v85, v98, v97
	global_store_dwordx4 v[102:103], v[82:85], off offset:256
	v_lshlrev_b32_e32 v86, 16, v82
	v_lshlrev_b32_e32 v87, 16, v83
	v_and_b32_e32 v82, 0xffff0000, v82
	v_and_b32_e32 v83, 0xffff0000, v83
	v_lshlrev_b32_e32 v88, 16, v84
	v_and_b32_e32 v84, 0xffff0000, v84
	v_lshlrev_b32_e32 v89, 16, v85
	v_and_b32_e32 v85, 0xffff0000, v85
	v_mul_f32_e32 v82, v82, v82
	v_mul_f32_e32 v83, v83, v83
	v_mul_f32_e32 v84, v84, v84
	v_mul_f32_e32 v85, v85, v85
	v_fmac_f32_e32 v82, v86, v86
	v_fmac_f32_e32 v83, v87, v87
	v_fmac_f32_e32 v84, v88, v88
	v_fmac_f32_e32 v85, v89, v89
	v_add_f32_e32 v82, v82, v83
	v_add_f32_e32 v83, v84, v85
	v_add_f32_e32 v82, v82, v83
	v_add_f32_e32 v82, v90, v82
	v_mov_b32_e32 v83, v82
	s_nop 1
	v_permlane16_swap_b32_e32 v82, v83
	v_add_f32_e32 v82, v82, v83
	v_mov_b32_e32 v83, v82
	s_nop 1
	v_permlane32_swap_b32_e32 v82, v83
	s_and_saveexec_b64 s[2:3], s[8:9]
	s_cbranch_execz .LBB0_660
	v_add_f32_e32 v82, v82, v83
	s_mov_b32 s1, 0x49800000
	v_fma_f32 v82, v82, s1, 0.5
	v_trunc_f32_e32 v82, v82
	v_mul_f32_e32 v83, 0x2f800000, v82
	v_floor_f32_e32 v83, v83
	v_fmac_f32_e32 v82, 0xcf800000, v83
	v_cvt_u32_f32_e32 v82, v82
	v_cvt_u32_f32_e32 v83, v83
	global_atomic_add_x2 v[114:115], v[82:83], off offset:256
.LBB0_660:
	s_or_b64 exec, exec, s[2:3]
	v_or_b32_e32 v82, 48, v144
	v_ashrrev_i32_e32 v83, 31, v82
	v_lshlrev_b64 v[82:83], 12, v[82:83]
	v_lshl_add_u64 v[82:83], s[20:21], 0, v[82:83]
	v_lshl_add_u64 v[86:87], v[142:143], 1, v[82:83]
	v_mov_b32_e32 v82, v166
	v_mov_b32_e32 v83, v167
	v_mov_b32_e32 v84, v168
	v_mov_b32_e32 v85, v169
	v_lshlrev_b32_e32 v88, 16, v82
	v_and_b32_e32 v82, 0xffff0000, v82
	v_lshlrev_b32_e32 v89, 16, v83
	v_and_b32_e32 v83, 0xffff0000, v83
	v_lshlrev_b32_e32 v90, 16, v84
	v_and_b32_e32 v84, 0xffff0000, v84
	v_lshlrev_b32_e32 v91, 16, v85
	v_and_b32_e32 v85, 0xffff0000, v85
	v_fmac_f32_e32 v88, 0.5, v78
	v_fmac_f32_e32 v90, 0.5, v74
	v_fmac_f32_e32 v82, 0.5, v79
	v_fmac_f32_e32 v84, 0.5, v75
	v_fmac_f32_e32 v89, 0.5, v80
	v_fmac_f32_e32 v91, 0.5, v76
	v_fmac_f32_e32 v83, 0.5, v81
	v_fmac_f32_e32 v85, 0.5, v77
	v_cvt_pk_bf16_f32 v74, v88, v82
	v_cvt_pk_bf16_f32 v75, v89, v83
	v_cvt_pk_bf16_f32 v76, v90, v84
	v_cvt_pk_bf16_f32 v77, v91, v85
	v_mov_b32_e32 v78, v220
	v_mov_b32_e32 v79, v221
	v_mov_b32_e32 v80, v222
	v_mov_b32_e32 v81, v223
	v_lshlrev_b32_e32 v82, 16, v74
	global_store_dwordx4 v[86:87], v[74:77], off
	v_lshlrev_b32_e32 v83, 16, v75
	v_lshlrev_b32_e32 v84, 16, v76
	v_and_b32_e32 v74, 0xffff0000, v74
	v_and_b32_e32 v75, 0xffff0000, v75
	v_and_b32_e32 v76, 0xffff0000, v76
	v_lshlrev_b32_e32 v85, 16, v77
	v_and_b32_e32 v77, 0xffff0000, v77
	v_mul_f32_e32 v74, v74, v74
	v_mul_f32_e32 v75, v75, v75
	v_mul_f32_e32 v76, v76, v76
	v_mul_f32_e32 v77, v77, v77
	v_fmac_f32_e32 v74, v82, v82
	v_fmac_f32_e32 v75, v83, v83
	v_fmac_f32_e32 v76, v84, v84
	v_fmac_f32_e32 v77, v85, v85
	v_add_f32_e32 v74, v74, v75
	v_add_f32_e32 v75, v76, v77
	v_add_f32_e32 v74, v74, v75
	v_lshlrev_b32_e32 v75, 16, v78
	v_and_b32_e32 v76, 0xffff0000, v78
	v_lshlrev_b32_e32 v77, 16, v79
	v_and_b32_e32 v78, 0xffff0000, v79
	v_lshlrev_b32_e32 v79, 16, v80
	v_and_b32_e32 v80, 0xffff0000, v80
	v_lshlrev_b32_e32 v82, 16, v81
	v_and_b32_e32 v81, 0xffff0000, v81
	v_fmac_f32_e32 v75, 0.5, v70
	v_fmac_f32_e32 v79, 0.5, v66
	v_fmac_f32_e32 v76, 0.5, v71
	v_fmac_f32_e32 v80, 0.5, v67
	v_fmac_f32_e32 v77, 0.5, v72
	v_fmac_f32_e32 v82, 0.5, v68
	v_fmac_f32_e32 v78, 0.5, v73
	v_fmac_f32_e32 v81, 0.5, v69
	v_cvt_pk_bf16_f32 v66, v75, v76
	v_cvt_pk_bf16_f32 v67, v77, v78
	v_cvt_pk_bf16_f32 v68, v79, v80
	v_cvt_pk_bf16_f32 v69, v82, v81
	global_store_dwordx4 v[86:87], v[66:69], off offset:256
	v_lshlrev_b32_e32 v70, 16, v66
	v_lshlrev_b32_e32 v71, 16, v67
	v_and_b32_e32 v66, 0xffff0000, v66
	v_and_b32_e32 v67, 0xffff0000, v67
	v_lshlrev_b32_e32 v72, 16, v68
	v_and_b32_e32 v68, 0xffff0000, v68
	v_lshlrev_b32_e32 v73, 16, v69
	v_and_b32_e32 v69, 0xffff0000, v69
	v_mul_f32_e32 v66, v66, v66
	v_mul_f32_e32 v67, v67, v67
	v_mul_f32_e32 v68, v68, v68
	v_mul_f32_e32 v69, v69, v69
	v_fmac_f32_e32 v66, v70, v70
	v_fmac_f32_e32 v67, v71, v71
	v_fmac_f32_e32 v68, v72, v72
	v_fmac_f32_e32 v69, v73, v73
	v_add_f32_e32 v66, v66, v67
	v_add_f32_e32 v67, v68, v69
	v_add_f32_e32 v66, v66, v67
	v_add_f32_e32 v66, v74, v66
	v_mov_b32_e32 v67, v66
	s_nop 1
	v_permlane16_swap_b32_e32 v66, v67
	v_add_f32_e32 v66, v66, v67
	v_mov_b32_e32 v67, v66
	s_nop 1
	v_permlane32_swap_b32_e32 v66, v67
	s_and_saveexec_b64 s[2:3], s[8:9]
	s_cbranch_execz .LBB0_662
	v_add_f32_e32 v66, v66, v67
	s_mov_b32 s1, 0x49800000
	v_fma_f32 v66, v66, s1, 0.5
	v_trunc_f32_e32 v66, v66
	v_mul_f32_e32 v67, 0x2f800000, v66
	v_floor_f32_e32 v67, v67
	v_fmac_f32_e32 v66, 0xcf800000, v67
	v_cvt_u32_f32_e32 v66, v66
	v_cvt_u32_f32_e32 v67, v67
	global_atomic_add_x2 v[114:115], v[66:67], off offset:384
; __device__ __forceinline__ unsigned cvt_pk_bf16(float lo, float hi) { unsigned r; asm volatile("v_cvt_pk_bf16_f32 %0, %1, %2" : "=v"(r) : "v"(lo), "v"(hi)); return r; }
;     __device__ __forceinline__ void operator()(const f32x4 (&acc)[2][2][4][2], const Unit& u, int wr, int wc, int fr, int fq) const {
;     ...
;             for (int m = 0; m < 4; ++m) { const int row = row0 + ai * HALF + m * 16; const size_t ro = (size_t)row * ldc + col0;
;                 float rs = 1.0f; if (GATED) rs = rs_of(rsq_in, row);
;                 float ss = 0.f;
; #pragma unroll
;                 for (int bj = 0; bj < 2; ++bj) { u32x4* p = (u32x4*)(H + ro + bj * HALF); const u32x4 hw = *p; const f32x4 a0 = acc[ai][bj][m][0], a1 = acc[ai][bj][m][1];
;                     float h[8] = {bf_lo(hw.x), bf_hi(hw.x), bf_lo(hw.y), bf_hi(hw.y), bf_lo(hw.z), bf_hi(hw.z), bf_lo(hw.w), bf_hi(hw.w)};
;                     if (GATED) { const u32x4 pw = *(const u32x4*)(PP + ro + bj * HALF);
;                         const float pp[8] = {bf_lo(pw.x), bf_hi(pw.x), bf_lo(pw.y), bf_hi(pw.y), bf_lo(pw.z), bf_hi(pw.z), bf_lo(pw.w), bf_hi(pw.w)};
; #pragma unroll
;                         for (int j = 0; j < 4; ++j) { h[j] += __builtin_amdgcn_rcpf(1.0f + __builtin_amdgcn_exp2f(-1.4426950408889634f * rs * a0[j])) * pp[j];
;                                                       h[4 + j] += __builtin_amdgcn_rcpf(1.0f + __builtin_amdgcn_exp2f(-1.4426950408889634f * rs * a1[j])) * pp[4 + j]; } }
;                     else {
; #pragma unroll
;                         for (int j = 0; j < 4; ++j) { h[j] += a0[j] * scale; h[4 + j] += a1[j] * scale; } }
;                     u32x4 w; w.x = cvt_pk_bf16(h[0], h[1]); w.y = cvt_pk_bf16(h[2], h[3]); w.z = cvt_pk_bf16(h[4], h[5]); w.w = cvt_pk_bf16(h[6], h[7]);
;                     *p = w; if (CP) *(u32x4*)(CP + ro + bj * HALF) = w;
;                     if (rsq_out) { const float r0 = bf_lo(w.x), r1 = bf_hi(w.x), r2 = bf_lo(w.y), r3 = bf_hi(w.y), r4 = bf_lo(w.z), r5 = bf_hi(w.z), r6 = bf_lo(w.w), r7 = bf_hi(w.w);
;                         ss += ((r0 * r0 + r1 * r1) + (r2 * r2 + r3 * r3)) + ((r4 * r4 + r5 * r5) + (r6 * r6 + r7 * r7)); } }
;                 if (rsq_out) { ss = sum_fq(ss); if (fq == 0) __hip_atomic_fetch_add(rsq_out + row, rsq_fix(ss), __ATOMIC_RELAXED, __HIP_MEMORY_SCOPE_AGENT); } }
.LBB0_662:
	s_or_b64 exec, exec, s[2:3]
	v_add_co_u32_e32 v70, vcc, 0x80000, v140
	s_mov_b64 s[2:3], 0x80000
	s_nop 0
	v_addc_co_u32_e32 v71, vcc, 0, v141, vcc
	v_mov_b32_e32 v66, v170
	v_mov_b32_e32 v67, v171
	v_mov_b32_e32 v68, v172
	v_mov_b32_e32 v69, v173
	v_lshl_add_u64 v[72:73], v[140:141], 0, s[2:3]
	v_lshlrev_b32_e32 v74, 16, v66
	v_and_b32_e32 v66, 0xffff0000, v66
	v_lshlrev_b32_e32 v75, 16, v67
	v_and_b32_e32 v67, 0xffff0000, v67
	v_lshlrev_b32_e32 v76, 16, v68
	v_and_b32_e32 v68, 0xffff0000, v68
	v_lshlrev_b32_e32 v77, 16, v69
	v_and_b32_e32 v69, 0xffff0000, v69
	v_fmac_f32_e32 v74, 0.5, v62
	v_fmac_f32_e32 v76, 0.5, v58
	v_fmac_f32_e32 v66, 0.5, v63
	v_fmac_f32_e32 v68, 0.5, v59
	v_fmac_f32_e32 v75, 0.5, v64
	v_fmac_f32_e32 v77, 0.5, v60
	v_fmac_f32_e32 v67, 0.5, v65
	v_fmac_f32_e32 v69, 0.5, v61
	v_cvt_pk_bf16_f32 v58, v74, v66
	v_cvt_pk_bf16_f32 v59, v75, v67
	v_cvt_pk_bf16_f32 v60, v76, v68
	v_cvt_pk_bf16_f32 v61, v77, v69
	global_load_dwordx4 v[62:65], v[72:73], off offset:256
	v_lshlrev_b32_e32 v66, 16, v58
	global_store_dwordx4 v[70:71], v[58:61], off
	v_lshlrev_b32_e32 v67, 16, v59
	v_lshlrev_b32_e32 v68, 16, v60
	v_and_b32_e32 v58, 0xffff0000, v58
	v_and_b32_e32 v59, 0xffff0000, v59
	v_and_b32_e32 v60, 0xffff0000, v60
	v_lshlrev_b32_e32 v69, 16, v61
	v_and_b32_e32 v61, 0xffff0000, v61
	v_mul_f32_e32 v58, v58, v58
	v_mul_f32_e32 v59, v59, v59
	v_mul_f32_e32 v60, v60, v60
	v_mul_f32_e32 v61, v61, v61
	v_fmac_f32_e32 v58, v66, v66
	v_fmac_f32_e32 v59, v67, v67
	v_fmac_f32_e32 v60, v68, v68
	v_fmac_f32_e32 v61, v69, v69
	v_add_f32_e32 v58, v58, v59
	v_add_f32_e32 v59, v60, v61
	v_add_f32_e32 v58, v58, v59
	s_waitcnt vmcnt(1)
	v_lshlrev_b32_e32 v59, 16, v62
	v_and_b32_e32 v60, 0xffff0000, v62
	v_lshlrev_b32_e32 v61, 16, v63
	v_and_b32_e32 v62, 0xffff0000, v63
	v_lshlrev_b32_e32 v63, 16, v64
	v_and_b32_e32 v64, 0xffff0000, v64
	v_lshlrev_b32_e32 v66, 16, v65
	v_and_b32_e32 v65, 0xffff0000, v65
	v_fmac_f32_e32 v59, 0.5, v54
	v_fmac_f32_e32 v63, 0.5, v50
	v_fmac_f32_e32 v60, 0.5, v55
	v_fmac_f32_e32 v64, 0.5, v51
	v_fmac_f32_e32 v61, 0.5, v56
	v_fmac_f32_e32 v66, 0.5, v52
	v_fmac_f32_e32 v62, 0.5, v57
	v_fmac_f32_e32 v65, 0.5, v53
	v_cvt_pk_bf16_f32 v50, v59, v60
	v_cvt_pk_bf16_f32 v51, v61, v62
	v_cvt_pk_bf16_f32 v52, v63, v64
	v_cvt_pk_bf16_f32 v53, v66, v65
	global_store_dwordx4 v[72:73], v[50:53], off offset:256
	v_lshlrev_b32_e32 v54, 16, v50
	v_lshlrev_b32_e32 v55, 16, v51
	v_and_b32_e32 v50, 0xffff0000, v50
	v_and_b32_e32 v51, 0xffff0000, v51
	v_lshlrev_b32_e32 v56, 16, v52
	v_and_b32_e32 v52, 0xffff0000, v52
	v_lshlrev_b32_e32 v57, 16, v53
	v_and_b32_e32 v53, 0xffff0000, v53
	v_mul_f32_e32 v50, v50, v50
	v_mul_f32_e32 v51, v51, v51
	v_mul_f32_e32 v52, v52, v52
	v_mul_f32_e32 v53, v53, v53
	v_fmac_f32_e32 v50, v54, v54
	v_fmac_f32_e32 v51, v55, v55
	v_fmac_f32_e32 v52, v56, v56
	v_fmac_f32_e32 v53, v57, v57
	v_add_f32_e32 v50, v50, v51
	v_add_f32_e32 v51, v52, v53
	v_add_f32_e32 v50, v50, v51
	v_add_f32_e32 v50, v58, v50
	v_mov_b32_e32 v51, v50
	s_nop 1
	v_permlane16_swap_b32_e32 v50, v51
	v_add_f32_e32 v50, v50, v51
	v_mov_b32_e32 v51, v50
	s_nop 1
	v_permlane32_swap_b32_e32 v50, v51
	s_and_saveexec_b64 s[2:3], s[8:9]
	s_cbranch_execz .LBB0_664
	v_add_f32_e32 v50, v50, v51
	s_mov_b32 s1, 0x49800000
	v_fma_f32 v50, v50, s1, 0.5
	v_trunc_f32_e32 v50, v50
	v_mul_f32_e32 v51, 0x2f800000, v50
	v_floor_f32_e32 v51, v51
	v_fmac_f32_e32 v50, 0xcf800000, v51
	v_cvt_u32_f32_e32 v50, v50
	v_cvt_u32_f32_e32 v51, v51
	global_atomic_add_x2 v[114:115], v[50:51], off offset:1024
.LBB0_664:
	s_or_b64 exec, exec, s[2:3]
	v_add_co_u32_e32 v54, vcc, 0x90000, v140
	v_lshl_add_u64 v[56:57], v[140:141], 0, s[54:55]
	s_nop 0
	v_addc_co_u32_e32 v55, vcc, 0, v141, vcc
	v_mov_b32_e32 v50, v174
	v_mov_b32_e32 v51, v175
	v_mov_b32_e32 v52, v176
	v_mov_b32_e32 v53, v177
	v_lshlrev_b32_e32 v58, 16, v50
	v_and_b32_e32 v50, 0xffff0000, v50
	v_lshlrev_b32_e32 v59, 16, v51
	v_and_b32_e32 v51, 0xffff0000, v51
	v_lshlrev_b32_e32 v60, 16, v52
	v_and_b32_e32 v52, 0xffff0000, v52
	v_lshlrev_b32_e32 v61, 16, v53
	v_and_b32_e32 v53, 0xffff0000, v53
	v_fmac_f32_e32 v58, 0.5, v46
	v_fmac_f32_e32 v60, 0.5, v42
	v_fmac_f32_e32 v50, 0.5, v47
	v_fmac_f32_e32 v52, 0.5, v43
	v_fmac_f32_e32 v59, 0.5, v48
	v_fmac_f32_e32 v61, 0.5, v44
	v_fmac_f32_e32 v51, 0.5, v49
	v_fmac_f32_e32 v53, 0.5, v45
	v_cvt_pk_bf16_f32 v42, v58, v50
	v_cvt_pk_bf16_f32 v43, v59, v51
	v_cvt_pk_bf16_f32 v44, v60, v52
	v_cvt_pk_bf16_f32 v45, v61, v53
	global_load_dwordx4 v[46:49], v[56:57], off offset:256
	v_lshlrev_b32_e32 v50, 16, v42
	global_store_dwordx4 v[54:55], v[42:45], off
	v_lshlrev_b32_e32 v51, 16, v43
	v_lshlrev_b32_e32 v52, 16, v44
	v_and_b32_e32 v42, 0xffff0000, v42
	v_and_b32_e32 v43, 0xffff0000, v43
	v_and_b32_e32 v44, 0xffff0000, v44
	v_lshlrev_b32_e32 v53, 16, v45
	v_and_b32_e32 v45, 0xffff0000, v45
	v_mul_f32_e32 v42, v42, v42
	v_mul_f32_e32 v43, v43, v43
	v_mul_f32_e32 v44, v44, v44
	v_mul_f32_e32 v45, v45, v45
	v_fmac_f32_e32 v42, v50, v50
	v_fmac_f32_e32 v43, v51, v51
	v_fmac_f32_e32 v44, v52, v52
	v_fmac_f32_e32 v45, v53, v53
	v_add_f32_e32 v42, v42, v43
	v_add_f32_e32 v43, v44, v45
	v_add_f32_e32 v42, v42, v43
	s_waitcnt vmcnt(1)
	v_lshlrev_b32_e32 v43, 16, v46
	v_and_b32_e32 v44, 0xffff0000, v46
	v_lshlrev_b32_e32 v45, 16, v47
	v_and_b32_e32 v46, 0xffff0000, v47
	v_lshlrev_b32_e32 v47, 16, v48
	v_and_b32_e32 v48, 0xffff0000, v48
	v_lshlrev_b32_e32 v50, 16, v49
	v_and_b32_e32 v49, 0xffff0000, v49
	v_fmac_f32_e32 v43, 0.5, v38
	v_fmac_f32_e32 v47, 0.5, v34
	v_fmac_f32_e32 v44, 0.5, v39
	v_fmac_f32_e32 v48, 0.5, v35
	v_fmac_f32_e32 v45, 0.5, v40
	v_fmac_f32_e32 v50, 0.5, v36
	v_fmac_f32_e32 v46, 0.5, v41
	v_fmac_f32_e32 v49, 0.5, v37
	v_cvt_pk_bf16_f32 v34, v43, v44
	v_cvt_pk_bf16_f32 v35, v45, v46
	v_cvt_pk_bf16_f32 v36, v47, v48
	v_cvt_pk_bf16_f32 v37, v50, v49
	global_store_dwordx4 v[56:57], v[34:37], off offset:256
	v_lshlrev_b32_e32 v38, 16, v34
	v_lshlrev_b32_e32 v39, 16, v35
	v_and_b32_e32 v34, 0xffff0000, v34
	v_and_b32_e32 v35, 0xffff0000, v35
	v_lshlrev_b32_e32 v40, 16, v36
	v_and_b32_e32 v36, 0xffff0000, v36
	v_lshlrev_b32_e32 v41, 16, v37
	v_and_b32_e32 v37, 0xffff0000, v37
	v_mul_f32_e32 v34, v34, v34
	v_mul_f32_e32 v35, v35, v35
	v_mul_f32_e32 v36, v36, v36
	v_mul_f32_e32 v37, v37, v37
	v_fmac_f32_e32 v34, v38, v38
	v_fmac_f32_e32 v35, v39, v39
	v_fmac_f32_e32 v36, v40, v40
	v_fmac_f32_e32 v37, v41, v41
	v_add_f32_e32 v34, v34, v35
	v_add_f32_e32 v35, v36, v37
	v_add_f32_e32 v34, v34, v35
	v_add_f32_e32 v34, v42, v34
	v_mov_b32_e32 v35, v34
	s_nop 1
	v_permlane16_swap_b32_e32 v34, v35
	v_add_f32_e32 v34, v34, v35
	v_mov_b32_e32 v35, v34
	s_nop 1
	v_permlane32_swap_b32_e32 v34, v35
	s_and_saveexec_b64 s[2:3], s[8:9]
	s_cbranch_execz .LBB0_666
; __device__ __forceinline__ unsigned cvt_pk_bf16(float lo, float hi) { unsigned r; asm volatile("v_cvt_pk_bf16_f32 %0, %1, %2" : "=v"(r) : "v"(lo), "v"(hi)); return r; }
;     __device__ __forceinline__ void operator()(const f32x4 (&acc)[2][2][4][2], const Unit& u, int wr, int wc, int fr, int fq) const {
;     ...
;             for (int m = 0; m < 4; ++m) { const int row = row0 + ai * HALF + m * 16; const size_t ro = (size_t)row * ldc + col0;
;                 float rs = 1.0f; if (GATED) rs = rs_of(rsq_in, row);
;                 float ss = 0.f;
; #pragma unroll
;                 for (int bj = 0; bj < 2; ++bj) { u32x4* p = (u32x4*)(H + ro + bj * HALF); const u32x4 hw = *p; const f32x4 a0 = acc[ai][bj][m][0], a1 = acc[ai][bj][m][1];
;                     float h[8] = {bf_lo(hw.x), bf_hi(hw.x), bf_lo(hw.y), bf_hi(hw.y), bf_lo(hw.z), bf_hi(hw.z), bf_lo(hw.w), bf_hi(hw.w)};
;                     if (GATED) { const u32x4 pw = *(const u32x4*)(PP + ro + bj * HALF);
;                         const float pp[8] = {bf_lo(pw.x), bf_hi(pw.x), bf_lo(pw.y), bf_hi(pw.y), bf_lo(pw.z), bf_hi(pw.z), bf_lo(pw.w), bf_hi(pw.w)};
; #pragma unroll
;                         for (int j = 0; j < 4; ++j) { h[j] += __builtin_amdgcn_rcpf(1.0f + __builtin_amdgcn_exp2f(-1.4426950408889634f * rs * a0[j])) * pp[j];
;                                                       h[4 + j] += __builtin_amdgcn_rcpf(1.0f + __builtin_amdgcn_exp2f(-1.4426950408889634f * rs * a1[j])) * pp[4 + j]; } }
;                     else {
; #pragma unroll
;                         for (int j = 0; j < 4; ++j) { h[j] += a0[j] * scale; h[4 + j] += a1[j] * scale; } }
;                     u32x4 w; w.x = cvt_pk_bf16(h[0], h[1]); w.y = cvt_pk_bf16(h[2], h[3]); w.z = cvt_pk_bf16(h[4], h[5]); w.w = cvt_pk_bf16(h[6], h[7]);
;                     *p = w; if (CP) *(u32x4*)(CP + ro + bj * HALF) = w;
;                     if (rsq_out) { const float r0 = bf_lo(w.x), r1 = bf_hi(w.x), r2 = bf_lo(w.y), r3 = bf_hi(w.y), r4 = bf_lo(w.z), r5 = bf_hi(w.z), r6 = bf_lo(w.w), r7 = bf_hi(w.w);
;                         ss += ((r0 * r0 + r1 * r1) + (r2 * r2 + r3 * r3)) + ((r4 * r4 + r5 * r5) + (r6 * r6 + r7 * r7)); } }
;                 if (rsq_out) { ss = sum_fq(ss); if (fq == 0) __hip_atomic_fetch_add(rsq_out + row, rsq_fix(ss), __ATOMIC_RELAXED, __HIP_MEMORY_SCOPE_AGENT); } }
	v_add_f32_e32 v34, v34, v35
	s_mov_b32 s1, 0x49800000
	v_fma_f32 v34, v34, s1, 0.5
	v_trunc_f32_e32 v34, v34
	v_mul_f32_e32 v35, 0x2f800000, v34
	v_floor_f32_e32 v35, v35
	v_fmac_f32_e32 v34, 0xcf800000, v35
	v_cvt_u32_f32_e32 v34, v34
	v_cvt_u32_f32_e32 v35, v35
	global_atomic_add_x2 v[114:115], v[34:35], off offset:1152
.LBB0_666:
	s_or_b64 exec, exec, s[2:3]
	v_add_co_u32_e32 v38, vcc, 0xa0000, v140
	s_mov_b64 s[2:3], 0xa0000
	s_nop 0
	v_addc_co_u32_e32 v39, vcc, 0, v141, vcc
	v_mov_b32_e32 v34, v190
	v_mov_b32_e32 v35, v191
	v_mov_b32_e32 v36, v192
	v_mov_b32_e32 v37, v193
	v_lshl_add_u64 v[40:41], v[140:141], 0, s[2:3]
	v_lshlrev_b32_e32 v42, 16, v34
	v_and_b32_e32 v34, 0xffff0000, v34
	v_lshlrev_b32_e32 v43, 16, v35
	v_and_b32_e32 v35, 0xffff0000, v35
	v_lshlrev_b32_e32 v44, 16, v36
	v_and_b32_e32 v36, 0xffff0000, v36
	v_lshlrev_b32_e32 v45, 16, v37
	v_and_b32_e32 v37, 0xffff0000, v37
	v_fmac_f32_e32 v42, 0.5, v30
	v_fmac_f32_e32 v44, 0.5, v26
	v_fmac_f32_e32 v34, 0.5, v31
	v_fmac_f32_e32 v36, 0.5, v27
	v_fmac_f32_e32 v43, 0.5, v32
	v_fmac_f32_e32 v45, 0.5, v28
	v_fmac_f32_e32 v35, 0.5, v33
	v_fmac_f32_e32 v37, 0.5, v29
	v_cvt_pk_bf16_f32 v26, v42, v34
	v_cvt_pk_bf16_f32 v27, v43, v35
	v_cvt_pk_bf16_f32 v28, v44, v36
	v_cvt_pk_bf16_f32 v29, v45, v37
	global_load_dwordx4 v[30:33], v[40:41], off offset:256
	v_lshlrev_b32_e32 v34, 16, v26
	global_store_dwordx4 v[38:39], v[26:29], off
	v_lshlrev_b32_e32 v35, 16, v27
	v_lshlrev_b32_e32 v36, 16, v28
	v_and_b32_e32 v26, 0xffff0000, v26
	v_and_b32_e32 v27, 0xffff0000, v27
	v_and_b32_e32 v28, 0xffff0000, v28
	v_lshlrev_b32_e32 v37, 16, v29
	v_and_b32_e32 v29, 0xffff0000, v29
	v_mul_f32_e32 v26, v26, v26
	v_mul_f32_e32 v27, v27, v27
	v_mul_f32_e32 v28, v28, v28
	v_mul_f32_e32 v29, v29, v29
	v_fmac_f32_e32 v26, v34, v34
	v_fmac_f32_e32 v27, v35, v35
	v_fmac_f32_e32 v28, v36, v36
	v_fmac_f32_e32 v29, v37, v37
	v_add_f32_e32 v26, v26, v27
	v_add_f32_e32 v27, v28, v29
	v_add_f32_e32 v26, v26, v27
	s_waitcnt vmcnt(1)
	v_lshlrev_b32_e32 v27, 16, v30
	v_and_b32_e32 v28, 0xffff0000, v30
	v_lshlrev_b32_e32 v29, 16, v31
	v_and_b32_e32 v30, 0xffff0000, v31
	v_lshlrev_b32_e32 v31, 16, v32
	v_and_b32_e32 v32, 0xffff0000, v32
	v_lshlrev_b32_e32 v34, 16, v33
	v_and_b32_e32 v33, 0xffff0000, v33
	v_fmac_f32_e32 v27, 0.5, v22
	v_fmac_f32_e32 v31, 0.5, v18
	v_fmac_f32_e32 v28, 0.5, v23
	v_fmac_f32_e32 v32, 0.5, v19
	v_fmac_f32_e32 v29, 0.5, v24
	v_fmac_f32_e32 v34, 0.5, v20
	v_fmac_f32_e32 v30, 0.5, v25
	v_fmac_f32_e32 v33, 0.5, v21
	v_cvt_pk_bf16_f32 v18, v27, v28
	v_cvt_pk_bf16_f32 v19, v29, v30
	v_cvt_pk_bf16_f32 v20, v31, v32
	v_cvt_pk_bf16_f32 v21, v34, v33
	global_store_dwordx4 v[40:41], v[18:21], off offset:256
	v_lshlrev_b32_e32 v22, 16, v18
	v_lshlrev_b32_e32 v23, 16, v19
	v_and_b32_e32 v18, 0xffff0000, v18
	v_and_b32_e32 v19, 0xffff0000, v19
	v_lshlrev_b32_e32 v24, 16, v20
	v_and_b32_e32 v20, 0xffff0000, v20
	v_lshlrev_b32_e32 v25, 16, v21
	v_and_b32_e32 v21, 0xffff0000, v21
	v_mul_f32_e32 v18, v18, v18
	v_mul_f32_e32 v19, v19, v19
	v_mul_f32_e32 v20, v20, v20
	v_mul_f32_e32 v21, v21, v21
	v_fmac_f32_e32 v18, v22, v22
	v_fmac_f32_e32 v19, v23, v23
	v_fmac_f32_e32 v20, v24, v24
	v_fmac_f32_e32 v21, v25, v25
	v_add_f32_e32 v18, v18, v19
	v_add_f32_e32 v19, v20, v21
	v_add_f32_e32 v18, v18, v19
	v_add_f32_e32 v18, v26, v18
	v_mov_b32_e32 v19, v18
	s_nop 1
	v_permlane16_swap_b32_e32 v18, v19
	v_add_f32_e32 v18, v18, v19
	v_mov_b32_e32 v19, v18
	s_nop 1
	v_permlane32_swap_b32_e32 v18, v19
	s_and_saveexec_b64 s[2:3], s[8:9]
	s_cbranch_execz .LBB0_668
	v_add_f32_e32 v18, v18, v19
	s_mov_b32 s1, 0x49800000
	v_fma_f32 v18, v18, s1, 0.5
	v_trunc_f32_e32 v18, v18
	v_mul_f32_e32 v19, 0x2f800000, v18
	v_floor_f32_e32 v19, v19
	v_fmac_f32_e32 v18, 0xcf800000, v19
	v_cvt_u32_f32_e32 v18, v18
	v_cvt_u32_f32_e32 v19, v19
	global_atomic_add_x2 v[114:115], v[18:19], off offset:1280
; __device__ __forceinline__ unsigned cvt_pk_bf16(float lo, float hi) { unsigned r; asm volatile("v_cvt_pk_bf16_f32 %0, %1, %2" : "=v"(r) : "v"(lo), "v"(hi)); return r; }
;     __device__ __forceinline__ void operator()(const f32x4 (&acc)[2][2][4][2], const Unit& u, int wr, int wc, int fr, int fq) const {
;     ...
;             for (int m = 0; m < 4; ++m) { const int row = row0 + ai * HALF + m * 16; const size_t ro = (size_t)row * ldc + col0;
;                 float rs = 1.0f; if (GATED) rs = rs_of(rsq_in, row);
;                 float ss = 0.f;
; #pragma unroll
;                 for (int bj = 0; bj < 2; ++bj) { u32x4* p = (u32x4*)(H + ro + bj * HALF); const u32x4 hw = *p; const f32x4 a0 = acc[ai][bj][m][0], a1 = acc[ai][bj][m][1];
;                     float h[8] = {bf_lo(hw.x), bf_hi(hw.x), bf_lo(hw.y), bf_hi(hw.y), bf_lo(hw.z), bf_hi(hw.z), bf_lo(hw.w), bf_hi(hw.w)};
;                     if (GATED) { const u32x4 pw = *(const u32x4*)(PP + ro + bj * HALF);
;                         const float pp[8] = {bf_lo(pw.x), bf_hi(pw.x), bf_lo(pw.y), bf_hi(pw.y), bf_lo(pw.z), bf_hi(pw.z), bf_lo(pw.w), bf_hi(pw.w)};
; #pragma unroll
;                         for (int j = 0; j < 4; ++j) { h[j] += __builtin_amdgcn_rcpf(1.0f + __builtin_amdgcn_exp2f(-1.4426950408889634f * rs * a0[j])) * pp[j];
;                                                       h[4 + j] += __builtin_amdgcn_rcpf(1.0f + __builtin_amdgcn_exp2f(-1.4426950408889634f * rs * a1[j])) * pp[4 + j]; } }
;                     else {
; #pragma unroll
;                         for (int j = 0; j < 4; ++j) { h[j] += a0[j] * scale; h[4 + j] += a1[j] * scale; } }
;                     u32x4 w; w.x = cvt_pk_bf16(h[0], h[1]); w.y = cvt_pk_bf16(h[2], h[3]); w.z = cvt_pk_bf16(h[4], h[5]); w.w = cvt_pk_bf16(h[6], h[7]);
;                     *p = w; if (CP) *(u32x4*)(CP + ro + bj * HALF) = w;
;                     if (rsq_out) { const float r0 = bf_lo(w.x), r1 = bf_hi(w.x), r2 = bf_lo(w.y), r3 = bf_hi(w.y), r4 = bf_lo(w.z), r5 = bf_hi(w.z), r6 = bf_lo(w.w), r7 = bf_hi(w.w);
;                         ss += ((r0 * r0 + r1 * r1) + (r2 * r2 + r3 * r3)) + ((r4 * r4 + r5 * r5) + (r6 * r6 + r7 * r7)); } }
;                 if (rsq_out) { ss = sum_fq(ss); if (fq == 0) __hip_atomic_fetch_add(rsq_out + row, rsq_fix(ss), __ATOMIC_RELAXED, __HIP_MEMORY_SCOPE_AGENT); } }
.LBB0_668:
	s_or_b64 exec, exec, s[2:3]
	v_add_co_u32_e32 v24, vcc, 0xb0000, v140
	s_mov_b64 s[2:3], 0xb0000
	s_nop 0
	v_addc_co_u32_e32 v25, vcc, 0, v141, vcc
	v_mov_b32_e32 v20, v194
	v_mov_b32_e32 v21, v195
	v_mov_b32_e32 v22, v196
	v_mov_b32_e32 v23, v197
	v_lshl_add_u64 v[18:19], v[140:141], 0, s[2:3]
	v_lshlrev_b32_e32 v26, 16, v20
	v_and_b32_e32 v20, 0xffff0000, v20
	v_lshlrev_b32_e32 v27, 16, v21
	v_and_b32_e32 v21, 0xffff0000, v21
	v_lshlrev_b32_e32 v28, 16, v22
	v_and_b32_e32 v22, 0xffff0000, v22
	v_lshlrev_b32_e32 v29, 16, v23
	v_and_b32_e32 v23, 0xffff0000, v23
	v_fmac_f32_e32 v26, 0.5, v14
	v_fmac_f32_e32 v28, 0.5, v10
	v_fmac_f32_e32 v20, 0.5, v15
	v_fmac_f32_e32 v22, 0.5, v11
	v_fmac_f32_e32 v27, 0.5, v16
	v_fmac_f32_e32 v21, 0.5, v17
	v_cvt_pk_bf16_f32 v10, v26, v20
	v_cvt_pk_bf16_f32 v11, v27, v21
	v_fmac_f32_e32 v29, 0.5, v12
	v_fmac_f32_e32 v23, 0.5, v13
	v_cvt_pk_bf16_f32 v12, v28, v22
	v_cvt_pk_bf16_f32 v13, v29, v23
	global_store_dwordx4 v[24:25], v[10:13], off
	v_lshlrev_b32_e32 v14, 16, v10
	v_lshlrev_b32_e32 v15, 16, v11
	v_and_b32_e32 v10, 0xffff0000, v10
	v_and_b32_e32 v11, 0xffff0000, v11
	v_mul_f32_e32 v10, v10, v10
	v_mul_f32_e32 v11, v11, v11
	v_lshlrev_b32_e32 v16, 16, v12
	v_and_b32_e32 v12, 0xffff0000, v12
	v_lshlrev_b32_e32 v17, 16, v13
	v_and_b32_e32 v13, 0xffff0000, v13
	v_fmac_f32_e32 v10, v14, v14
	v_fmac_f32_e32 v11, v15, v15
	v_add_f32_e32 v10, v10, v11
	v_mul_f32_e32 v11, v12, v12
	v_mul_f32_e32 v12, v13, v13
	v_fmac_f32_e32 v11, v16, v16
	v_fmac_f32_e32 v12, v17, v17
	v_add_f32_e32 v11, v11, v12
	v_add_f32_e32 v14, v10, v11
	global_load_dwordx4 v[10:13], v[18:19], off offset:256
	s_waitcnt vmcnt(0)
	v_lshlrev_b32_e32 v15, 16, v10
	v_and_b32_e32 v10, 0xffff0000, v10
	v_lshlrev_b32_e32 v16, 16, v11
	v_and_b32_e32 v11, 0xffff0000, v11
	v_lshlrev_b32_e32 v17, 16, v12
	v_and_b32_e32 v12, 0xffff0000, v12
	v_lshlrev_b32_e32 v20, 16, v13
	v_and_b32_e32 v13, 0xffff0000, v13
	v_fmac_f32_e32 v15, 0.5, v6
	v_fmac_f32_e32 v17, 0.5, v2
	v_fmac_f32_e32 v10, 0.5, v7
	v_fmac_f32_e32 v12, 0.5, v3
	v_fmac_f32_e32 v16, 0.5, v8
	v_fmac_f32_e32 v11, 0.5, v9
	v_cvt_pk_bf16_f32 v2, v15, v10
	v_cvt_pk_bf16_f32 v3, v16, v11
	v_fmac_f32_e32 v20, 0.5, v4
	v_fmac_f32_e32 v13, 0.5, v5
	v_cvt_pk_bf16_f32 v4, v17, v12
	v_cvt_pk_bf16_f32 v5, v20, v13
	global_store_dwordx4 v[18:19], v[2:5], off offset:256
	v_lshlrev_b32_e32 v6, 16, v2
	v_lshlrev_b32_e32 v7, 16, v3
	v_and_b32_e32 v2, 0xffff0000, v2
	v_and_b32_e32 v3, 0xffff0000, v3
	v_mul_f32_e32 v2, v2, v2
	v_mul_f32_e32 v3, v3, v3
	v_lshlrev_b32_e32 v8, 16, v4
	v_and_b32_e32 v4, 0xffff0000, v4
	v_lshlrev_b32_e32 v9, 16, v5
	v_and_b32_e32 v5, 0xffff0000, v5
	v_fmac_f32_e32 v2, v6, v6
	v_fmac_f32_e32 v3, v7, v7
	v_add_f32_e32 v2, v2, v3
	v_mul_f32_e32 v3, v4, v4
	v_mul_f32_e32 v4, v5, v5
	v_fmac_f32_e32 v3, v8, v8
	v_fmac_f32_e32 v4, v9, v9
	v_add_f32_e32 v3, v3, v4
	v_add_f32_e32 v2, v2, v3
	v_add_f32_e32 v2, v14, v2
	v_mov_b32_e32 v3, v2
	s_nop 1
	v_permlane16_swap_b32_e32 v2, v3
	v_add_f32_e32 v2, v2, v3
	v_mov_b32_e32 v3, v2
	s_nop 1
	v_permlane32_swap_b32_e32 v2, v3
	s_and_saveexec_b64 s[2:3], s[8:9]
	s_cbranch_execz .LBB0_670
	v_add_f32_e32 v2, v2, v3
	s_mov_b32 s1, 0x49800000
	v_fma_f32 v2, v2, s1, 0.5
	v_trunc_f32_e32 v2, v2
	v_mul_f32_e32 v3, 0x2f800000, v2
	v_floor_f32_e32 v3, v3
	v_fmac_f32_e32 v2, 0xcf800000, v3
	v_cvt_u32_f32_e32 v2, v2
	v_cvt_u32_f32_e32 v3, v3
	global_atomic_add_x2 v[114:115], v[2:3], off offset:1408

; __device__ __forceinline__ unsigned cvt_pk_bf16(float lo, float hi) { unsigned r; asm volatile("v_cvt_pk_bf16_f32 %0, %1, %2" : "=v"(r) : "v"(lo), "v"(hi)); return r; }
;     __device__ __forceinline__ void operator()(const f32x4 (&acc)[2][2][4][2], const Unit& u, int wr, int wc, int fr, int fq) const {
;     ...
;             for (int m = 0; m < 4; ++m) { const int row = row0 + ai * HALF + m * 16; const size_t ro = (size_t)row * ldc + col0;
;                 float rs = 1.0f; if (GATED) rs = rs_of(rsq_in, row);
;                 float ss = 0.f;
; #pragma unroll
;                 for (int bj = 0; bj < 2; ++bj) { u32x4* p = (u32x4*)(H + ro + bj * HALF); const u32x4 hw = *p; const f32x4 a0 = acc[ai][bj][m][0], a1 = acc[ai][bj][m][1];
;                     float h[8] = {bf_lo(hw.x), bf_hi(hw.x), bf_lo(hw.y), bf_hi(hw.y), bf_lo(hw.z), bf_hi(hw.z), bf_lo(hw.w), bf_hi(hw.w)};
;                     if (GATED) { const u32x4 pw = *(const u32x4*)(PP + ro + bj * HALF);
;                         const float pp[8] = {bf_lo(pw.x), bf_hi(pw.x), bf_lo(pw.y), bf_hi(pw.y), bf_lo(pw.z), bf_hi(pw.z), bf_lo(pw.w), bf_hi(pw.w)};
; #pragma unroll
;                         for (int j = 0; j < 4; ++j) { h[j] += __builtin_amdgcn_rcpf(1.0f + __builtin_amdgcn_exp2f(-1.4426950408889634f * rs * a0[j])) * pp[j];
;                                                       h[4 + j] += __builtin_amdgcn_rcpf(1.0f + __builtin_amdgcn_exp2f(-1.4426950408889634f * rs * a1[j])) * pp[4 + j]; } }
;                     else {
; #pragma unroll
;                         for (int j = 0; j < 4; ++j) { h[j] += a0[j] * scale; h[4 + j] += a1[j] * scale; } }
;                     u32x4 w; w.x = cvt_pk_bf16(h[0], h[1]); w.y = cvt_pk_bf16(h[2], h[3]); w.z = cvt_pk_bf16(h[4], h[5]); w.w = cvt_pk_bf16(h[6], h[7]);
;                     *p = w; if (CP) *(u32x4*)(CP + ro + bj * HALF) = w;
;                     if (rsq_out) { const float r0 = bf_lo(w.x), r1 = bf_hi(w.x), r2 = bf_lo(w.y), r3 = bf_hi(w.y), r4 = bf_lo(w.z), r5 = bf_hi(w.z), r6 = bf_lo(w.w), r7 = bf_hi(w.w);
;                         ss += ((r0 * r0 + r1 * r1) + (r2 * r2 + r3 * r3)) + ((r4 * r4 + r5 * r5) + (r6 * r6 + r7 * r7)); } }
;                 if (rsq_out) { ss = sum_fq(ss); if (fq == 0) __hip_atomic_fetch_add(rsq_out + row, rsq_fix(ss), __ATOMIC_RELAXED, __HIP_MEMORY_SCOPE_AGENT); } }
.LBB0_1278:
	v_lshl_add_u32 v144, s4, 8, v146
	v_ashrrev_i32_e32 v145, 31, v144
	v_lshl_add_u32 v142, s14, 8, v148
	v_lshlrev_b64 v[140:141], 12, v[144:145]
	v_ashrrev_i32_e32 v143, 31, v142
	v_lshl_add_u64 v[140:141], s[12:13], 0, v[140:141]
	v_lshl_add_u64 v[140:141], v[142:143], 1, v[140:141]
	global_load_dwordx4 v[150:153], v[140:141], off
	v_mov_b32_e32 v220, 0x10000
	v_mov_b32_e32 v221, 0
	global_load_dwordx4 v[194:197], v[140:141], off offset:256
	v_lshl_add_u64 v[222:223], v[220:221], 0, v[140:141]
	global_load_dwordx4 v[158:161], v[222:223], off
	global_load_dwordx4 v[208:211], v[222:223], off offset:256
	v_lshl_add_u64 v[222:223], v[220:221], 0, v[222:223]
	global_load_dwordx4 v[162:165], v[222:223], off
	global_load_dwordx4 v[212:215], v[222:223], off offset:256
	v_lshl_add_u64 v[222:223], v[220:221], 0, v[222:223]
	global_load_dwordx4 v[166:169], v[222:223], off
	global_load_dwordx4 v[216:219], v[222:223], off offset:256
	v_lshl_add_u64 v[222:223], v[220:221], 3, v[140:141]
	global_load_dwordx4 v[170:173], v[222:223], off
	v_lshl_add_u64 v[222:223], v[220:221], 0, v[222:223]
	global_load_dwordx4 v[174:177], v[222:223], off
	v_lshl_add_u64 v[222:223], v[220:221], 0, v[222:223]
	global_load_dwordx4 v[186:189], v[222:223], off
	v_lshl_add_u64 v[222:223], v[220:221], 0, v[222:223]
	global_load_dwordx4 v[190:193], v[222:223], off
	s_waitcnt vmcnt(0)
	v_lshlrev_b32_e32 v154, 16, v150
	v_and_b32_e32 v150, 0xffff0000, v150
	v_lshlrev_b32_e32 v155, 16, v151
	v_and_b32_e32 v151, 0xffff0000, v151
	v_lshlrev_b32_e32 v156, 16, v152
	v_and_b32_e32 v152, 0xffff0000, v152
	v_lshlrev_b32_e32 v157, 16, v153
	v_and_b32_e32 v153, 0xffff0000, v153
	v_add_f32_e32 v126, v126, v154
	v_add_f32_e32 v154, v122, v156
	v_add_f32_e32 v122, v127, v150
	v_add_f32_e32 v127, v123, v152
	v_add_f32_e32 v123, v128, v155
	v_add_f32_e32 v128, v124, v157
	v_add_f32_e32 v124, v129, v151
	v_add_f32_e32 v125, v125, v153
	v_cvt_pk_bf16_f32 v122, v126, v122
	v_cvt_pk_bf16_f32 v123, v123, v124
	v_cvt_pk_bf16_f32 v124, v154, v127
	v_cvt_pk_bf16_f32 v125, v128, v125
	v_mov_b32_e32 v126, v194
	v_mov_b32_e32 v127, v195
	v_mov_b32_e32 v128, v196
	v_mov_b32_e32 v129, v197
	v_lshlrev_b32_e32 v150, 16, v122
	global_store_dwordx4 v[140:141], v[122:125], off
	v_lshlrev_b32_e32 v151, 16, v123
	v_lshlrev_b32_e32 v152, 16, v124
	v_and_b32_e32 v122, 0xffff0000, v122
	v_and_b32_e32 v123, 0xffff0000, v123
	v_and_b32_e32 v124, 0xffff0000, v124
	v_lshlrev_b32_e32 v153, 16, v125
	v_and_b32_e32 v125, 0xffff0000, v125
	v_mul_f32_e32 v122, v122, v122
	v_mul_f32_e32 v123, v123, v123
	v_mul_f32_e32 v124, v124, v124
	v_mul_f32_e32 v125, v125, v125
	v_fmac_f32_e32 v122, v150, v150
	v_fmac_f32_e32 v123, v151, v151
	v_fmac_f32_e32 v124, v152, v152
	v_fmac_f32_e32 v125, v153, v153
	v_add_f32_e32 v122, v122, v123
	v_add_f32_e32 v123, v124, v125
	v_add_f32_e32 v122, v122, v123
	v_lshlrev_b32_e32 v123, 16, v126
	v_and_b32_e32 v124, 0xffff0000, v126
	v_lshlrev_b32_e32 v125, 16, v127
	v_and_b32_e32 v126, 0xffff0000, v127
	v_lshlrev_b32_e32 v127, 16, v128
	v_and_b32_e32 v128, 0xffff0000, v128
	v_lshlrev_b32_e32 v150, 16, v129
	v_and_b32_e32 v129, 0xffff0000, v129
	v_add_f32_e32 v118, v118, v123
	v_add_f32_e32 v123, v114, v127
	v_add_f32_e32 v114, v119, v124
	v_add_f32_e32 v119, v115, v128
	v_add_f32_e32 v115, v120, v125
	v_add_f32_e32 v120, v116, v150
	v_add_f32_e32 v116, v121, v126
	v_add_f32_e32 v117, v117, v129
	v_cvt_pk_bf16_f32 v114, v118, v114
	v_cvt_pk_bf16_f32 v115, v115, v116
	v_cvt_pk_bf16_f32 v116, v123, v119
	v_cvt_pk_bf16_f32 v117, v120, v117
	global_store_dwordx4 v[140:141], v[114:117], off offset:256
	v_lshlrev_b32_e32 v118, 16, v114
	v_lshlrev_b32_e32 v119, 16, v115
	v_and_b32_e32 v114, 0xffff0000, v114
	v_and_b32_e32 v115, 0xffff0000, v115
	v_lshlrev_b32_e32 v120, 16, v116
	v_and_b32_e32 v116, 0xffff0000, v116
	v_lshlrev_b32_e32 v121, 16, v117
	v_and_b32_e32 v117, 0xffff0000, v117
	v_mul_f32_e32 v114, v114, v114
	v_mul_f32_e32 v115, v115, v115
	v_mul_f32_e32 v116, v116, v116
	v_mul_f32_e32 v117, v117, v117
	v_fmac_f32_e32 v114, v118, v118
	v_fmac_f32_e32 v115, v119, v119
	v_fmac_f32_e32 v116, v120, v120
	v_fmac_f32_e32 v117, v121, v121
	v_add_f32_e32 v114, v114, v115
	v_add_f32_e32 v115, v116, v117
	v_add_f32_e32 v114, v114, v115
	v_add_f32_e32 v114, v122, v114
	v_mov_b32_e32 v115, v114
	s_nop 1
	v_permlane16_swap_b32_e32 v114, v115
	v_add_f32_e32 v116, v114, v115
	v_mov_b32_e32 v117, v116
	s_nop 1
	v_permlane32_swap_b32_e32 v116, v117
	v_lshl_add_u64 v[114:115], v[144:145], 3, s[18:19]
	s_and_saveexec_b64 s[2:3], s[6:7]
	s_cbranch_execz .LBB0_1280
	v_add_f32_e32 v116, v116, v117
	s_mov_b32 s1, 0x49800000
	v_fma_f32 v116, v116, s1, 0.5
	v_trunc_f32_e32 v116, v116
	v_mul_f32_e32 v117, 0x2f800000, v116
	v_floor_f32_e32 v117, v117
	v_fmac_f32_e32 v116, 0xcf800000, v117
	v_cvt_u32_f32_e32 v116, v116
	v_cvt_u32_f32_e32 v117, v117
	global_atomic_add_x2 v[114:115], v[116:117], off
; __device__ __forceinline__ unsigned cvt_pk_bf16(float lo, float hi) { unsigned r; asm volatile("v_cvt_pk_bf16_f32 %0, %1, %2" : "=v"(r) : "v"(lo), "v"(hi)); return r; }
;     __device__ __forceinline__ void operator()(const f32x4 (&acc)[2][2][4][2], const Unit& u, int wr, int wc, int fr, int fq) const {
;     ...
;             for (int m = 0; m < 4; ++m) { const int row = row0 + ai * HALF + m * 16; const size_t ro = (size_t)row * ldc + col0;
;                 float rs = 1.0f; if (GATED) rs = rs_of(rsq_in, row);
;                 float ss = 0.f;
; #pragma unroll
;                 for (int bj = 0; bj < 2; ++bj) { u32x4* p = (u32x4*)(H + ro + bj * HALF); const u32x4 hw = *p; const f32x4 a0 = acc[ai][bj][m][0], a1 = acc[ai][bj][m][1];
;                     float h[8] = {bf_lo(hw.x), bf_hi(hw.x), bf_lo(hw.y), bf_hi(hw.y), bf_lo(hw.z), bf_hi(hw.z), bf_lo(hw.w), bf_hi(hw.w)};
;                     if (GATED) { const u32x4 pw = *(const u32x4*)(PP + ro + bj * HALF);
;                         const float pp[8] = {bf_lo(pw.x), bf_hi(pw.x), bf_lo(pw.y), bf_hi(pw.y), bf_lo(pw.z), bf_hi(pw.z), bf_lo(pw.w), bf_hi(pw.w)};
; #pragma unroll
;                         for (int j = 0; j < 4; ++j) { h[j] += __builtin_amdgcn_rcpf(1.0f + __builtin_amdgcn_exp2f(-1.4426950408889634f * rs * a0[j])) * pp[j];
;                                                       h[4 + j] += __builtin_amdgcn_rcpf(1.0f + __builtin_amdgcn_exp2f(-1.4426950408889634f * rs * a1[j])) * pp[4 + j]; } }
;                     else {
; #pragma unroll
;                         for (int j = 0; j < 4; ++j) { h[j] += a0[j] * scale; h[4 + j] += a1[j] * scale; } }
;                     u32x4 w; w.x = cvt_pk_bf16(h[0], h[1]); w.y = cvt_pk_bf16(h[2], h[3]); w.z = cvt_pk_bf16(h[4], h[5]); w.w = cvt_pk_bf16(h[6], h[7]);
;                     *p = w; if (CP) *(u32x4*)(CP + ro + bj * HALF) = w;
;                     if (rsq_out) { const float r0 = bf_lo(w.x), r1 = bf_hi(w.x), r2 = bf_lo(w.y), r3 = bf_hi(w.y), r4 = bf_lo(w.z), r5 = bf_hi(w.z), r6 = bf_lo(w.w), r7 = bf_hi(w.w);
;                         ss += ((r0 * r0 + r1 * r1) + (r2 * r2 + r3 * r3)) + ((r4 * r4 + r5 * r5) + (r6 * r6 + r7 * r7)); } }
;                 if (rsq_out) { ss = sum_fq(ss); if (fq == 0) __hip_atomic_fetch_add(rsq_out + row, rsq_fix(ss), __ATOMIC_RELAXED, __HIP_MEMORY_SCOPE_AGENT); } }
.LBB0_1280:
	s_or_b64 exec, exec, s[2:3]
	v_or_b32_e32 v116, 16, v144
	v_ashrrev_i32_e32 v117, 31, v116
	v_lshlrev_b64 v[116:117], 12, v[116:117]
	v_lshl_add_u64 v[116:117], s[12:13], 0, v[116:117]
	v_lshl_add_u64 v[120:121], v[142:143], 1, v[116:117]
	v_mov_b32_e32 v116, v158
	v_mov_b32_e32 v117, v159
	v_mov_b32_e32 v118, v160
	v_mov_b32_e32 v119, v161
	v_lshlrev_b32_e32 v122, 16, v116
	v_and_b32_e32 v116, 0xffff0000, v116
	v_lshlrev_b32_e32 v123, 16, v117
	v_and_b32_e32 v117, 0xffff0000, v117
	v_lshlrev_b32_e32 v124, 16, v118
	v_and_b32_e32 v118, 0xffff0000, v118
	v_lshlrev_b32_e32 v125, 16, v119
	v_and_b32_e32 v119, 0xffff0000, v119
	v_add_f32_e32 v110, v110, v122
	v_add_f32_e32 v122, v106, v124
	v_add_f32_e32 v106, v111, v116
	v_add_f32_e32 v111, v107, v118
	v_add_f32_e32 v107, v112, v123
	v_add_f32_e32 v112, v108, v125
	v_add_f32_e32 v108, v113, v117
	v_add_f32_e32 v109, v109, v119
	v_cvt_pk_bf16_f32 v106, v110, v106
	v_cvt_pk_bf16_f32 v107, v107, v108
	v_cvt_pk_bf16_f32 v108, v122, v111
	v_cvt_pk_bf16_f32 v109, v112, v109
	v_mov_b32_e32 v110, v208
	v_mov_b32_e32 v111, v209
	v_mov_b32_e32 v112, v210
	v_mov_b32_e32 v113, v211
	v_lshlrev_b32_e32 v116, 16, v106
	global_store_dwordx4 v[120:121], v[106:109], off
	v_lshlrev_b32_e32 v117, 16, v107
	v_lshlrev_b32_e32 v118, 16, v108
	v_and_b32_e32 v106, 0xffff0000, v106
	v_and_b32_e32 v107, 0xffff0000, v107
	v_and_b32_e32 v108, 0xffff0000, v108
	v_lshlrev_b32_e32 v119, 16, v109
	v_and_b32_e32 v109, 0xffff0000, v109
	v_mul_f32_e32 v106, v106, v106
	v_mul_f32_e32 v107, v107, v107
	v_mul_f32_e32 v108, v108, v108
	v_mul_f32_e32 v109, v109, v109
	v_fmac_f32_e32 v106, v116, v116
	v_fmac_f32_e32 v107, v117, v117
	v_fmac_f32_e32 v108, v118, v118
	v_fmac_f32_e32 v109, v119, v119
	v_add_f32_e32 v106, v106, v107
	v_add_f32_e32 v107, v108, v109
	v_add_f32_e32 v106, v106, v107
	v_lshlrev_b32_e32 v107, 16, v110
	v_and_b32_e32 v108, 0xffff0000, v110
	v_lshlrev_b32_e32 v109, 16, v111
	v_and_b32_e32 v110, 0xffff0000, v111
	v_lshlrev_b32_e32 v111, 16, v112
	v_and_b32_e32 v112, 0xffff0000, v112
	v_lshlrev_b32_e32 v116, 16, v113
	v_and_b32_e32 v113, 0xffff0000, v113
	v_add_f32_e32 v102, v102, v107
	v_add_f32_e32 v107, v98, v111
	v_add_f32_e32 v98, v103, v108
	v_add_f32_e32 v103, v99, v112
	v_add_f32_e32 v99, v104, v109
	v_add_f32_e32 v104, v100, v116
	v_add_f32_e32 v100, v105, v110
	v_add_f32_e32 v101, v101, v113
	v_cvt_pk_bf16_f32 v98, v102, v98
	v_cvt_pk_bf16_f32 v99, v99, v100
	v_cvt_pk_bf16_f32 v100, v107, v103
	v_cvt_pk_bf16_f32 v101, v104, v101
	global_store_dwordx4 v[120:121], v[98:101], off offset:256
	v_lshlrev_b32_e32 v102, 16, v98
	v_lshlrev_b32_e32 v103, 16, v99
	v_and_b32_e32 v98, 0xffff0000, v98
	v_and_b32_e32 v99, 0xffff0000, v99
	v_lshlrev_b32_e32 v104, 16, v100
	v_and_b32_e32 v100, 0xffff0000, v100
	v_lshlrev_b32_e32 v105, 16, v101
	v_and_b32_e32 v101, 0xffff0000, v101
	v_mul_f32_e32 v98, v98, v98
	v_mul_f32_e32 v99, v99, v99
	v_mul_f32_e32 v100, v100, v100
	v_mul_f32_e32 v101, v101, v101
	v_fmac_f32_e32 v98, v102, v102
	v_fmac_f32_e32 v99, v103, v103
	v_fmac_f32_e32 v100, v104, v104
	v_fmac_f32_e32 v101, v105, v105
	v_add_f32_e32 v98, v98, v99
	v_add_f32_e32 v99, v100, v101
	v_add_f32_e32 v98, v98, v99
	v_add_f32_e32 v98, v106, v98
	v_mov_b32_e32 v99, v98
	s_nop 1
	v_permlane16_swap_b32_e32 v98, v99
	v_add_f32_e32 v98, v98, v99
	v_mov_b32_e32 v99, v98
	s_nop 1
	v_permlane32_swap_b32_e32 v98, v99
	s_and_saveexec_b64 s[2:3], s[6:7]
	s_cbranch_execz .LBB0_1282
	v_add_f32_e32 v98, v98, v99
	s_mov_b32 s1, 0x49800000
	v_fma_f32 v98, v98, s1, 0.5
	v_trunc_f32_e32 v98, v98
	v_mul_f32_e32 v99, 0x2f800000, v98
	v_floor_f32_e32 v99, v99
	v_fmac_f32_e32 v98, 0xcf800000, v99
	v_cvt_u32_f32_e32 v98, v98
	v_cvt_u32_f32_e32 v99, v99
	global_atomic_add_x2 v[114:115], v[98:99], off offset:128
.LBB0_1282:
	s_or_b64 exec, exec, s[2:3]
	v_or_b32_e32 v98, 32, v144
	v_ashrrev_i32_e32 v99, 31, v98
	v_lshlrev_b64 v[98:99], 12, v[98:99]
	v_lshl_add_u64 v[98:99], s[12:13], 0, v[98:99]
	v_lshl_add_u64 v[102:103], v[142:143], 1, v[98:99]
	v_mov_b32_e32 v98, v162
	v_mov_b32_e32 v99, v163
	v_mov_b32_e32 v100, v164
	v_mov_b32_e32 v101, v165
	v_lshlrev_b32_e32 v104, 16, v98
	v_and_b32_e32 v98, 0xffff0000, v98
	v_lshlrev_b32_e32 v105, 16, v99
	v_and_b32_e32 v99, 0xffff0000, v99
	v_lshlrev_b32_e32 v106, 16, v100
	v_and_b32_e32 v100, 0xffff0000, v100
	v_lshlrev_b32_e32 v107, 16, v101
	v_and_b32_e32 v101, 0xffff0000, v101
	v_add_f32_e32 v94, v94, v104
	v_add_f32_e32 v104, v90, v106
	v_add_f32_e32 v90, v95, v98
	v_add_f32_e32 v95, v91, v100
	v_add_f32_e32 v91, v96, v105
	v_add_f32_e32 v96, v92, v107
	v_add_f32_e32 v92, v97, v99
	v_add_f32_e32 v93, v93, v101
	v_cvt_pk_bf16_f32 v90, v94, v90
	v_cvt_pk_bf16_f32 v91, v91, v92
	v_cvt_pk_bf16_f32 v92, v104, v95
	v_cvt_pk_bf16_f32 v93, v96, v93
	v_mov_b32_e32 v94, v212
	v_mov_b32_e32 v95, v213
	v_mov_b32_e32 v96, v214
	v_mov_b32_e32 v97, v215
	v_lshlrev_b32_e32 v98, 16, v90
	global_store_dwordx4 v[102:103], v[90:93], off
	v_lshlrev_b32_e32 v99, 16, v91
	v_lshlrev_b32_e32 v100, 16, v92
	v_and_b32_e32 v90, 0xffff0000, v90
	v_and_b32_e32 v91, 0xffff0000, v91
	v_and_b32_e32 v92, 0xffff0000, v92
	v_lshlrev_b32_e32 v101, 16, v93
	v_and_b32_e32 v93, 0xffff0000, v93
	v_mul_f32_e32 v90, v90, v90
	v_mul_f32_e32 v91, v91, v91
	v_mul_f32_e32 v92, v92, v92
	v_mul_f32_e32 v93, v93, v93
	v_fmac_f32_e32 v90, v98, v98
	v_fmac_f32_e32 v91, v99, v99
	v_fmac_f32_e32 v92, v100, v100
	v_fmac_f32_e32 v93, v101, v101
	v_add_f32_e32 v90, v90, v91
	v_add_f32_e32 v91, v92, v93
	v_add_f32_e32 v90, v90, v91
	v_lshlrev_b32_e32 v91, 16, v94
	v_and_b32_e32 v92, 0xffff0000, v94
	v_lshlrev_b32_e32 v93, 16, v95
; __device__ __forceinline__ unsigned cvt_pk_bf16(float lo, float hi) { unsigned r; asm volatile("v_cvt_pk_bf16_f32 %0, %1, %2" : "=v"(r) : "v"(lo), "v"(hi)); return r; }
;     __device__ __forceinline__ void operator()(const f32x4 (&acc)[2][2][4][2], const Unit& u, int wr, int wc, int fr, int fq) const {
;     ...
;             for (int m = 0; m < 4; ++m) { const int row = row0 + ai * HALF + m * 16; const size_t ro = (size_t)row * ldc + col0;
;                 float rs = 1.0f; if (GATED) rs = rs_of(rsq_in, row);
;                 float ss = 0.f;
; #pragma unroll
;                 for (int bj = 0; bj < 2; ++bj) { u32x4* p = (u32x4*)(H + ro + bj * HALF); const u32x4 hw = *p; const f32x4 a0 = acc[ai][bj][m][0], a1 = acc[ai][bj][m][1];
;                     float h[8] = {bf_lo(hw.x), bf_hi(hw.x), bf_lo(hw.y), bf_hi(hw.y), bf_lo(hw.z), bf_hi(hw.z), bf_lo(hw.w), bf_hi(hw.w)};
;                     if (GATED) { const u32x4 pw = *(const u32x4*)(PP + ro + bj * HALF);
;                         const float pp[8] = {bf_lo(pw.x), bf_hi(pw.x), bf_lo(pw.y), bf_hi(pw.y), bf_lo(pw.z), bf_hi(pw.z), bf_lo(pw.w), bf_hi(pw.w)};
; #pragma unroll
;                         for (int j = 0; j < 4; ++j) { h[j] += __builtin_amdgcn_rcpf(1.0f + __builtin_amdgcn_exp2f(-1.4426950408889634f * rs * a0[j])) * pp[j];
;                                                       h[4 + j] += __builtin_amdgcn_rcpf(1.0f + __builtin_amdgcn_exp2f(-1.4426950408889634f * rs * a1[j])) * pp[4 + j]; } }
;                     else {
; #pragma unroll
;                         for (int j = 0; j < 4; ++j) { h[j] += a0[j] * scale; h[4 + j] += a1[j] * scale; } }
;                     u32x4 w; w.x = cvt_pk_bf16(h[0], h[1]); w.y = cvt_pk_bf16(h[2], h[3]); w.z = cvt_pk_bf16(h[4], h[5]); w.w = cvt_pk_bf16(h[6], h[7]);
;                     *p = w; if (CP) *(u32x4*)(CP + ro + bj * HALF) = w;
;                     if (rsq_out) { const float r0 = bf_lo(w.x), r1 = bf_hi(w.x), r2 = bf_lo(w.y), r3 = bf_hi(w.y), r4 = bf_lo(w.z), r5 = bf_hi(w.z), r6 = bf_lo(w.w), r7 = bf_hi(w.w);
;                         ss += ((r0 * r0 + r1 * r1) + (r2 * r2 + r3 * r3)) + ((r4 * r4 + r5 * r5) + (r6 * r6 + r7 * r7)); } }
;                 if (rsq_out) { ss = sum_fq(ss); if (fq == 0) __hip_atomic_fetch_add(rsq_out + row, rsq_fix(ss), __ATOMIC_RELAXED, __HIP_MEMORY_SCOPE_AGENT); } }
	v_and_b32_e32 v94, 0xffff0000, v95
	v_lshlrev_b32_e32 v95, 16, v96
	v_and_b32_e32 v96, 0xffff0000, v96
	v_lshlrev_b32_e32 v98, 16, v97
	v_and_b32_e32 v97, 0xffff0000, v97
	v_add_f32_e32 v86, v86, v91
	v_add_f32_e32 v91, v82, v95
	v_add_f32_e32 v82, v87, v92
	v_add_f32_e32 v87, v83, v96
	v_add_f32_e32 v83, v88, v93
	v_add_f32_e32 v88, v84, v98
	v_add_f32_e32 v84, v89, v94
	v_add_f32_e32 v85, v85, v97
	v_cvt_pk_bf16_f32 v82, v86, v82
	v_cvt_pk_bf16_f32 v83, v83, v84
	v_cvt_pk_bf16_f32 v84, v91, v87
	v_cvt_pk_bf16_f32 v85, v88, v85
	global_store_dwordx4 v[102:103], v[82:85], off offset:256
	v_lshlrev_b32_e32 v86, 16, v82
	v_lshlrev_b32_e32 v87, 16, v83
	v_and_b32_e32 v82, 0xffff0000, v82
	v_and_b32_e32 v83, 0xffff0000, v83
	v_lshlrev_b32_e32 v88, 16, v84
	v_and_b32_e32 v84, 0xffff0000, v84
	v_lshlrev_b32_e32 v89, 16, v85
	v_and_b32_e32 v85, 0xffff0000, v85
	v_mul_f32_e32 v82, v82, v82
	v_mul_f32_e32 v83, v83, v83
	v_mul_f32_e32 v84, v84, v84
	v_mul_f32_e32 v85, v85, v85
	v_fmac_f32_e32 v82, v86, v86
	v_fmac_f32_e32 v83, v87, v87
	v_fmac_f32_e32 v84, v88, v88
	v_fmac_f32_e32 v85, v89, v89
	v_add_f32_e32 v82, v82, v83
	v_add_f32_e32 v83, v84, v85
	v_add_f32_e32 v82, v82, v83
	v_add_f32_e32 v82, v90, v82
	v_mov_b32_e32 v83, v82
	s_nop 1
	v_permlane16_swap_b32_e32 v82, v83
	v_add_f32_e32 v82, v82, v83
	v_mov_b32_e32 v83, v82
	s_nop 1
	v_permlane32_swap_b32_e32 v82, v83
	s_and_saveexec_b64 s[2:3], s[6:7]
	s_cbranch_execz .LBB0_1284
	v_add_f32_e32 v82, v82, v83
	s_mov_b32 s1, 0x49800000
	v_fma_f32 v82, v82, s1, 0.5
	v_trunc_f32_e32 v82, v82
	v_mul_f32_e32 v83, 0x2f800000, v82
	v_floor_f32_e32 v83, v83
	v_fmac_f32_e32 v82, 0xcf800000, v83
	v_cvt_u32_f32_e32 v82, v82
	v_cvt_u32_f32_e32 v83, v83
	global_atomic_add_x2 v[114:115], v[82:83], off offset:256
.LBB0_1284:
	s_or_b64 exec, exec, s[2:3]
	v_or_b32_e32 v82, 48, v144
	v_ashrrev_i32_e32 v83, 31, v82
	v_lshlrev_b64 v[82:83], 12, v[82:83]
	v_lshl_add_u64 v[82:83], s[12:13], 0, v[82:83]
	v_lshl_add_u64 v[86:87], v[142:143], 1, v[82:83]
	v_mov_b32_e32 v82, v166
	v_mov_b32_e32 v83, v167
	v_mov_b32_e32 v84, v168
	v_mov_b32_e32 v85, v169
	v_lshlrev_b32_e32 v88, 16, v82
	v_and_b32_e32 v82, 0xffff0000, v82
	v_lshlrev_b32_e32 v89, 16, v83
	v_and_b32_e32 v83, 0xffff0000, v83
	v_lshlrev_b32_e32 v90, 16, v84
	v_and_b32_e32 v84, 0xffff0000, v84
	v_lshlrev_b32_e32 v91, 16, v85
	v_and_b32_e32 v85, 0xffff0000, v85
	v_add_f32_e32 v78, v78, v88
	v_add_f32_e32 v88, v74, v90
	v_add_f32_e32 v74, v79, v82
	v_add_f32_e32 v79, v75, v84
	v_add_f32_e32 v75, v80, v89
	v_add_f32_e32 v80, v76, v91
	v_add_f32_e32 v76, v81, v83
	v_add_f32_e32 v77, v77, v85
	v_cvt_pk_bf16_f32 v74, v78, v74
	v_cvt_pk_bf16_f32 v75, v75, v76
	v_cvt_pk_bf16_f32 v76, v88, v79
	v_cvt_pk_bf16_f32 v77, v80, v77
	v_mov_b32_e32 v78, v216
	v_mov_b32_e32 v79, v217
	v_mov_b32_e32 v80, v218
	v_mov_b32_e32 v81, v219
	v_lshlrev_b32_e32 v82, 16, v74
	global_store_dwordx4 v[86:87], v[74:77], off
	v_lshlrev_b32_e32 v83, 16, v75
	v_lshlrev_b32_e32 v84, 16, v76
	v_and_b32_e32 v74, 0xffff0000, v74
	v_and_b32_e32 v75, 0xffff0000, v75
	v_and_b32_e32 v76, 0xffff0000, v76
	v_lshlrev_b32_e32 v85, 16, v77
	v_and_b32_e32 v77, 0xffff0000, v77
	v_mul_f32_e32 v74, v74, v74
	v_mul_f32_e32 v75, v75, v75
	v_mul_f32_e32 v76, v76, v76
	v_mul_f32_e32 v77, v77, v77
	v_fmac_f32_e32 v74, v82, v82
	v_fmac_f32_e32 v75, v83, v83
	v_fmac_f32_e32 v76, v84, v84
	v_fmac_f32_e32 v77, v85, v85
	v_add_f32_e32 v74, v74, v75
	v_add_f32_e32 v75, v76, v77
	v_add_f32_e32 v74, v74, v75
	v_lshlrev_b32_e32 v75, 16, v78
	v_and_b32_e32 v76, 0xffff0000, v78
	v_lshlrev_b32_e32 v77, 16, v79
	v_and_b32_e32 v78, 0xffff0000, v79
	v_lshlrev_b32_e32 v79, 16, v80
	v_and_b32_e32 v80, 0xffff0000, v80
	v_lshlrev_b32_e32 v82, 16, v81
	v_and_b32_e32 v81, 0xffff0000, v81
	v_add_f32_e32 v70, v70, v75
	v_add_f32_e32 v75, v66, v79
	v_add_f32_e32 v66, v71, v76
	v_add_f32_e32 v71, v67, v80
	v_add_f32_e32 v67, v72, v77
	v_add_f32_e32 v72, v68, v82
	v_add_f32_e32 v68, v73, v78
	v_add_f32_e32 v69, v69, v81
	v_cvt_pk_bf16_f32 v66, v70, v66
	v_cvt_pk_bf16_f32 v67, v67, v68
	v_cvt_pk_bf16_f32 v68, v75, v71
	v_cvt_pk_bf16_f32 v69, v72, v69
	global_store_dwordx4 v[86:87], v[66:69], off offset:256
	v_lshlrev_b32_e32 v70, 16, v66
	v_lshlrev_b32_e32 v71, 16, v67
	v_and_b32_e32 v66, 0xffff0000, v66
	v_and_b32_e32 v67, 0xffff0000, v67
	v_lshlrev_b32_e32 v72, 16, v68
	v_and_b32_e32 v68, 0xffff0000, v68
	v_lshlrev_b32_e32 v73, 16, v69
	v_and_b32_e32 v69, 0xffff0000, v69
	v_mul_f32_e32 v66, v66, v66
	v_mul_f32_e32 v67, v67, v67
	v_mul_f32_e32 v68, v68, v68
	v_mul_f32_e32 v69, v69, v69
	v_fmac_f32_e32 v66, v70, v70
	v_fmac_f32_e32 v67, v71, v71
	v_fmac_f32_e32 v68, v72, v72
	v_fmac_f32_e32 v69, v73, v73
	v_add_f32_e32 v66, v66, v67
	v_add_f32_e32 v67, v68, v69
	v_add_f32_e32 v66, v66, v67
	v_add_f32_e32 v66, v74, v66
	v_mov_b32_e32 v67, v66
	s_nop 1
	v_permlane16_swap_b32_e32 v66, v67
	v_add_f32_e32 v66, v66, v67
	v_mov_b32_e32 v67, v66
	s_nop 1
	v_permlane32_swap_b32_e32 v66, v67
	s_and_saveexec_b64 s[2:3], s[6:7]
	s_cbranch_execz .LBB0_1286
	v_add_f32_e32 v66, v66, v67
	s_mov_b32 s1, 0x49800000
	v_fma_f32 v66, v66, s1, 0.5
	v_trunc_f32_e32 v66, v66
	v_mul_f32_e32 v67, 0x2f800000, v66
	v_floor_f32_e32 v67, v67
	v_fmac_f32_e32 v66, 0xcf800000, v67
	v_cvt_u32_f32_e32 v66, v66
	v_cvt_u32_f32_e32 v67, v67
	global_atomic_add_x2 v[114:115], v[66:67], off offset:384
; __device__ __forceinline__ unsigned cvt_pk_bf16(float lo, float hi) { unsigned r; asm volatile("v_cvt_pk_bf16_f32 %0, %1, %2" : "=v"(r) : "v"(lo), "v"(hi)); return r; }
;     __device__ __forceinline__ void operator()(const f32x4 (&acc)[2][2][4][2], const Unit& u, int wr, int wc, int fr, int fq) const {
;     ...
;             for (int m = 0; m < 4; ++m) { const int row = row0 + ai * HALF + m * 16; const size_t ro = (size_t)row * ldc + col0;
;                 float rs = 1.0f; if (GATED) rs = rs_of(rsq_in, row);
;                 float ss = 0.f;
; #pragma unroll
;                 for (int bj = 0; bj < 2; ++bj) { u32x4* p = (u32x4*)(H + ro + bj * HALF); const u32x4 hw = *p; const f32x4 a0 = acc[ai][bj][m][0], a1 = acc[ai][bj][m][1];
;                     float h[8] = {bf_lo(hw.x), bf_hi(hw.x), bf_lo(hw.y), bf_hi(hw.y), bf_lo(hw.z), bf_hi(hw.z), bf_lo(hw.w), bf_hi(hw.w)};
;                     if (GATED) { const u32x4 pw = *(const u32x4*)(PP + ro + bj * HALF);
;                         const float pp[8] = {bf_lo(pw.x), bf_hi(pw.x), bf_lo(pw.y), bf_hi(pw.y), bf_lo(pw.z), bf_hi(pw.z), bf_lo(pw.w), bf_hi(pw.w)};
; #pragma unroll
;                         for (int j = 0; j < 4; ++j) { h[j] += __builtin_amdgcn_rcpf(1.0f + __builtin_amdgcn_exp2f(-1.4426950408889634f * rs * a0[j])) * pp[j];
;                                                       h[4 + j] += __builtin_amdgcn_rcpf(1.0f + __builtin_amdgcn_exp2f(-1.4426950408889634f * rs * a1[j])) * pp[4 + j]; } }
;                     else {
; #pragma unroll
;                         for (int j = 0; j < 4; ++j) { h[j] += a0[j] * scale; h[4 + j] += a1[j] * scale; } }
;                     u32x4 w; w.x = cvt_pk_bf16(h[0], h[1]); w.y = cvt_pk_bf16(h[2], h[3]); w.z = cvt_pk_bf16(h[4], h[5]); w.w = cvt_pk_bf16(h[6], h[7]);
;                     *p = w; if (CP) *(u32x4*)(CP + ro + bj * HALF) = w;
;                     if (rsq_out) { const float r0 = bf_lo(w.x), r1 = bf_hi(w.x), r2 = bf_lo(w.y), r3 = bf_hi(w.y), r4 = bf_lo(w.z), r5 = bf_hi(w.z), r6 = bf_lo(w.w), r7 = bf_hi(w.w);
;                         ss += ((r0 * r0 + r1 * r1) + (r2 * r2 + r3 * r3)) + ((r4 * r4 + r5 * r5) + (r6 * r6 + r7 * r7)); } }
;                 if (rsq_out) { ss = sum_fq(ss); if (fq == 0) __hip_atomic_fetch_add(rsq_out + row, rsq_fix(ss), __ATOMIC_RELAXED, __HIP_MEMORY_SCOPE_AGENT); } }
.LBB0_1286:
	s_or_b64 exec, exec, s[2:3]
	v_add_co_u32_e32 v70, vcc, 0x80000, v140
	s_mov_b64 s[2:3], 0x80000
	s_nop 0
	v_addc_co_u32_e32 v71, vcc, 0, v141, vcc
	v_mov_b32_e32 v66, v170
	v_mov_b32_e32 v67, v171
	v_mov_b32_e32 v68, v172
	v_mov_b32_e32 v69, v173
	v_lshl_add_u64 v[72:73], v[140:141], 0, s[2:3]
	v_lshlrev_b32_e32 v74, 16, v66
	v_and_b32_e32 v66, 0xffff0000, v66
	v_lshlrev_b32_e32 v75, 16, v67
	v_and_b32_e32 v67, 0xffff0000, v67
	v_lshlrev_b32_e32 v76, 16, v68
	v_and_b32_e32 v68, 0xffff0000, v68
	v_lshlrev_b32_e32 v77, 16, v69
	v_and_b32_e32 v69, 0xffff0000, v69
	v_add_f32_e32 v62, v62, v74
	v_add_f32_e32 v74, v58, v76
	v_add_f32_e32 v58, v63, v66
	v_add_f32_e32 v63, v59, v68
	v_add_f32_e32 v59, v64, v75
	v_add_f32_e32 v64, v60, v77
	v_add_f32_e32 v60, v65, v67
	v_add_f32_e32 v61, v61, v69
	v_cvt_pk_bf16_f32 v58, v62, v58
	v_cvt_pk_bf16_f32 v59, v59, v60
	v_cvt_pk_bf16_f32 v60, v74, v63
	v_cvt_pk_bf16_f32 v61, v64, v61
	global_load_dwordx4 v[62:65], v[72:73], off offset:256
	v_lshlrev_b32_e32 v66, 16, v58
	global_store_dwordx4 v[70:71], v[58:61], off
	v_lshlrev_b32_e32 v67, 16, v59
	v_lshlrev_b32_e32 v68, 16, v60
	v_and_b32_e32 v58, 0xffff0000, v58
	v_and_b32_e32 v59, 0xffff0000, v59
	v_and_b32_e32 v60, 0xffff0000, v60
	v_lshlrev_b32_e32 v69, 16, v61
	v_and_b32_e32 v61, 0xffff0000, v61
	v_mul_f32_e32 v58, v58, v58
	v_mul_f32_e32 v59, v59, v59
	v_mul_f32_e32 v60, v60, v60
	v_mul_f32_e32 v61, v61, v61
	v_fmac_f32_e32 v58, v66, v66
	v_fmac_f32_e32 v59, v67, v67
	v_fmac_f32_e32 v60, v68, v68
	v_fmac_f32_e32 v61, v69, v69
	v_add_f32_e32 v58, v58, v59
	v_add_f32_e32 v59, v60, v61
	v_add_f32_e32 v58, v58, v59
	s_waitcnt vmcnt(1)
	v_lshlrev_b32_e32 v59, 16, v62
	v_and_b32_e32 v60, 0xffff0000, v62
	v_lshlrev_b32_e32 v61, 16, v63
	v_and_b32_e32 v62, 0xffff0000, v63
	v_lshlrev_b32_e32 v63, 16, v64
	v_and_b32_e32 v64, 0xffff0000, v64
	v_lshlrev_b32_e32 v66, 16, v65
	v_and_b32_e32 v65, 0xffff0000, v65
	v_add_f32_e32 v54, v54, v59
	v_add_f32_e32 v59, v50, v63
	v_add_f32_e32 v50, v55, v60
	v_add_f32_e32 v55, v51, v64
	v_add_f32_e32 v51, v56, v61
	v_add_f32_e32 v56, v52, v66
	v_add_f32_e32 v52, v57, v62
	v_add_f32_e32 v53, v53, v65
	v_cvt_pk_bf16_f32 v50, v54, v50
	v_cvt_pk_bf16_f32 v51, v51, v52
	v_cvt_pk_bf16_f32 v52, v59, v55
	v_cvt_pk_bf16_f32 v53, v56, v53
	global_store_dwordx4 v[72:73], v[50:53], off offset:256
	v_lshlrev_b32_e32 v54, 16, v50
	v_lshlrev_b32_e32 v55, 16, v51
	v_and_b32_e32 v50, 0xffff0000, v50
	v_and_b32_e32 v51, 0xffff0000, v51
	v_lshlrev_b32_e32 v56, 16, v52
	v_and_b32_e32 v52, 0xffff0000, v52
	v_lshlrev_b32_e32 v57, 16, v53
	v_and_b32_e32 v53, 0xffff0000, v53
	v_mul_f32_e32 v50, v50, v50
	v_mul_f32_e32 v51, v51, v51
	v_mul_f32_e32 v52, v52, v52
	v_mul_f32_e32 v53, v53, v53
	v_fmac_f32_e32 v50, v54, v54
	v_fmac_f32_e32 v51, v55, v55
	v_fmac_f32_e32 v52, v56, v56
	v_fmac_f32_e32 v53, v57, v57
	v_add_f32_e32 v50, v50, v51
	v_add_f32_e32 v51, v52, v53
	v_add_f32_e32 v50, v50, v51
	v_add_f32_e32 v50, v58, v50
	v_mov_b32_e32 v51, v50
	s_nop 1
	v_permlane16_swap_b32_e32 v50, v51
	v_add_f32_e32 v50, v50, v51
	v_mov_b32_e32 v51, v50
	s_nop 1
	v_permlane32_swap_b32_e32 v50, v51
	s_and_saveexec_b64 s[2:3], s[6:7]
	s_cbranch_execz .LBB0_1288
	v_add_f32_e32 v50, v50, v51
	s_mov_b32 s1, 0x49800000
	v_fma_f32 v50, v50, s1, 0.5
	v_trunc_f32_e32 v50, v50
	v_mul_f32_e32 v51, 0x2f800000, v50
	v_floor_f32_e32 v51, v51
	v_fmac_f32_e32 v50, 0xcf800000, v51
	v_cvt_u32_f32_e32 v50, v50
	v_cvt_u32_f32_e32 v51, v51
	global_atomic_add_x2 v[114:115], v[50:51], off offset:1024
.LBB0_1288:
	s_or_b64 exec, exec, s[2:3]
	v_add_co_u32_e32 v54, vcc, 0x90000, v140
	v_lshl_add_u64 v[56:57], v[140:141], 0, s[54:55]
	s_nop 0
	v_addc_co_u32_e32 v55, vcc, 0, v141, vcc
	v_mov_b32_e32 v50, v174
	v_mov_b32_e32 v51, v175
	v_mov_b32_e32 v52, v176
	v_mov_b32_e32 v53, v177
	v_lshlrev_b32_e32 v58, 16, v50
	v_and_b32_e32 v50, 0xffff0000, v50
	v_lshlrev_b32_e32 v59, 16, v51
	v_and_b32_e32 v51, 0xffff0000, v51
	v_lshlrev_b32_e32 v60, 16, v52
	v_and_b32_e32 v52, 0xffff0000, v52
	v_lshlrev_b32_e32 v61, 16, v53
	v_and_b32_e32 v53, 0xffff0000, v53
	v_add_f32_e32 v46, v46, v58
	v_add_f32_e32 v58, v42, v60
	v_add_f32_e32 v42, v47, v50
	v_add_f32_e32 v47, v43, v52
	v_add_f32_e32 v43, v48, v59
	v_add_f32_e32 v48, v44, v61
	v_add_f32_e32 v44, v49, v51
	v_add_f32_e32 v45, v45, v53
	v_cvt_pk_bf16_f32 v42, v46, v42
	v_cvt_pk_bf16_f32 v43, v43, v44
	v_cvt_pk_bf16_f32 v44, v58, v47
	v_cvt_pk_bf16_f32 v45, v48, v45
	global_load_dwordx4 v[46:49], v[56:57], off offset:256
	v_lshlrev_b32_e32 v50, 16, v42
	global_store_dwordx4 v[54:55], v[42:45], off
	v_lshlrev_b32_e32 v51, 16, v43
	v_lshlrev_b32_e32 v52, 16, v44
	v_and_b32_e32 v42, 0xffff0000, v42
	v_and_b32_e32 v43, 0xffff0000, v43
	v_and_b32_e32 v44, 0xffff0000, v44
	v_lshlrev_b32_e32 v53, 16, v45
	v_and_b32_e32 v45, 0xffff0000, v45
	v_mul_f32_e32 v42, v42, v42
	v_mul_f32_e32 v43, v43, v43
	v_mul_f32_e32 v44, v44, v44
	v_mul_f32_e32 v45, v45, v45
	v_fmac_f32_e32 v42, v50, v50
	v_fmac_f32_e32 v43, v51, v51
	v_fmac_f32_e32 v44, v52, v52
	v_fmac_f32_e32 v45, v53, v53
	v_add_f32_e32 v42, v42, v43
	v_add_f32_e32 v43, v44, v45
	v_add_f32_e32 v42, v42, v43
	s_waitcnt vmcnt(1)
	v_lshlrev_b32_e32 v43, 16, v46
	v_and_b32_e32 v44, 0xffff0000, v46
	v_lshlrev_b32_e32 v45, 16, v47
	v_and_b32_e32 v46, 0xffff0000, v47
	v_lshlrev_b32_e32 v47, 16, v48
	v_and_b32_e32 v48, 0xffff0000, v48
	v_lshlrev_b32_e32 v50, 16, v49
	v_and_b32_e32 v49, 0xffff0000, v49
	v_add_f32_e32 v38, v38, v43
	v_add_f32_e32 v43, v34, v47
	v_add_f32_e32 v34, v39, v44
	v_add_f32_e32 v39, v35, v48
	v_add_f32_e32 v35, v40, v45
	v_add_f32_e32 v40, v36, v50
	v_add_f32_e32 v36, v41, v46
	v_add_f32_e32 v37, v37, v49
	v_cvt_pk_bf16_f32 v34, v38, v34
	v_cvt_pk_bf16_f32 v35, v35, v36
	v_cvt_pk_bf16_f32 v36, v43, v39
	v_cvt_pk_bf16_f32 v37, v40, v37
	global_store_dwordx4 v[56:57], v[34:37], off offset:256
	v_lshlrev_b32_e32 v38, 16, v34
	v_lshlrev_b32_e32 v39, 16, v35
	v_and_b32_e32 v34, 0xffff0000, v34
	v_and_b32_e32 v35, 0xffff0000, v35
	v_lshlrev_b32_e32 v40, 16, v36
	v_and_b32_e32 v36, 0xffff0000, v36
	v_lshlrev_b32_e32 v41, 16, v37
	v_and_b32_e32 v37, 0xffff0000, v37
	v_mul_f32_e32 v34, v34, v34
	v_mul_f32_e32 v35, v35, v35
	v_mul_f32_e32 v36, v36, v36
	v_mul_f32_e32 v37, v37, v37
	v_fmac_f32_e32 v34, v38, v38
	v_fmac_f32_e32 v35, v39, v39
	v_fmac_f32_e32 v36, v40, v40
	v_fmac_f32_e32 v37, v41, v41
	v_add_f32_e32 v34, v34, v35
	v_add_f32_e32 v35, v36, v37
	v_add_f32_e32 v34, v34, v35
	v_add_f32_e32 v34, v42, v34
	v_mov_b32_e32 v35, v34
	s_nop 1
	v_permlane16_swap_b32_e32 v34, v35
	v_add_f32_e32 v34, v34, v35
	v_mov_b32_e32 v35, v34
	s_nop 1
	v_permlane32_swap_b32_e32 v34, v35
	s_and_saveexec_b64 s[2:3], s[6:7]
	s_cbranch_execz .LBB0_1290
	v_add_f32_e32 v34, v34, v35
	s_mov_b32 s1, 0x49800000
	v_fma_f32 v34, v34, s1, 0.5
	v_trunc_f32_e32 v34, v34
	v_mul_f32_e32 v35, 0x2f800000, v34
	v_floor_f32_e32 v35, v35
	v_fmac_f32_e32 v34, 0xcf800000, v35
	v_cvt_u32_f32_e32 v34, v34
	v_cvt_u32_f32_e32 v35, v35
	global_atomic_add_x2 v[114:115], v[34:35], off offset:1152
; __device__ __forceinline__ unsigned cvt_pk_bf16(float lo, float hi) { unsigned r; asm volatile("v_cvt_pk_bf16_f32 %0, %1, %2" : "=v"(r) : "v"(lo), "v"(hi)); return r; }
;     __device__ __forceinline__ void operator()(const f32x4 (&acc)[2][2][4][2], const Unit& u, int wr, int wc, int fr, int fq) const {
;     ...
;             for (int m = 0; m < 4; ++m) { const int row = row0 + ai * HALF + m * 16; const size_t ro = (size_t)row * ldc + col0;
;                 float rs = 1.0f; if (GATED) rs = rs_of(rsq_in, row);
;                 float ss = 0.f;
; #pragma unroll
;                 for (int bj = 0; bj < 2; ++bj) { u32x4* p = (u32x4*)(H + ro + bj * HALF); const u32x4 hw = *p; const f32x4 a0 = acc[ai][bj][m][0], a1 = acc[ai][bj][m][1];
;                     float h[8] = {bf_lo(hw.x), bf_hi(hw.x), bf_lo(hw.y), bf_hi(hw.y), bf_lo(hw.z), bf_hi(hw.z), bf_lo(hw.w), bf_hi(hw.w)};
;                     if (GATED) { const u32x4 pw = *(const u32x4*)(PP + ro + bj * HALF);
;                         const float pp[8] = {bf_lo(pw.x), bf_hi(pw.x), bf_lo(pw.y), bf_hi(pw.y), bf_lo(pw.z), bf_hi(pw.z), bf_lo(pw.w), bf_hi(pw.w)};
; #pragma unroll
;                         for (int j = 0; j < 4; ++j) { h[j] += __builtin_amdgcn_rcpf(1.0f + __builtin_amdgcn_exp2f(-1.4426950408889634f * rs * a0[j])) * pp[j];
;                                                       h[4 + j] += __builtin_amdgcn_rcpf(1.0f + __builtin_amdgcn_exp2f(-1.4426950408889634f * rs * a1[j])) * pp[4 + j]; } }
;                     else {
; #pragma unroll
;                         for (int j = 0; j < 4; ++j) { h[j] += a0[j] * scale; h[4 + j] += a1[j] * scale; } }
;                     u32x4 w; w.x = cvt_pk_bf16(h[0], h[1]); w.y = cvt_pk_bf16(h[2], h[3]); w.z = cvt_pk_bf16(h[4], h[5]); w.w = cvt_pk_bf16(h[6], h[7]);
;                     *p = w; if (CP) *(u32x4*)(CP + ro + bj * HALF) = w;
;                     if (rsq_out) { const float r0 = bf_lo(w.x), r1 = bf_hi(w.x), r2 = bf_lo(w.y), r3 = bf_hi(w.y), r4 = bf_lo(w.z), r5 = bf_hi(w.z), r6 = bf_lo(w.w), r7 = bf_hi(w.w);
;                         ss += ((r0 * r0 + r1 * r1) + (r2 * r2 + r3 * r3)) + ((r4 * r4 + r5 * r5) + (r6 * r6 + r7 * r7)); } }
;                 if (rsq_out) { ss = sum_fq(ss); if (fq == 0) __hip_atomic_fetch_add(rsq_out + row, rsq_fix(ss), __ATOMIC_RELAXED, __HIP_MEMORY_SCOPE_AGENT); } }
.LBB0_1290:
	s_or_b64 exec, exec, s[2:3]
	v_add_co_u32_e32 v38, vcc, 0xa0000, v140
	s_mov_b64 s[2:3], 0xa0000
	s_nop 0
	v_addc_co_u32_e32 v39, vcc, 0, v141, vcc
	v_mov_b32_e32 v34, v186
	v_mov_b32_e32 v35, v187
	v_mov_b32_e32 v36, v188
	v_mov_b32_e32 v37, v189
	v_lshl_add_u64 v[40:41], v[140:141], 0, s[2:3]
	v_lshlrev_b32_e32 v42, 16, v34
	v_and_b32_e32 v34, 0xffff0000, v34
	v_lshlrev_b32_e32 v43, 16, v35
	v_and_b32_e32 v35, 0xffff0000, v35
	v_lshlrev_b32_e32 v44, 16, v36
	v_and_b32_e32 v36, 0xffff0000, v36
	v_lshlrev_b32_e32 v45, 16, v37
	v_and_b32_e32 v37, 0xffff0000, v37
	v_add_f32_e32 v30, v30, v42
	v_add_f32_e32 v42, v26, v44
	v_add_f32_e32 v26, v31, v34
	v_add_f32_e32 v31, v27, v36
	v_add_f32_e32 v27, v32, v43
	v_add_f32_e32 v32, v28, v45
	v_add_f32_e32 v28, v33, v35
	v_add_f32_e32 v29, v29, v37
	v_cvt_pk_bf16_f32 v26, v30, v26
	v_cvt_pk_bf16_f32 v27, v27, v28
	v_cvt_pk_bf16_f32 v28, v42, v31
	v_cvt_pk_bf16_f32 v29, v32, v29
	global_load_dwordx4 v[30:33], v[40:41], off offset:256
	v_lshlrev_b32_e32 v34, 16, v26
	global_store_dwordx4 v[38:39], v[26:29], off
	v_lshlrev_b32_e32 v35, 16, v27
	v_lshlrev_b32_e32 v36, 16, v28
	v_and_b32_e32 v26, 0xffff0000, v26
	v_and_b32_e32 v27, 0xffff0000, v27
	v_and_b32_e32 v28, 0xffff0000, v28
	v_lshlrev_b32_e32 v37, 16, v29
	v_and_b32_e32 v29, 0xffff0000, v29
	v_mul_f32_e32 v26, v26, v26
	v_mul_f32_e32 v27, v27, v27
	v_mul_f32_e32 v28, v28, v28
	v_mul_f32_e32 v29, v29, v29
	v_fmac_f32_e32 v26, v34, v34
	v_fmac_f32_e32 v27, v35, v35
	v_fmac_f32_e32 v28, v36, v36
	v_fmac_f32_e32 v29, v37, v37
	v_add_f32_e32 v26, v26, v27
	v_add_f32_e32 v27, v28, v29
	v_add_f32_e32 v26, v26, v27
	s_waitcnt vmcnt(1)
	v_lshlrev_b32_e32 v27, 16, v30
	v_and_b32_e32 v28, 0xffff0000, v30
	v_lshlrev_b32_e32 v29, 16, v31
	v_and_b32_e32 v30, 0xffff0000, v31
	v_lshlrev_b32_e32 v31, 16, v32
	v_and_b32_e32 v32, 0xffff0000, v32
	v_lshlrev_b32_e32 v34, 16, v33
	v_and_b32_e32 v33, 0xffff0000, v33
	v_add_f32_e32 v22, v22, v27
	v_add_f32_e32 v27, v18, v31
	v_add_f32_e32 v18, v23, v28
	v_add_f32_e32 v23, v19, v32
	v_add_f32_e32 v19, v24, v29
	v_add_f32_e32 v24, v20, v34
	v_add_f32_e32 v20, v25, v30
	v_add_f32_e32 v21, v21, v33
	v_cvt_pk_bf16_f32 v18, v22, v18
	v_cvt_pk_bf16_f32 v19, v19, v20
	v_cvt_pk_bf16_f32 v20, v27, v23
	v_cvt_pk_bf16_f32 v21, v24, v21
	global_store_dwordx4 v[40:41], v[18:21], off offset:256
	v_lshlrev_b32_e32 v22, 16, v18
	v_lshlrev_b32_e32 v23, 16, v19
	v_and_b32_e32 v18, 0xffff0000, v18
	v_and_b32_e32 v19, 0xffff0000, v19
	v_lshlrev_b32_e32 v24, 16, v20
	v_and_b32_e32 v20, 0xffff0000, v20
	v_lshlrev_b32_e32 v25, 16, v21
	v_and_b32_e32 v21, 0xffff0000, v21
	v_mul_f32_e32 v18, v18, v18
	v_mul_f32_e32 v19, v19, v19
	v_mul_f32_e32 v20, v20, v20
	v_mul_f32_e32 v21, v21, v21
	v_fmac_f32_e32 v18, v22, v22
	v_fmac_f32_e32 v19, v23, v23
	v_fmac_f32_e32 v20, v24, v24
	v_fmac_f32_e32 v21, v25, v25
	v_add_f32_e32 v18, v18, v19
	v_add_f32_e32 v19, v20, v21
	v_add_f32_e32 v18, v18, v19
	v_add_f32_e32 v18, v26, v18
	v_mov_b32_e32 v19, v18
	s_nop 1
	v_permlane16_swap_b32_e32 v18, v19
	v_add_f32_e32 v18, v18, v19
	v_mov_b32_e32 v19, v18
	s_nop 1
	v_permlane32_swap_b32_e32 v18, v19
	s_and_saveexec_b64 s[2:3], s[6:7]
	s_cbranch_execz .LBB0_1292
	v_add_f32_e32 v18, v18, v19
	s_mov_b32 s1, 0x49800000
	v_fma_f32 v18, v18, s1, 0.5
	v_trunc_f32_e32 v18, v18
	v_mul_f32_e32 v19, 0x2f800000, v18
	v_floor_f32_e32 v19, v19
	v_fmac_f32_e32 v18, 0xcf800000, v19
	v_cvt_u32_f32_e32 v18, v18
	v_cvt_u32_f32_e32 v19, v19
	global_atomic_add_x2 v[114:115], v[18:19], off offset:1280
.LBB0_1292:
	s_or_b64 exec, exec, s[2:3]
	v_add_co_u32_e32 v24, vcc, 0xb0000, v140
	s_mov_b64 s[2:3], 0xb0000
	s_nop 0
	v_addc_co_u32_e32 v25, vcc, 0, v141, vcc
	v_mov_b32_e32 v18, v190
	v_mov_b32_e32 v19, v191
	v_mov_b32_e32 v20, v192
	v_mov_b32_e32 v21, v193
	v_lshl_add_u64 v[22:23], v[140:141], 0, s[2:3]
	v_lshlrev_b32_e32 v26, 16, v18
	v_and_b32_e32 v18, 0xffff0000, v18
	v_lshlrev_b32_e32 v27, 16, v19
	v_lshlrev_b32_e32 v28, 16, v20
	v_and_b32_e32 v20, 0xffff0000, v20
	v_and_b32_e32 v19, 0xffff0000, v19
	v_lshlrev_b32_e32 v29, 16, v21
	v_and_b32_e32 v21, 0xffff0000, v21
	v_add_f32_e32 v14, v14, v26
	v_add_f32_e32 v26, v10, v28
	v_add_f32_e32 v10, v15, v18
	v_add_f32_e32 v15, v11, v20
	v_add_f32_e32 v11, v16, v27
	v_add_f32_e32 v16, v12, v29
	v_add_f32_e32 v12, v17, v19
	v_add_f32_e32 v13, v13, v21
	v_cvt_pk_bf16_f32 v10, v14, v10
	v_cvt_pk_bf16_f32 v11, v11, v12
	v_cvt_pk_bf16_f32 v12, v26, v15
	v_cvt_pk_bf16_f32 v13, v16, v13
	global_store_dwordx4 v[24:25], v[10:13], off
	v_lshlrev_b32_e32 v14, 16, v10
	v_lshlrev_b32_e32 v15, 16, v11
	v_and_b32_e32 v10, 0xffff0000, v10
	v_and_b32_e32 v11, 0xffff0000, v11
	v_mul_f32_e32 v10, v10, v10
	v_mul_f32_e32 v11, v11, v11
	v_lshlrev_b32_e32 v16, 16, v12
	v_and_b32_e32 v12, 0xffff0000, v12
	v_lshlrev_b32_e32 v17, 16, v13
	v_and_b32_e32 v13, 0xffff0000, v13
	v_fmac_f32_e32 v10, v14, v14
	v_fmac_f32_e32 v11, v15, v15
	v_add_f32_e32 v10, v10, v11
	v_mul_f32_e32 v11, v12, v12
	v_mul_f32_e32 v12, v13, v13
	v_fmac_f32_e32 v11, v16, v16
	v_fmac_f32_e32 v12, v17, v17
	v_add_f32_e32 v11, v11, v12
	v_add_f32_e32 v14, v10, v11
	global_load_dwordx4 v[10:13], v[22:23], off offset:256
	s_waitcnt vmcnt(0)
	v_lshlrev_b32_e32 v15, 16, v10
	v_and_b32_e32 v10, 0xffff0000, v10
	v_lshlrev_b32_e32 v16, 16, v11
	v_lshlrev_b32_e32 v17, 16, v12
	v_and_b32_e32 v12, 0xffff0000, v12
	v_and_b32_e32 v11, 0xffff0000, v11
	v_lshlrev_b32_e32 v18, 16, v13
	v_and_b32_e32 v13, 0xffff0000, v13
	v_add_f32_e32 v6, v6, v15
	v_add_f32_e32 v15, v2, v17
	v_add_f32_e32 v2, v7, v10
	v_add_f32_e32 v7, v3, v12
	v_add_f32_e32 v3, v8, v16
	v_add_f32_e32 v8, v4, v18
	v_add_f32_e32 v4, v9, v11
	v_add_f32_e32 v5, v5, v13
	v_cvt_pk_bf16_f32 v2, v6, v2
	v_cvt_pk_bf16_f32 v3, v3, v4
	v_cvt_pk_bf16_f32 v4, v15, v7
	v_cvt_pk_bf16_f32 v5, v8, v5
	global_store_dwordx4 v[22:23], v[2:5], off offset:256
	v_lshlrev_b32_e32 v6, 16, v2
	v_lshlrev_b32_e32 v7, 16, v3
	v_and_b32_e32 v2, 0xffff0000, v2
	v_and_b32_e32 v3, 0xffff0000, v3
	v_mul_f32_e32 v2, v2, v2
	v_mul_f32_e32 v3, v3, v3
	v_lshlrev_b32_e32 v8, 16, v4
	v_and_b32_e32 v4, 0xffff0000, v4
	v_lshlrev_b32_e32 v9, 16, v5
	v_and_b32_e32 v5, 0xffff0000, v5
	v_fmac_f32_e32 v2, v6, v6
	v_fmac_f32_e32 v3, v7, v7
	v_add_f32_e32 v2, v2, v3
	v_mul_f32_e32 v3, v4, v4
	v_mul_f32_e32 v4, v5, v5
	v_fmac_f32_e32 v3, v8, v8
	v_fmac_f32_e32 v4, v9, v9
	v_add_f32_e32 v3, v3, v4
	v_add_f32_e32 v2, v2, v3
	v_add_f32_e32 v2, v14, v2
	v_mov_b32_e32 v3, v2
	s_nop 1
	v_permlane16_swap_b32_e32 v2, v3
	v_add_f32_e32 v2, v2, v3
	v_mov_b32_e32 v3, v2
	s_nop 1
	v_permlane32_swap_b32_e32 v2, v3
	s_and_saveexec_b64 s[2:3], s[6:7]
	s_cbranch_execz .LBB0_1294
	v_add_f32_e32 v2, v2, v3
	s_mov_b32 s1, 0x49800000
	v_fma_f32 v2, v2, s1, 0.5
	v_trunc_f32_e32 v2, v2
	v_mul_f32_e32 v3, 0x2f800000, v2
	v_floor_f32_e32 v3, v3
	v_fmac_f32_e32 v2, 0xcf800000, v3
	v_cvt_u32_f32_e32 v2, v2
	v_cvt_u32_f32_e32 v3, v3
	global_atomic_add_x2 v[114:115], v[2:3], off offset:1408

; __device__ __forceinline__ unsigned cvt_pk_bf16(float lo, float hi) { unsigned r; asm volatile("v_cvt_pk_bf16_f32 %0, %1, %2" : "=v"(r) : "v"(lo), "v"(hi)); return r; }
;     __device__ __forceinline__ void operator()(const f32x4 (&acc)[2][2][4][2], const Unit& u, int wr, int wc, int fr, int fq) const {
;     ...
;             for (int m = 0; m < 4; ++m) { const int row = row0 + ai * HALF + m * 16; const size_t ro = (size_t)row * ldc + col0;
;                 float rs = 1.0f; if (GATED) rs = rs_of(rsq_in, row);
;                 float ss = 0.f;
; #pragma unroll
;                 for (int bj = 0; bj < 2; ++bj) { u32x4* p = (u32x4*)(H + ro + bj * HALF); const u32x4 hw = *p; const f32x4 a0 = acc[ai][bj][m][0], a1 = acc[ai][bj][m][1];
;                     float h[8] = {bf_lo(hw.x), bf_hi(hw.x), bf_lo(hw.y), bf_hi(hw.y), bf_lo(hw.z), bf_hi(hw.z), bf_lo(hw.w), bf_hi(hw.w)};
;                     if (GATED) { const u32x4 pw = *(const u32x4*)(PP + ro + bj * HALF);
;                         const float pp[8] = {bf_lo(pw.x), bf_hi(pw.x), bf_lo(pw.y), bf_hi(pw.y), bf_lo(pw.z), bf_hi(pw.z), bf_lo(pw.w), bf_hi(pw.w)};
; #pragma unroll
;                         for (int j = 0; j < 4; ++j) { h[j] += __builtin_amdgcn_rcpf(1.0f + __builtin_amdgcn_exp2f(-1.4426950408889634f * rs * a0[j])) * pp[j];
;                                                       h[4 + j] += __builtin_amdgcn_rcpf(1.0f + __builtin_amdgcn_exp2f(-1.4426950408889634f * rs * a1[j])) * pp[4 + j]; } }
;                     else {
; #pragma unroll
;                         for (int j = 0; j < 4; ++j) { h[j] += a0[j] * scale; h[4 + j] += a1[j] * scale; } }
;                     u32x4 w; w.x = cvt_pk_bf16(h[0], h[1]); w.y = cvt_pk_bf16(h[2], h[3]); w.z = cvt_pk_bf16(h[4], h[5]); w.w = cvt_pk_bf16(h[6], h[7]);
;                     *p = w; if (CP) *(u32x4*)(CP + ro + bj * HALF) = w;
;                     if (rsq_out) { const float r0 = bf_lo(w.x), r1 = bf_hi(w.x), r2 = bf_lo(w.y), r3 = bf_hi(w.y), r4 = bf_lo(w.z), r5 = bf_hi(w.z), r6 = bf_lo(w.w), r7 = bf_hi(w.w);
;                         ss += ((r0 * r0 + r1 * r1) + (r2 * r2 + r3 * r3)) + ((r4 * r4 + r5 * r5) + (r6 * r6 + r7 * r7)); } }
;                 if (rsq_out) { ss = sum_fq(ss); if (fq == 0) __hip_atomic_fetch_add(rsq_out + row, rsq_fix(ss), __ATOMIC_RELAXED, __HIP_MEMORY_SCOPE_AGENT); } }
.LBB0_1517:
	v_lshl_add_u32 v144, s1, 8, v146
	v_lshl_add_u32 v142, s42, 8, v148
	v_ashrrev_i32_e32 v145, 31, v144
	v_ashrrev_i32_e32 v143, 31, v142
	v_lshlrev_b64 v[140:141], 11, v[144:145]
	v_lshl_add_u64 v[140:141], v[140:141], 0, v[142:143]
	v_lshlrev_b64 v[154:155], 1, v[140:141]
	v_lshl_add_u64 v[156:157], s[12:13], 0, v[154:155]
	global_load_dwordx4 v[150:153], v[156:157], off
	v_mov_b32_e32 v224, 0x10000
	v_mov_b32_e32 v225, 0
	global_load_dwordx4 v[208:211], v[156:157], off offset:256
	v_lshl_add_u64 v[226:227], v[224:225], 0, v[156:157]
	global_load_dwordx4 v[162:165], v[226:227], off
	global_load_dwordx4 v[212:215], v[226:227], off offset:256
	v_lshl_add_u64 v[226:227], v[224:225], 0, v[226:227]
	global_load_dwordx4 v[166:169], v[226:227], off
	global_load_dwordx4 v[216:219], v[226:227], off offset:256
	v_lshl_add_u64 v[226:227], v[224:225], 0, v[226:227]
	global_load_dwordx4 v[170:173], v[226:227], off
	global_load_dwordx4 v[220:223], v[226:227], off offset:256
	v_lshl_add_u64 v[226:227], v[224:225], 3, v[156:157]
	global_load_dwordx4 v[174:177], v[226:227], off
	v_lshl_add_u64 v[226:227], v[224:225], 0, v[226:227]
	global_load_dwordx4 v[186:189], v[226:227], off
	v_lshl_add_u64 v[226:227], v[224:225], 0, v[226:227]
	global_load_dwordx4 v[190:193], v[226:227], off
	v_lshl_add_u64 v[226:227], v[224:225], 0, v[226:227]
	global_load_dwordx4 v[194:197], v[226:227], off
	s_waitcnt vmcnt(0)
	v_lshlrev_b32_e32 v158, 16, v150
	v_and_b32_e32 v150, 0xffff0000, v150
	v_lshlrev_b32_e32 v159, 16, v151
	v_and_b32_e32 v151, 0xffff0000, v151
	v_lshlrev_b32_e32 v160, 16, v152
	v_and_b32_e32 v152, 0xffff0000, v152
	v_lshlrev_b32_e32 v161, 16, v153
	v_and_b32_e32 v153, 0xffff0000, v153
	v_fmac_f32_e32 v158, 0.5, v126
	v_fmac_f32_e32 v160, 0.5, v122
	v_fmac_f32_e32 v150, 0.5, v127
	v_fmac_f32_e32 v152, 0.5, v123
	v_fmac_f32_e32 v159, 0.5, v128
	v_fmac_f32_e32 v161, 0.5, v124
	v_fmac_f32_e32 v151, 0.5, v129
	v_fmac_f32_e32 v153, 0.5, v125
	v_cvt_pk_bf16_f32 v122, v158, v150
	v_cvt_pk_bf16_f32 v123, v159, v151
	v_cvt_pk_bf16_f32 v124, v160, v152
	v_cvt_pk_bf16_f32 v125, v161, v153
	v_mov_b32_e32 v126, v208
	v_mov_b32_e32 v127, v209
	v_mov_b32_e32 v128, v210
	v_mov_b32_e32 v129, v211
	v_lshl_add_u64 v[150:151], s[20:21], 0, v[154:155]
	global_store_dwordx4 v[156:157], v[122:125], off
	global_store_dwordx4 v[150:151], v[122:125], off
	v_lshlrev_b32_e32 v152, 16, v122
	v_lshlrev_b32_e32 v153, 16, v123
	v_and_b32_e32 v122, 0xffff0000, v122
	v_and_b32_e32 v123, 0xffff0000, v123
	v_lshlrev_b32_e32 v154, 16, v124
	v_and_b32_e32 v124, 0xffff0000, v124
	v_lshlrev_b32_e32 v155, 16, v125
	v_and_b32_e32 v125, 0xffff0000, v125
	v_mul_f32_e32 v122, v122, v122
	v_mul_f32_e32 v123, v123, v123
	v_mul_f32_e32 v124, v124, v124
	v_mul_f32_e32 v125, v125, v125
	v_fmac_f32_e32 v122, v152, v152
	v_fmac_f32_e32 v123, v153, v153
	v_fmac_f32_e32 v124, v154, v154
	v_fmac_f32_e32 v125, v155, v155
	v_add_f32_e32 v122, v122, v123
	v_add_f32_e32 v123, v124, v125
	v_add_f32_e32 v122, v122, v123
	v_lshlrev_b32_e32 v123, 16, v126
	v_and_b32_e32 v124, 0xffff0000, v126
	v_lshlrev_b32_e32 v125, 16, v127
	v_and_b32_e32 v126, 0xffff0000, v127
	v_lshlrev_b32_e32 v127, 16, v128
	v_and_b32_e32 v128, 0xffff0000, v128
	v_lshlrev_b32_e32 v152, 16, v129
	v_and_b32_e32 v129, 0xffff0000, v129
	v_fmac_f32_e32 v123, 0.5, v118
	v_fmac_f32_e32 v127, 0.5, v114
	v_fmac_f32_e32 v124, 0.5, v119
	v_fmac_f32_e32 v128, 0.5, v115
	v_fmac_f32_e32 v125, 0.5, v120
	v_fmac_f32_e32 v152, 0.5, v116
	v_fmac_f32_e32 v126, 0.5, v121
	v_fmac_f32_e32 v129, 0.5, v117
	v_cvt_pk_bf16_f32 v114, v123, v124
	v_cvt_pk_bf16_f32 v115, v125, v126
	v_cvt_pk_bf16_f32 v116, v127, v128
	v_cvt_pk_bf16_f32 v117, v152, v129
	global_store_dwordx4 v[156:157], v[114:117], off offset:256
	global_store_dwordx4 v[150:151], v[114:117], off offset:256
	v_lshlrev_b32_e32 v118, 16, v114
	v_lshlrev_b32_e32 v119, 16, v115
	v_and_b32_e32 v114, 0xffff0000, v114
	v_and_b32_e32 v115, 0xffff0000, v115
	v_lshlrev_b32_e32 v120, 16, v116
	v_and_b32_e32 v116, 0xffff0000, v116
	v_lshlrev_b32_e32 v121, 16, v117
	v_and_b32_e32 v117, 0xffff0000, v117
	v_mul_f32_e32 v114, v114, v114
	v_mul_f32_e32 v115, v115, v115
	v_mul_f32_e32 v116, v116, v116
	v_mul_f32_e32 v117, v117, v117
	v_fmac_f32_e32 v114, v118, v118
	v_fmac_f32_e32 v115, v119, v119
	v_fmac_f32_e32 v116, v120, v120
	v_fmac_f32_e32 v117, v121, v121
	v_add_f32_e32 v114, v114, v115
	v_add_f32_e32 v115, v116, v117
	v_add_f32_e32 v114, v114, v115
	v_add_f32_e32 v114, v122, v114
	v_mov_b32_e32 v115, v114
	s_nop 1
	v_permlane16_swap_b32_e32 v114, v115
	v_add_f32_e32 v116, v114, v115
	v_mov_b32_e32 v117, v116
	s_nop 1
	v_permlane32_swap_b32_e32 v116, v117
	v_lshl_add_u64 v[114:115], v[144:145], 3, s[18:19]
	s_and_saveexec_b64 s[2:3], s[4:5]
	s_cbranch_execz .LBB0_1519
	v_add_f32_e32 v116, v116, v117
	s_mov_b32 s1, 0x49800000
	v_fma_f32 v116, v116, s1, 0.5
	v_trunc_f32_e32 v116, v116
	v_mul_f32_e32 v117, 0x2f800000, v116
	v_floor_f32_e32 v117, v117
	v_fmac_f32_e32 v116, 0xcf800000, v117
	v_cvt_u32_f32_e32 v116, v116
	v_cvt_u32_f32_e32 v117, v117
	global_atomic_add_x2 v[114:115], v[116:117], off
; __device__ __forceinline__ unsigned cvt_pk_bf16(float lo, float hi) { unsigned r; asm volatile("v_cvt_pk_bf16_f32 %0, %1, %2" : "=v"(r) : "v"(lo), "v"(hi)); return r; }
;     __device__ __forceinline__ void operator()(const f32x4 (&acc)[2][2][4][2], const Unit& u, int wr, int wc, int fr, int fq) const {
;     ...
;             for (int m = 0; m < 4; ++m) { const int row = row0 + ai * HALF + m * 16; const size_t ro = (size_t)row * ldc + col0;
;                 float rs = 1.0f; if (GATED) rs = rs_of(rsq_in, row);
;                 float ss = 0.f;
; #pragma unroll
;                 for (int bj = 0; bj < 2; ++bj) { u32x4* p = (u32x4*)(H + ro + bj * HALF); const u32x4 hw = *p; const f32x4 a0 = acc[ai][bj][m][0], a1 = acc[ai][bj][m][1];
;                     float h[8] = {bf_lo(hw.x), bf_hi(hw.x), bf_lo(hw.y), bf_hi(hw.y), bf_lo(hw.z), bf_hi(hw.z), bf_lo(hw.w), bf_hi(hw.w)};
;                     if (GATED) { const u32x4 pw = *(const u32x4*)(PP + ro + bj * HALF);
;                         const float pp[8] = {bf_lo(pw.x), bf_hi(pw.x), bf_lo(pw.y), bf_hi(pw.y), bf_lo(pw.z), bf_hi(pw.z), bf_lo(pw.w), bf_hi(pw.w)};
; #pragma unroll
;                         for (int j = 0; j < 4; ++j) { h[j] += __builtin_amdgcn_rcpf(1.0f + __builtin_amdgcn_exp2f(-1.4426950408889634f * rs * a0[j])) * pp[j];
;                                                       h[4 + j] += __builtin_amdgcn_rcpf(1.0f + __builtin_amdgcn_exp2f(-1.4426950408889634f * rs * a1[j])) * pp[4 + j]; } }
;                     else {
; #pragma unroll
;                         for (int j = 0; j < 4; ++j) { h[j] += a0[j] * scale; h[4 + j] += a1[j] * scale; } }
;                     u32x4 w; w.x = cvt_pk_bf16(h[0], h[1]); w.y = cvt_pk_bf16(h[2], h[3]); w.z = cvt_pk_bf16(h[4], h[5]); w.w = cvt_pk_bf16(h[6], h[7]);
;                     *p = w; if (CP) *(u32x4*)(CP + ro + bj * HALF) = w;
;                     if (rsq_out) { const float r0 = bf_lo(w.x), r1 = bf_hi(w.x), r2 = bf_lo(w.y), r3 = bf_hi(w.y), r4 = bf_lo(w.z), r5 = bf_hi(w.z), r6 = bf_lo(w.w), r7 = bf_hi(w.w);
;                         ss += ((r0 * r0 + r1 * r1) + (r2 * r2 + r3 * r3)) + ((r4 * r4 + r5 * r5) + (r6 * r6 + r7 * r7)); } }
;                 if (rsq_out) { ss = sum_fq(ss); if (fq == 0) __hip_atomic_fetch_add(rsq_out + row, rsq_fix(ss), __ATOMIC_RELAXED, __HIP_MEMORY_SCOPE_AGENT); } }
.LBB0_1519:
	s_or_b64 exec, exec, s[2:3]
	v_or_b32_e32 v116, 16, v144
	v_ashrrev_i32_e32 v117, 31, v116
	v_lshlrev_b64 v[116:117], 11, v[116:117]
	v_lshl_add_u64 v[116:117], v[116:117], 0, v[142:143]
	v_lshlrev_b64 v[120:121], 1, v[116:117]
	v_lshl_add_u64 v[122:123], s[12:13], 0, v[120:121]
	v_mov_b32_e32 v116, v162
	v_mov_b32_e32 v117, v163
	v_mov_b32_e32 v118, v164
	v_mov_b32_e32 v119, v165
	v_lshlrev_b32_e32 v124, 16, v116
	v_and_b32_e32 v116, 0xffff0000, v116
	v_lshlrev_b32_e32 v125, 16, v117
	v_and_b32_e32 v117, 0xffff0000, v117
	v_lshlrev_b32_e32 v126, 16, v118
	v_and_b32_e32 v118, 0xffff0000, v118
	v_lshlrev_b32_e32 v127, 16, v119
	v_and_b32_e32 v119, 0xffff0000, v119
	v_fmac_f32_e32 v124, 0.5, v110
	v_fmac_f32_e32 v126, 0.5, v106
	v_fmac_f32_e32 v116, 0.5, v111
	v_fmac_f32_e32 v118, 0.5, v107
	v_fmac_f32_e32 v125, 0.5, v112
	v_fmac_f32_e32 v127, 0.5, v108
	v_fmac_f32_e32 v117, 0.5, v113
	v_fmac_f32_e32 v119, 0.5, v109
	v_cvt_pk_bf16_f32 v106, v124, v116
	v_cvt_pk_bf16_f32 v107, v125, v117
	v_cvt_pk_bf16_f32 v108, v126, v118
	v_cvt_pk_bf16_f32 v109, v127, v119
	v_mov_b32_e32 v110, v212
	v_mov_b32_e32 v111, v213
	v_mov_b32_e32 v112, v214
	v_mov_b32_e32 v113, v215
	v_lshl_add_u64 v[116:117], s[20:21], 0, v[120:121]
	global_store_dwordx4 v[122:123], v[106:109], off
	global_store_dwordx4 v[116:117], v[106:109], off
	v_lshlrev_b32_e32 v118, 16, v106
	v_lshlrev_b32_e32 v119, 16, v107
	v_and_b32_e32 v106, 0xffff0000, v106
	v_and_b32_e32 v107, 0xffff0000, v107
	v_lshlrev_b32_e32 v120, 16, v108
	v_and_b32_e32 v108, 0xffff0000, v108
	v_lshlrev_b32_e32 v121, 16, v109
	v_and_b32_e32 v109, 0xffff0000, v109
	v_mul_f32_e32 v106, v106, v106
	v_mul_f32_e32 v107, v107, v107
	v_mul_f32_e32 v108, v108, v108
	v_mul_f32_e32 v109, v109, v109
	v_fmac_f32_e32 v106, v118, v118
	v_fmac_f32_e32 v107, v119, v119
	v_fmac_f32_e32 v108, v120, v120
	v_fmac_f32_e32 v109, v121, v121
	v_add_f32_e32 v106, v106, v107
	v_add_f32_e32 v107, v108, v109
	v_add_f32_e32 v106, v106, v107
	v_lshlrev_b32_e32 v107, 16, v110
	v_and_b32_e32 v108, 0xffff0000, v110
	v_lshlrev_b32_e32 v109, 16, v111
	v_and_b32_e32 v110, 0xffff0000, v111
	v_lshlrev_b32_e32 v111, 16, v112
	v_and_b32_e32 v112, 0xffff0000, v112
	v_lshlrev_b32_e32 v118, 16, v113
	v_and_b32_e32 v113, 0xffff0000, v113
	v_fmac_f32_e32 v107, 0.5, v102
	v_fmac_f32_e32 v111, 0.5, v98
	v_fmac_f32_e32 v108, 0.5, v103
	v_fmac_f32_e32 v112, 0.5, v99
	v_fmac_f32_e32 v109, 0.5, v104
	v_fmac_f32_e32 v118, 0.5, v100
	v_fmac_f32_e32 v110, 0.5, v105
	v_fmac_f32_e32 v113, 0.5, v101
	v_cvt_pk_bf16_f32 v98, v107, v108
	v_cvt_pk_bf16_f32 v99, v109, v110
	v_cvt_pk_bf16_f32 v100, v111, v112
	v_cvt_pk_bf16_f32 v101, v118, v113
	global_store_dwordx4 v[122:123], v[98:101], off offset:256
	global_store_dwordx4 v[116:117], v[98:101], off offset:256
	v_lshlrev_b32_e32 v102, 16, v98
	v_lshlrev_b32_e32 v103, 16, v99
	v_and_b32_e32 v98, 0xffff0000, v98
	v_and_b32_e32 v99, 0xffff0000, v99
	v_lshlrev_b32_e32 v104, 16, v100
	v_and_b32_e32 v100, 0xffff0000, v100
	v_lshlrev_b32_e32 v105, 16, v101
	v_and_b32_e32 v101, 0xffff0000, v101
	v_mul_f32_e32 v98, v98, v98
	v_mul_f32_e32 v99, v99, v99
	v_mul_f32_e32 v100, v100, v100
	v_mul_f32_e32 v101, v101, v101
	v_fmac_f32_e32 v98, v102, v102
	v_fmac_f32_e32 v99, v103, v103
	v_fmac_f32_e32 v100, v104, v104
	v_fmac_f32_e32 v101, v105, v105
	v_add_f32_e32 v98, v98, v99
	v_add_f32_e32 v99, v100, v101
	v_add_f32_e32 v98, v98, v99
	v_add_f32_e32 v98, v106, v98
	v_mov_b32_e32 v99, v98
	s_nop 1
	v_permlane16_swap_b32_e32 v98, v99
	v_add_f32_e32 v98, v98, v99
	v_mov_b32_e32 v99, v98
	s_nop 1
	v_permlane32_swap_b32_e32 v98, v99
	s_and_saveexec_b64 s[2:3], s[4:5]
	s_cbranch_execz .LBB0_1521
	v_add_f32_e32 v98, v98, v99
	s_mov_b32 s1, 0x49800000
	v_fma_f32 v98, v98, s1, 0.5
	v_trunc_f32_e32 v98, v98
	v_mul_f32_e32 v99, 0x2f800000, v98
	v_floor_f32_e32 v99, v99
	v_fmac_f32_e32 v98, 0xcf800000, v99
	v_cvt_u32_f32_e32 v98, v98
	v_cvt_u32_f32_e32 v99, v99
	global_atomic_add_x2 v[114:115], v[98:99], off offset:128
.LBB0_1521:
	s_or_b64 exec, exec, s[2:3]
	v_or_b32_e32 v98, 32, v144
	v_ashrrev_i32_e32 v99, 31, v98
	v_lshlrev_b64 v[98:99], 11, v[98:99]
	v_lshl_add_u64 v[98:99], v[98:99], 0, v[142:143]
	v_lshlrev_b64 v[102:103], 1, v[98:99]
	v_lshl_add_u64 v[104:105], s[12:13], 0, v[102:103]
	v_mov_b32_e32 v98, v166
	v_mov_b32_e32 v99, v167
	v_mov_b32_e32 v100, v168
	v_mov_b32_e32 v101, v169
	v_lshlrev_b32_e32 v106, 16, v98
	v_and_b32_e32 v98, 0xffff0000, v98
	v_lshlrev_b32_e32 v107, 16, v99
	v_and_b32_e32 v99, 0xffff0000, v99
	v_lshlrev_b32_e32 v108, 16, v100
	v_and_b32_e32 v100, 0xffff0000, v100
	v_lshlrev_b32_e32 v109, 16, v101
	v_and_b32_e32 v101, 0xffff0000, v101
	v_fmac_f32_e32 v106, 0.5, v94
	v_fmac_f32_e32 v108, 0.5, v90
	v_fmac_f32_e32 v98, 0.5, v95
	v_fmac_f32_e32 v100, 0.5, v91
	v_fmac_f32_e32 v107, 0.5, v96
	v_fmac_f32_e32 v109, 0.5, v92
	v_fmac_f32_e32 v99, 0.5, v97
	v_fmac_f32_e32 v101, 0.5, v93
	v_cvt_pk_bf16_f32 v90, v106, v98
	v_cvt_pk_bf16_f32 v91, v107, v99
	v_cvt_pk_bf16_f32 v92, v108, v100
	v_cvt_pk_bf16_f32 v93, v109, v101
	v_mov_b32_e32 v94, v216
	v_mov_b32_e32 v95, v217
	v_mov_b32_e32 v96, v218
	v_mov_b32_e32 v97, v219
	v_lshl_add_u64 v[98:99], s[20:21], 0, v[102:103]
	global_store_dwordx4 v[104:105], v[90:93], off
	global_store_dwordx4 v[98:99], v[90:93], off
	v_lshlrev_b32_e32 v100, 16, v90
	v_lshlrev_b32_e32 v101, 16, v91
	v_and_b32_e32 v90, 0xffff0000, v90
	v_and_b32_e32 v91, 0xffff0000, v91
	v_lshlrev_b32_e32 v102, 16, v92
	v_and_b32_e32 v92, 0xffff0000, v92
	v_lshlrev_b32_e32 v103, 16, v93
	v_and_b32_e32 v93, 0xffff0000, v93
	v_mul_f32_e32 v90, v90, v90
	v_mul_f32_e32 v91, v91, v91
	v_mul_f32_e32 v92, v92, v92
; __device__ __forceinline__ unsigned cvt_pk_bf16(float lo, float hi) { unsigned r; asm volatile("v_cvt_pk_bf16_f32 %0, %1, %2" : "=v"(r) : "v"(lo), "v"(hi)); return r; }
;     __device__ __forceinline__ void operator()(const f32x4 (&acc)[2][2][4][2], const Unit& u, int wr, int wc, int fr, int fq) const {
;     ...
;             for (int m = 0; m < 4; ++m) { const int row = row0 + ai * HALF + m * 16; const size_t ro = (size_t)row * ldc + col0;
;                 float rs = 1.0f; if (GATED) rs = rs_of(rsq_in, row);
;                 float ss = 0.f;
; #pragma unroll
;                 for (int bj = 0; bj < 2; ++bj) { u32x4* p = (u32x4*)(H + ro + bj * HALF); const u32x4 hw = *p; const f32x4 a0 = acc[ai][bj][m][0], a1 = acc[ai][bj][m][1];
;                     float h[8] = {bf_lo(hw.x), bf_hi(hw.x), bf_lo(hw.y), bf_hi(hw.y), bf_lo(hw.z), bf_hi(hw.z), bf_lo(hw.w), bf_hi(hw.w)};
;                     if (GATED) { const u32x4 pw = *(const u32x4*)(PP + ro + bj * HALF);
;                         const float pp[8] = {bf_lo(pw.x), bf_hi(pw.x), bf_lo(pw.y), bf_hi(pw.y), bf_lo(pw.z), bf_hi(pw.z), bf_lo(pw.w), bf_hi(pw.w)};
; #pragma unroll
;                         for (int j = 0; j < 4; ++j) { h[j] += __builtin_amdgcn_rcpf(1.0f + __builtin_amdgcn_exp2f(-1.4426950408889634f * rs * a0[j])) * pp[j];
;                                                       h[4 + j] += __builtin_amdgcn_rcpf(1.0f + __builtin_amdgcn_exp2f(-1.4426950408889634f * rs * a1[j])) * pp[4 + j]; } }
;                     else {
; #pragma unroll
;                         for (int j = 0; j < 4; ++j) { h[j] += a0[j] * scale; h[4 + j] += a1[j] * scale; } }
;                     u32x4 w; w.x = cvt_pk_bf16(h[0], h[1]); w.y = cvt_pk_bf16(h[2], h[3]); w.z = cvt_pk_bf16(h[4], h[5]); w.w = cvt_pk_bf16(h[6], h[7]);
;                     *p = w; if (CP) *(u32x4*)(CP + ro + bj * HALF) = w;
;                     if (rsq_out) { const float r0 = bf_lo(w.x), r1 = bf_hi(w.x), r2 = bf_lo(w.y), r3 = bf_hi(w.y), r4 = bf_lo(w.z), r5 = bf_hi(w.z), r6 = bf_lo(w.w), r7 = bf_hi(w.w);
;                         ss += ((r0 * r0 + r1 * r1) + (r2 * r2 + r3 * r3)) + ((r4 * r4 + r5 * r5) + (r6 * r6 + r7 * r7)); } }
;                 if (rsq_out) { ss = sum_fq(ss); if (fq == 0) __hip_atomic_fetch_add(rsq_out + row, rsq_fix(ss), __ATOMIC_RELAXED, __HIP_MEMORY_SCOPE_AGENT); } }
	v_mul_f32_e32 v93, v93, v93
	v_fmac_f32_e32 v90, v100, v100
	v_fmac_f32_e32 v91, v101, v101
	v_fmac_f32_e32 v92, v102, v102
	v_fmac_f32_e32 v93, v103, v103
	v_add_f32_e32 v90, v90, v91
	v_add_f32_e32 v91, v92, v93
	v_add_f32_e32 v90, v90, v91
	v_lshlrev_b32_e32 v91, 16, v94
	v_and_b32_e32 v92, 0xffff0000, v94
	v_lshlrev_b32_e32 v93, 16, v95
	v_and_b32_e32 v94, 0xffff0000, v95
	v_lshlrev_b32_e32 v95, 16, v96
	v_and_b32_e32 v96, 0xffff0000, v96
	v_lshlrev_b32_e32 v100, 16, v97
	v_and_b32_e32 v97, 0xffff0000, v97
	v_fmac_f32_e32 v91, 0.5, v86
	v_fmac_f32_e32 v95, 0.5, v82
	v_fmac_f32_e32 v92, 0.5, v87
	v_fmac_f32_e32 v96, 0.5, v83
	v_fmac_f32_e32 v93, 0.5, v88
	v_fmac_f32_e32 v100, 0.5, v84
	v_fmac_f32_e32 v94, 0.5, v89
	v_fmac_f32_e32 v97, 0.5, v85
	v_cvt_pk_bf16_f32 v82, v91, v92
	v_cvt_pk_bf16_f32 v83, v93, v94
	v_cvt_pk_bf16_f32 v84, v95, v96
	v_cvt_pk_bf16_f32 v85, v100, v97
	global_store_dwordx4 v[104:105], v[82:85], off offset:256
	global_store_dwordx4 v[98:99], v[82:85], off offset:256
	v_lshlrev_b32_e32 v86, 16, v82
	v_lshlrev_b32_e32 v87, 16, v83
	v_and_b32_e32 v82, 0xffff0000, v82
	v_and_b32_e32 v83, 0xffff0000, v83
	v_lshlrev_b32_e32 v88, 16, v84
	v_and_b32_e32 v84, 0xffff0000, v84
	v_lshlrev_b32_e32 v89, 16, v85
	v_and_b32_e32 v85, 0xffff0000, v85
	v_mul_f32_e32 v82, v82, v82
	v_mul_f32_e32 v83, v83, v83
	v_mul_f32_e32 v84, v84, v84
	v_mul_f32_e32 v85, v85, v85
	v_fmac_f32_e32 v82, v86, v86
	v_fmac_f32_e32 v83, v87, v87
	v_fmac_f32_e32 v84, v88, v88
	v_fmac_f32_e32 v85, v89, v89
	v_add_f32_e32 v82, v82, v83
	v_add_f32_e32 v83, v84, v85
	v_add_f32_e32 v82, v82, v83
	v_add_f32_e32 v82, v90, v82
	v_mov_b32_e32 v83, v82
	s_nop 1
	v_permlane16_swap_b32_e32 v82, v83
	v_add_f32_e32 v82, v82, v83
	v_mov_b32_e32 v83, v82
	s_nop 1
	v_permlane32_swap_b32_e32 v82, v83
	s_and_saveexec_b64 s[2:3], s[4:5]
	s_cbranch_execz .LBB0_1523
	v_add_f32_e32 v82, v82, v83
	s_mov_b32 s1, 0x49800000
	v_fma_f32 v82, v82, s1, 0.5
	v_trunc_f32_e32 v82, v82
	v_mul_f32_e32 v83, 0x2f800000, v82
	v_floor_f32_e32 v83, v83
	v_fmac_f32_e32 v82, 0xcf800000, v83
	v_cvt_u32_f32_e32 v82, v82
	v_cvt_u32_f32_e32 v83, v83
	global_atomic_add_x2 v[114:115], v[82:83], off offset:256
.LBB0_1523:
	s_or_b64 exec, exec, s[2:3]
	v_or_b32_e32 v82, 48, v144
	v_ashrrev_i32_e32 v83, 31, v82
	v_lshlrev_b64 v[82:83], 11, v[82:83]
	v_lshl_add_u64 v[82:83], v[82:83], 0, v[142:143]
	v_lshlrev_b64 v[86:87], 1, v[82:83]
	v_lshl_add_u64 v[88:89], s[12:13], 0, v[86:87]
	v_mov_b32_e32 v82, v170
	v_mov_b32_e32 v83, v171
	v_mov_b32_e32 v84, v172
	v_mov_b32_e32 v85, v173
	v_lshlrev_b32_e32 v90, 16, v82
	v_and_b32_e32 v82, 0xffff0000, v82
	v_lshlrev_b32_e32 v91, 16, v83
	v_and_b32_e32 v83, 0xffff0000, v83
	v_lshlrev_b32_e32 v92, 16, v84
	v_and_b32_e32 v84, 0xffff0000, v84
	v_lshlrev_b32_e32 v93, 16, v85
	v_and_b32_e32 v85, 0xffff0000, v85
	v_fmac_f32_e32 v90, 0.5, v78
	v_fmac_f32_e32 v92, 0.5, v74
	v_fmac_f32_e32 v82, 0.5, v79
	v_fmac_f32_e32 v84, 0.5, v75
	v_fmac_f32_e32 v91, 0.5, v80
	v_fmac_f32_e32 v93, 0.5, v76
	v_fmac_f32_e32 v83, 0.5, v81
	v_fmac_f32_e32 v85, 0.5, v77
	v_cvt_pk_bf16_f32 v74, v90, v82
	v_cvt_pk_bf16_f32 v75, v91, v83
	v_cvt_pk_bf16_f32 v76, v92, v84
	v_cvt_pk_bf16_f32 v77, v93, v85
	v_mov_b32_e32 v78, v220
	v_mov_b32_e32 v79, v221
	v_mov_b32_e32 v80, v222
	v_mov_b32_e32 v81, v223
	v_lshl_add_u64 v[82:83], s[20:21], 0, v[86:87]
	global_store_dwordx4 v[88:89], v[74:77], off
	global_store_dwordx4 v[82:83], v[74:77], off
	v_lshlrev_b32_e32 v84, 16, v74
	v_lshlrev_b32_e32 v85, 16, v75
	v_and_b32_e32 v74, 0xffff0000, v74
	v_and_b32_e32 v75, 0xffff0000, v75
	v_lshlrev_b32_e32 v86, 16, v76
	v_and_b32_e32 v76, 0xffff0000, v76
	v_lshlrev_b32_e32 v87, 16, v77
	v_and_b32_e32 v77, 0xffff0000, v77
	v_mul_f32_e32 v74, v74, v74
	v_mul_f32_e32 v75, v75, v75
	v_mul_f32_e32 v76, v76, v76
	v_mul_f32_e32 v77, v77, v77
	v_fmac_f32_e32 v74, v84, v84
	v_fmac_f32_e32 v75, v85, v85
	v_fmac_f32_e32 v76, v86, v86
	v_fmac_f32_e32 v77, v87, v87
	v_add_f32_e32 v74, v74, v75
	v_add_f32_e32 v75, v76, v77
	v_add_f32_e32 v74, v74, v75
	v_lshlrev_b32_e32 v75, 16, v78
	v_and_b32_e32 v76, 0xffff0000, v78
	v_lshlrev_b32_e32 v77, 16, v79
	v_and_b32_e32 v78, 0xffff0000, v79
	v_lshlrev_b32_e32 v79, 16, v80
	v_and_b32_e32 v80, 0xffff0000, v80
	v_lshlrev_b32_e32 v84, 16, v81
	v_and_b32_e32 v81, 0xffff0000, v81
	v_fmac_f32_e32 v75, 0.5, v70
	v_fmac_f32_e32 v79, 0.5, v66
	v_fmac_f32_e32 v76, 0.5, v71
	v_fmac_f32_e32 v80, 0.5, v67
	v_fmac_f32_e32 v77, 0.5, v72
	v_fmac_f32_e32 v84, 0.5, v68
	v_fmac_f32_e32 v78, 0.5, v73
	v_fmac_f32_e32 v81, 0.5, v69
	v_cvt_pk_bf16_f32 v66, v75, v76
	v_cvt_pk_bf16_f32 v67, v77, v78
	v_cvt_pk_bf16_f32 v68, v79, v80
	v_cvt_pk_bf16_f32 v69, v84, v81
	global_store_dwordx4 v[88:89], v[66:69], off offset:256
	global_store_dwordx4 v[82:83], v[66:69], off offset:256
	v_lshlrev_b32_e32 v70, 16, v66
	v_lshlrev_b32_e32 v71, 16, v67
	v_and_b32_e32 v66, 0xffff0000, v66
	v_and_b32_e32 v67, 0xffff0000, v67
	v_lshlrev_b32_e32 v72, 16, v68
	v_and_b32_e32 v68, 0xffff0000, v68
	v_lshlrev_b32_e32 v73, 16, v69
	v_and_b32_e32 v69, 0xffff0000, v69
	v_mul_f32_e32 v66, v66, v66
	v_mul_f32_e32 v67, v67, v67
	v_mul_f32_e32 v68, v68, v68
	v_mul_f32_e32 v69, v69, v69
	v_fmac_f32_e32 v66, v70, v70
	v_fmac_f32_e32 v67, v71, v71
	v_fmac_f32_e32 v68, v72, v72
	v_fmac_f32_e32 v69, v73, v73
	v_add_f32_e32 v66, v66, v67
	v_add_f32_e32 v67, v68, v69
	v_add_f32_e32 v66, v66, v67
	v_add_f32_e32 v66, v74, v66
	v_mov_b32_e32 v67, v66
	s_nop 1
	v_permlane16_swap_b32_e32 v66, v67
	v_add_f32_e32 v66, v66, v67
	v_mov_b32_e32 v67, v66
	s_nop 1
	v_permlane32_swap_b32_e32 v66, v67
	s_and_saveexec_b64 s[2:3], s[4:5]
	s_cbranch_execz .LBB0_1525
	v_add_f32_e32 v66, v66, v67
	s_mov_b32 s1, 0x49800000
	v_fma_f32 v66, v66, s1, 0.5
	v_trunc_f32_e32 v66, v66
	v_mul_f32_e32 v67, 0x2f800000, v66
	v_floor_f32_e32 v67, v67
	v_fmac_f32_e32 v66, 0xcf800000, v67
	v_cvt_u32_f32_e32 v66, v66
	v_cvt_u32_f32_e32 v67, v67
	global_atomic_add_x2 v[114:115], v[66:67], off offset:384
; __device__ __forceinline__ unsigned cvt_pk_bf16(float lo, float hi) { unsigned r; asm volatile("v_cvt_pk_bf16_f32 %0, %1, %2" : "=v"(r) : "v"(lo), "v"(hi)); return r; }
;     __device__ __forceinline__ void operator()(const f32x4 (&acc)[2][2][4][2], const Unit& u, int wr, int wc, int fr, int fq) const {
;     ...
;             for (int m = 0; m < 4; ++m) { const int row = row0 + ai * HALF + m * 16; const size_t ro = (size_t)row * ldc + col0;
;                 float rs = 1.0f; if (GATED) rs = rs_of(rsq_in, row);
;                 float ss = 0.f;
; #pragma unroll
;                 for (int bj = 0; bj < 2; ++bj) { u32x4* p = (u32x4*)(H + ro + bj * HALF); const u32x4 hw = *p; const f32x4 a0 = acc[ai][bj][m][0], a1 = acc[ai][bj][m][1];
;                     float h[8] = {bf_lo(hw.x), bf_hi(hw.x), bf_lo(hw.y), bf_hi(hw.y), bf_lo(hw.z), bf_hi(hw.z), bf_lo(hw.w), bf_hi(hw.w)};
;                     if (GATED) { const u32x4 pw = *(const u32x4*)(PP + ro + bj * HALF);
;                         const float pp[8] = {bf_lo(pw.x), bf_hi(pw.x), bf_lo(pw.y), bf_hi(pw.y), bf_lo(pw.z), bf_hi(pw.z), bf_lo(pw.w), bf_hi(pw.w)};
; #pragma unroll
;                         for (int j = 0; j < 4; ++j) { h[j] += __builtin_amdgcn_rcpf(1.0f + __builtin_amdgcn_exp2f(-1.4426950408889634f * rs * a0[j])) * pp[j];
;                                                       h[4 + j] += __builtin_amdgcn_rcpf(1.0f + __builtin_amdgcn_exp2f(-1.4426950408889634f * rs * a1[j])) * pp[4 + j]; } }
;                     else {
; #pragma unroll
;                         for (int j = 0; j < 4; ++j) { h[j] += a0[j] * scale; h[4 + j] += a1[j] * scale; } }
;                     u32x4 w; w.x = cvt_pk_bf16(h[0], h[1]); w.y = cvt_pk_bf16(h[2], h[3]); w.z = cvt_pk_bf16(h[4], h[5]); w.w = cvt_pk_bf16(h[6], h[7]);
;                     *p = w; if (CP) *(u32x4*)(CP + ro + bj * HALF) = w;
;                     if (rsq_out) { const float r0 = bf_lo(w.x), r1 = bf_hi(w.x), r2 = bf_lo(w.y), r3 = bf_hi(w.y), r4 = bf_lo(w.z), r5 = bf_hi(w.z), r6 = bf_lo(w.w), r7 = bf_hi(w.w);
;                         ss += ((r0 * r0 + r1 * r1) + (r2 * r2 + r3 * r3)) + ((r4 * r4 + r5 * r5) + (r6 * r6 + r7 * r7)); } }
;                 if (rsq_out) { ss = sum_fq(ss); if (fq == 0) __hip_atomic_fetch_add(rsq_out + row, rsq_fix(ss), __ATOMIC_RELAXED, __HIP_MEMORY_SCOPE_AGENT); } }
.LBB0_1525:
	s_or_b64 exec, exec, s[2:3]
	v_mov_b64_e32 v[66:67], 0x80000
	v_lshl_add_u64 v[70:71], v[140:141], 1, v[66:67]
	v_lshl_add_u64 v[72:73], s[12:13], 0, v[70:71]
	v_mov_b32_e32 v66, v174
	v_mov_b32_e32 v67, v175
	v_mov_b32_e32 v68, v176
	v_mov_b32_e32 v69, v177
	v_lshlrev_b32_e32 v74, 16, v66
	v_and_b32_e32 v66, 0xffff0000, v66
	v_lshlrev_b32_e32 v75, 16, v67
	v_and_b32_e32 v67, 0xffff0000, v67
	v_lshlrev_b32_e32 v76, 16, v68
	v_and_b32_e32 v68, 0xffff0000, v68
	v_lshlrev_b32_e32 v77, 16, v69
	v_and_b32_e32 v69, 0xffff0000, v69
	v_fmac_f32_e32 v74, 0.5, v62
	v_fmac_f32_e32 v76, 0.5, v58
	v_fmac_f32_e32 v66, 0.5, v63
	v_fmac_f32_e32 v68, 0.5, v59
	v_fmac_f32_e32 v75, 0.5, v64
	v_fmac_f32_e32 v77, 0.5, v60
	v_fmac_f32_e32 v67, 0.5, v65
	v_fmac_f32_e32 v69, 0.5, v61
	v_cvt_pk_bf16_f32 v58, v74, v66
	v_cvt_pk_bf16_f32 v59, v75, v67
	v_cvt_pk_bf16_f32 v60, v76, v68
	v_cvt_pk_bf16_f32 v61, v77, v69
	global_load_dwordx4 v[62:65], v[72:73], off offset:256
	v_lshl_add_u64 v[66:67], s[20:21], 0, v[70:71]
	global_store_dwordx4 v[72:73], v[58:61], off
	global_store_dwordx4 v[66:67], v[58:61], off
	v_lshlrev_b32_e32 v68, 16, v58
	v_lshlrev_b32_e32 v69, 16, v59
	v_and_b32_e32 v58, 0xffff0000, v58
	v_and_b32_e32 v59, 0xffff0000, v59
	v_lshlrev_b32_e32 v70, 16, v60
	v_and_b32_e32 v60, 0xffff0000, v60
	v_lshlrev_b32_e32 v71, 16, v61
	v_and_b32_e32 v61, 0xffff0000, v61
	v_mul_f32_e32 v58, v58, v58
	v_mul_f32_e32 v59, v59, v59
	v_mul_f32_e32 v60, v60, v60
	v_mul_f32_e32 v61, v61, v61
	v_fmac_f32_e32 v58, v68, v68
	v_fmac_f32_e32 v59, v69, v69
	v_fmac_f32_e32 v60, v70, v70
	v_fmac_f32_e32 v61, v71, v71
	v_add_f32_e32 v58, v58, v59
	v_add_f32_e32 v59, v60, v61
	v_add_f32_e32 v58, v58, v59
	s_waitcnt vmcnt(2)
	v_lshlrev_b32_e32 v59, 16, v62
	v_and_b32_e32 v60, 0xffff0000, v62
	v_lshlrev_b32_e32 v61, 16, v63
	v_and_b32_e32 v62, 0xffff0000, v63
	v_lshlrev_b32_e32 v63, 16, v64
	v_and_b32_e32 v64, 0xffff0000, v64
	v_lshlrev_b32_e32 v68, 16, v65
	v_and_b32_e32 v65, 0xffff0000, v65
	v_fmac_f32_e32 v59, 0.5, v54
	v_fmac_f32_e32 v63, 0.5, v50
	v_fmac_f32_e32 v60, 0.5, v55
	v_fmac_f32_e32 v64, 0.5, v51
	v_fmac_f32_e32 v61, 0.5, v56
	v_fmac_f32_e32 v68, 0.5, v52
	v_fmac_f32_e32 v62, 0.5, v57
	v_fmac_f32_e32 v65, 0.5, v53
	v_cvt_pk_bf16_f32 v50, v59, v60
	v_cvt_pk_bf16_f32 v51, v61, v62
	v_cvt_pk_bf16_f32 v52, v63, v64
	v_cvt_pk_bf16_f32 v53, v68, v65
	global_store_dwordx4 v[72:73], v[50:53], off offset:256
	global_store_dwordx4 v[66:67], v[50:53], off offset:256
	v_lshlrev_b32_e32 v54, 16, v50
	v_lshlrev_b32_e32 v55, 16, v51
	v_and_b32_e32 v50, 0xffff0000, v50
	v_and_b32_e32 v51, 0xffff0000, v51
	v_lshlrev_b32_e32 v56, 16, v52
	v_and_b32_e32 v52, 0xffff0000, v52
	v_lshlrev_b32_e32 v57, 16, v53
	v_and_b32_e32 v53, 0xffff0000, v53
	v_mul_f32_e32 v50, v50, v50
	v_mul_f32_e32 v51, v51, v51
	v_mul_f32_e32 v52, v52, v52
	v_mul_f32_e32 v53, v53, v53
	v_fmac_f32_e32 v50, v54, v54
	v_fmac_f32_e32 v51, v55, v55
	v_fmac_f32_e32 v52, v56, v56
	v_fmac_f32_e32 v53, v57, v57
	v_add_f32_e32 v50, v50, v51
	v_add_f32_e32 v51, v52, v53
	v_add_f32_e32 v50, v50, v51
	v_add_f32_e32 v50, v58, v50
	v_mov_b32_e32 v51, v50
	s_nop 1
	v_permlane16_swap_b32_e32 v50, v51
	v_add_f32_e32 v50, v50, v51
	v_mov_b32_e32 v51, v50
	s_nop 1
	v_permlane32_swap_b32_e32 v50, v51
	s_and_saveexec_b64 s[2:3], s[4:5]
	s_cbranch_execz .LBB0_1527
	v_add_f32_e32 v50, v50, v51
	s_mov_b32 s1, 0x49800000
	v_fma_f32 v50, v50, s1, 0.5
	v_trunc_f32_e32 v50, v50
	v_mul_f32_e32 v51, 0x2f800000, v50
	v_floor_f32_e32 v51, v51
	v_fmac_f32_e32 v50, 0xcf800000, v51
	v_cvt_u32_f32_e32 v50, v50
	v_cvt_u32_f32_e32 v51, v51
	global_atomic_add_x2 v[114:115], v[50:51], off offset:1024
.LBB0_1527:
	s_or_b64 exec, exec, s[2:3]
	v_mov_b64_e32 v[50:51], 0x90000
	v_lshl_add_u64 v[54:55], v[140:141], 1, v[50:51]
	v_lshl_add_u64 v[56:57], s[12:13], 0, v[54:55]
	v_mov_b32_e32 v50, v186
	v_mov_b32_e32 v51, v187
	v_mov_b32_e32 v52, v188
	v_mov_b32_e32 v53, v189
	v_lshlrev_b32_e32 v58, 16, v50
	v_and_b32_e32 v50, 0xffff0000, v50
	v_lshlrev_b32_e32 v59, 16, v51
	v_and_b32_e32 v51, 0xffff0000, v51
	v_lshlrev_b32_e32 v60, 16, v52
	v_and_b32_e32 v52, 0xffff0000, v52
	v_lshlrev_b32_e32 v61, 16, v53
	v_and_b32_e32 v53, 0xffff0000, v53
	v_fmac_f32_e32 v58, 0.5, v46
	v_fmac_f32_e32 v60, 0.5, v42
	v_fmac_f32_e32 v50, 0.5, v47
	v_fmac_f32_e32 v52, 0.5, v43
	v_fmac_f32_e32 v59, 0.5, v48
	v_fmac_f32_e32 v61, 0.5, v44
	v_fmac_f32_e32 v51, 0.5, v49
	v_fmac_f32_e32 v53, 0.5, v45
	v_cvt_pk_bf16_f32 v42, v58, v50
	v_cvt_pk_bf16_f32 v43, v59, v51
	v_cvt_pk_bf16_f32 v44, v60, v52
	v_cvt_pk_bf16_f32 v45, v61, v53
	global_load_dwordx4 v[46:49], v[56:57], off offset:256
	v_lshl_add_u64 v[50:51], s[20:21], 0, v[54:55]
	global_store_dwordx4 v[56:57], v[42:45], off
	global_store_dwordx4 v[50:51], v[42:45], off
	v_lshlrev_b32_e32 v52, 16, v42
	v_lshlrev_b32_e32 v53, 16, v43
	v_and_b32_e32 v42, 0xffff0000, v42
	v_and_b32_e32 v43, 0xffff0000, v43
	v_lshlrev_b32_e32 v54, 16, v44
	v_and_b32_e32 v44, 0xffff0000, v44
	v_lshlrev_b32_e32 v55, 16, v45
	v_and_b32_e32 v45, 0xffff0000, v45
	v_mul_f32_e32 v42, v42, v42
	v_mul_f32_e32 v43, v43, v43
	v_mul_f32_e32 v44, v44, v44
	v_mul_f32_e32 v45, v45, v45
	v_fmac_f32_e32 v42, v52, v52
	v_fmac_f32_e32 v43, v53, v53
	v_fmac_f32_e32 v44, v54, v54
	v_fmac_f32_e32 v45, v55, v55
	v_add_f32_e32 v42, v42, v43
	v_add_f32_e32 v43, v44, v45
	v_add_f32_e32 v42, v42, v43
	s_waitcnt vmcnt(2)
	v_lshlrev_b32_e32 v43, 16, v46
	v_and_b32_e32 v44, 0xffff0000, v46
	v_lshlrev_b32_e32 v45, 16, v47
	v_and_b32_e32 v46, 0xffff0000, v47
	v_lshlrev_b32_e32 v47, 16, v48
	v_and_b32_e32 v48, 0xffff0000, v48
	v_lshlrev_b32_e32 v52, 16, v49
	v_and_b32_e32 v49, 0xffff0000, v49
	v_fmac_f32_e32 v43, 0.5, v38
	v_fmac_f32_e32 v47, 0.5, v34
	v_fmac_f32_e32 v44, 0.5, v39
	v_fmac_f32_e32 v48, 0.5, v35
	v_fmac_f32_e32 v45, 0.5, v40
	v_fmac_f32_e32 v52, 0.5, v36
	v_fmac_f32_e32 v46, 0.5, v41
	v_fmac_f32_e32 v49, 0.5, v37
	v_cvt_pk_bf16_f32 v34, v43, v44
	v_cvt_pk_bf16_f32 v35, v45, v46
	v_cvt_pk_bf16_f32 v36, v47, v48
	v_cvt_pk_bf16_f32 v37, v52, v49
	global_store_dwordx4 v[56:57], v[34:37], off offset:256
	global_store_dwordx4 v[50:51], v[34:37], off offset:256
	v_lshlrev_b32_e32 v38, 16, v34
	v_lshlrev_b32_e32 v39, 16, v35
	v_and_b32_e32 v34, 0xffff0000, v34
	v_and_b32_e32 v35, 0xffff0000, v35
	v_lshlrev_b32_e32 v40, 16, v36
	v_and_b32_e32 v36, 0xffff0000, v36
	v_lshlrev_b32_e32 v41, 16, v37
	v_and_b32_e32 v37, 0xffff0000, v37
	v_mul_f32_e32 v34, v34, v34
	v_mul_f32_e32 v35, v35, v35
	v_mul_f32_e32 v36, v36, v36
	v_mul_f32_e32 v37, v37, v37
	v_fmac_f32_e32 v34, v38, v38
	v_fmac_f32_e32 v35, v39, v39
	v_fmac_f32_e32 v36, v40, v40
	v_fmac_f32_e32 v37, v41, v41
	v_add_f32_e32 v34, v34, v35
	v_add_f32_e32 v35, v36, v37
	v_add_f32_e32 v34, v34, v35
	v_add_f32_e32 v34, v42, v34
	v_mov_b32_e32 v35, v34
	s_nop 1
	v_permlane16_swap_b32_e32 v34, v35
	v_add_f32_e32 v34, v34, v35
	v_mov_b32_e32 v35, v34
	s_nop 1
	v_permlane32_swap_b32_e32 v34, v35
	s_and_saveexec_b64 s[2:3], s[4:5]
	s_cbranch_execz .LBB0_1529
; __device__ __forceinline__ unsigned cvt_pk_bf16(float lo, float hi) { unsigned r; asm volatile("v_cvt_pk_bf16_f32 %0, %1, %2" : "=v"(r) : "v"(lo), "v"(hi)); return r; }
;     __device__ __forceinline__ void operator()(const f32x4 (&acc)[2][2][4][2], const Unit& u, int wr, int wc, int fr, int fq) const {
;     ...
;             for (int m = 0; m < 4; ++m) { const int row = row0 + ai * HALF + m * 16; const size_t ro = (size_t)row * ldc + col0;
;                 float rs = 1.0f; if (GATED) rs = rs_of(rsq_in, row);
;                 float ss = 0.f;
; #pragma unroll
;                 for (int bj = 0; bj < 2; ++bj) { u32x4* p = (u32x4*)(H + ro + bj * HALF); const u32x4 hw = *p; const f32x4 a0 = acc[ai][bj][m][0], a1 = acc[ai][bj][m][1];
;                     float h[8] = {bf_lo(hw.x), bf_hi(hw.x), bf_lo(hw.y), bf_hi(hw.y), bf_lo(hw.z), bf_hi(hw.z), bf_lo(hw.w), bf_hi(hw.w)};
;                     if (GATED) { const u32x4 pw = *(const u32x4*)(PP + ro + bj * HALF);
;                         const float pp[8] = {bf_lo(pw.x), bf_hi(pw.x), bf_lo(pw.y), bf_hi(pw.y), bf_lo(pw.z), bf_hi(pw.z), bf_lo(pw.w), bf_hi(pw.w)};
; #pragma unroll
;                         for (int j = 0; j < 4; ++j) { h[j] += __builtin_amdgcn_rcpf(1.0f + __builtin_amdgcn_exp2f(-1.4426950408889634f * rs * a0[j])) * pp[j];
;                                                       h[4 + j] += __builtin_amdgcn_rcpf(1.0f + __builtin_amdgcn_exp2f(-1.4426950408889634f * rs * a1[j])) * pp[4 + j]; } }
;                     else {
; #pragma unroll
;                         for (int j = 0; j < 4; ++j) { h[j] += a0[j] * scale; h[4 + j] += a1[j] * scale; } }
;                     u32x4 w; w.x = cvt_pk_bf16(h[0], h[1]); w.y = cvt_pk_bf16(h[2], h[3]); w.z = cvt_pk_bf16(h[4], h[5]); w.w = cvt_pk_bf16(h[6], h[7]);
;                     *p = w; if (CP) *(u32x4*)(CP + ro + bj * HALF) = w;
;                     if (rsq_out) { const float r0 = bf_lo(w.x), r1 = bf_hi(w.x), r2 = bf_lo(w.y), r3 = bf_hi(w.y), r4 = bf_lo(w.z), r5 = bf_hi(w.z), r6 = bf_lo(w.w), r7 = bf_hi(w.w);
;                         ss += ((r0 * r0 + r1 * r1) + (r2 * r2 + r3 * r3)) + ((r4 * r4 + r5 * r5) + (r6 * r6 + r7 * r7)); } }
;                 if (rsq_out) { ss = sum_fq(ss); if (fq == 0) __hip_atomic_fetch_add(rsq_out + row, rsq_fix(ss), __ATOMIC_RELAXED, __HIP_MEMORY_SCOPE_AGENT); } }
	v_add_f32_e32 v34, v34, v35
	s_mov_b32 s1, 0x49800000
	v_fma_f32 v34, v34, s1, 0.5
	v_trunc_f32_e32 v34, v34
	v_mul_f32_e32 v35, 0x2f800000, v34
	v_floor_f32_e32 v35, v35
	v_fmac_f32_e32 v34, 0xcf800000, v35
	v_cvt_u32_f32_e32 v34, v34
	v_cvt_u32_f32_e32 v35, v35
	global_atomic_add_x2 v[114:115], v[34:35], off offset:1152
.LBB0_1529:
	s_or_b64 exec, exec, s[2:3]
	v_lshl_add_u64 v[38:39], v[140:141], 1, v[252:253]
	v_lshl_add_u64 v[40:41], s[12:13], 0, v[38:39]
	v_mov_b32_e32 v34, v190
	v_mov_b32_e32 v35, v191
	v_mov_b32_e32 v36, v192
	v_mov_b32_e32 v37, v193
	v_lshlrev_b32_e32 v42, 16, v34
	v_and_b32_e32 v34, 0xffff0000, v34
	v_lshlrev_b32_e32 v43, 16, v35
	v_and_b32_e32 v35, 0xffff0000, v35
	v_lshlrev_b32_e32 v44, 16, v36
	v_and_b32_e32 v36, 0xffff0000, v36
	v_lshlrev_b32_e32 v45, 16, v37
	v_and_b32_e32 v37, 0xffff0000, v37
	v_fmac_f32_e32 v42, 0.5, v30
	v_fmac_f32_e32 v44, 0.5, v26
	v_fmac_f32_e32 v34, 0.5, v31
	v_fmac_f32_e32 v36, 0.5, v27
	v_fmac_f32_e32 v43, 0.5, v32
	v_fmac_f32_e32 v45, 0.5, v28
	v_fmac_f32_e32 v35, 0.5, v33
	v_fmac_f32_e32 v37, 0.5, v29
	v_cvt_pk_bf16_f32 v26, v42, v34
	v_cvt_pk_bf16_f32 v27, v43, v35
	v_cvt_pk_bf16_f32 v28, v44, v36
	v_cvt_pk_bf16_f32 v29, v45, v37
	global_load_dwordx4 v[30:33], v[40:41], off offset:256
	v_lshl_add_u64 v[34:35], s[20:21], 0, v[38:39]
	global_store_dwordx4 v[40:41], v[26:29], off
	global_store_dwordx4 v[34:35], v[26:29], off
	v_lshlrev_b32_e32 v36, 16, v26
	v_lshlrev_b32_e32 v37, 16, v27
	v_and_b32_e32 v26, 0xffff0000, v26
	v_and_b32_e32 v27, 0xffff0000, v27
	v_lshlrev_b32_e32 v38, 16, v28
	v_and_b32_e32 v28, 0xffff0000, v28
	v_lshlrev_b32_e32 v39, 16, v29
	v_and_b32_e32 v29, 0xffff0000, v29
	v_mul_f32_e32 v26, v26, v26
	v_mul_f32_e32 v27, v27, v27
	v_mul_f32_e32 v28, v28, v28
	v_mul_f32_e32 v29, v29, v29
	v_fmac_f32_e32 v26, v36, v36
	v_fmac_f32_e32 v27, v37, v37
	v_fmac_f32_e32 v28, v38, v38
	v_fmac_f32_e32 v29, v39, v39
	v_add_f32_e32 v26, v26, v27
	v_add_f32_e32 v27, v28, v29
	v_add_f32_e32 v26, v26, v27
	s_waitcnt vmcnt(2)
	v_lshlrev_b32_e32 v27, 16, v30
	v_and_b32_e32 v28, 0xffff0000, v30
	v_lshlrev_b32_e32 v29, 16, v31
	v_and_b32_e32 v30, 0xffff0000, v31
	v_lshlrev_b32_e32 v31, 16, v32
	v_and_b32_e32 v32, 0xffff0000, v32
	v_lshlrev_b32_e32 v36, 16, v33
	v_and_b32_e32 v33, 0xffff0000, v33
	v_fmac_f32_e32 v27, 0.5, v22
	v_fmac_f32_e32 v31, 0.5, v18
	v_fmac_f32_e32 v28, 0.5, v23
	v_fmac_f32_e32 v32, 0.5, v19
	v_fmac_f32_e32 v29, 0.5, v24
	v_fmac_f32_e32 v36, 0.5, v20
	v_fmac_f32_e32 v30, 0.5, v25
	v_fmac_f32_e32 v33, 0.5, v21
	v_cvt_pk_bf16_f32 v18, v27, v28
	v_cvt_pk_bf16_f32 v19, v29, v30
	v_cvt_pk_bf16_f32 v20, v31, v32
	v_cvt_pk_bf16_f32 v21, v36, v33
	global_store_dwordx4 v[40:41], v[18:21], off offset:256
	global_store_dwordx4 v[34:35], v[18:21], off offset:256
	v_lshlrev_b32_e32 v22, 16, v18
	v_lshlrev_b32_e32 v23, 16, v19
	v_and_b32_e32 v18, 0xffff0000, v18
	v_and_b32_e32 v19, 0xffff0000, v19
	v_lshlrev_b32_e32 v24, 16, v20
	v_and_b32_e32 v20, 0xffff0000, v20
	v_lshlrev_b32_e32 v25, 16, v21
	v_and_b32_e32 v21, 0xffff0000, v21
	v_mul_f32_e32 v18, v18, v18
	v_mul_f32_e32 v19, v19, v19
	v_mul_f32_e32 v20, v20, v20
	v_mul_f32_e32 v21, v21, v21
	v_fmac_f32_e32 v18, v22, v22
	v_fmac_f32_e32 v19, v23, v23
	v_fmac_f32_e32 v20, v24, v24
	v_fmac_f32_e32 v21, v25, v25
	v_add_f32_e32 v18, v18, v19
	v_add_f32_e32 v19, v20, v21
	v_add_f32_e32 v18, v18, v19
	v_add_f32_e32 v18, v26, v18
	v_mov_b32_e32 v19, v18
	s_nop 1
	v_permlane16_swap_b32_e32 v18, v19
	v_add_f32_e32 v18, v18, v19
	v_mov_b32_e32 v19, v18
	s_nop 1
	v_permlane32_swap_b32_e32 v18, v19
	s_and_saveexec_b64 s[2:3], s[4:5]
	s_cbranch_execz .LBB0_1531
	v_add_f32_e32 v18, v18, v19
	s_mov_b32 s1, 0x49800000
	v_fma_f32 v18, v18, s1, 0.5
	v_trunc_f32_e32 v18, v18
	v_mul_f32_e32 v19, 0x2f800000, v18
	v_floor_f32_e32 v19, v19
	v_fmac_f32_e32 v18, 0xcf800000, v19
	v_cvt_u32_f32_e32 v18, v18
	v_cvt_u32_f32_e32 v19, v19
	global_atomic_add_x2 v[114:115], v[18:19], off offset:1280
; __device__ __forceinline__ unsigned cvt_pk_bf16(float lo, float hi) { unsigned r; asm volatile("v_cvt_pk_bf16_f32 %0, %1, %2" : "=v"(r) : "v"(lo), "v"(hi)); return r; }
;     __device__ __forceinline__ void operator()(const f32x4 (&acc)[2][2][4][2], const Unit& u, int wr, int wc, int fr, int fq) const {
;     ...
;             for (int m = 0; m < 4; ++m) { const int row = row0 + ai * HALF + m * 16; const size_t ro = (size_t)row * ldc + col0;
;                 float rs = 1.0f; if (GATED) rs = rs_of(rsq_in, row);
;                 float ss = 0.f;
; #pragma unroll
;                 for (int bj = 0; bj < 2; ++bj) { u32x4* p = (u32x4*)(H + ro + bj * HALF); const u32x4 hw = *p; const f32x4 a0 = acc[ai][bj][m][0], a1 = acc[ai][bj][m][1];
;                     float h[8] = {bf_lo(hw.x), bf_hi(hw.x), bf_lo(hw.y), bf_hi(hw.y), bf_lo(hw.z), bf_hi(hw.z), bf_lo(hw.w), bf_hi(hw.w)};
;                     if (GATED) { const u32x4 pw = *(const u32x4*)(PP + ro + bj * HALF);
;                         const float pp[8] = {bf_lo(pw.x), bf_hi(pw.x), bf_lo(pw.y), bf_hi(pw.y), bf_lo(pw.z), bf_hi(pw.z), bf_lo(pw.w), bf_hi(pw.w)};
; #pragma unroll
;                         for (int j = 0; j < 4; ++j) { h[j] += __builtin_amdgcn_rcpf(1.0f + __builtin_amdgcn_exp2f(-1.4426950408889634f * rs * a0[j])) * pp[j];
;                                                       h[4 + j] += __builtin_amdgcn_rcpf(1.0f + __builtin_amdgcn_exp2f(-1.4426950408889634f * rs * a1[j])) * pp[4 + j]; } }
;                     else {
; #pragma unroll
;                         for (int j = 0; j < 4; ++j) { h[j] += a0[j] * scale; h[4 + j] += a1[j] * scale; } }
;                     u32x4 w; w.x = cvt_pk_bf16(h[0], h[1]); w.y = cvt_pk_bf16(h[2], h[3]); w.z = cvt_pk_bf16(h[4], h[5]); w.w = cvt_pk_bf16(h[6], h[7]);
;                     *p = w; if (CP) *(u32x4*)(CP + ro + bj * HALF) = w;
;                     if (rsq_out) { const float r0 = bf_lo(w.x), r1 = bf_hi(w.x), r2 = bf_lo(w.y), r3 = bf_hi(w.y), r4 = bf_lo(w.z), r5 = bf_hi(w.z), r6 = bf_lo(w.w), r7 = bf_hi(w.w);
;                         ss += ((r0 * r0 + r1 * r1) + (r2 * r2 + r3 * r3)) + ((r4 * r4 + r5 * r5) + (r6 * r6 + r7 * r7)); } }
;                 if (rsq_out) { ss = sum_fq(ss); if (fq == 0) __hip_atomic_fetch_add(rsq_out + row, rsq_fix(ss), __ATOMIC_RELAXED, __HIP_MEMORY_SCOPE_AGENT); } }
.LBB0_1531:
	s_or_b64 exec, exec, s[2:3]
	v_lshl_add_u64 v[22:23], v[140:141], 1, v[200:201]
	v_lshl_add_u64 v[24:25], s[12:13], 0, v[22:23]
	v_mov_b32_e32 v18, v194
	v_mov_b32_e32 v19, v195
	v_mov_b32_e32 v20, v196
	v_mov_b32_e32 v21, v197
	v_lshlrev_b32_e32 v26, 16, v18
	v_and_b32_e32 v18, 0xffff0000, v18
	v_lshlrev_b32_e32 v27, 16, v19
	v_and_b32_e32 v19, 0xffff0000, v19
	v_lshlrev_b32_e32 v28, 16, v20
	v_and_b32_e32 v20, 0xffff0000, v20
	v_lshlrev_b32_e32 v29, 16, v21
	v_and_b32_e32 v21, 0xffff0000, v21
	v_fmac_f32_e32 v26, 0.5, v14
	v_fmac_f32_e32 v28, 0.5, v10
	v_fmac_f32_e32 v18, 0.5, v15
	v_fmac_f32_e32 v20, 0.5, v11
	v_fmac_f32_e32 v27, 0.5, v16
	v_fmac_f32_e32 v29, 0.5, v12
	v_fmac_f32_e32 v19, 0.5, v17
	v_fmac_f32_e32 v21, 0.5, v13
	v_cvt_pk_bf16_f32 v10, v26, v18
	v_cvt_pk_bf16_f32 v11, v27, v19
	v_cvt_pk_bf16_f32 v12, v28, v20
	v_cvt_pk_bf16_f32 v13, v29, v21
	global_load_dwordx4 v[14:17], v[24:25], off offset:256
	v_lshl_add_u64 v[18:19], s[20:21], 0, v[22:23]
	global_store_dwordx4 v[24:25], v[10:13], off
	global_store_dwordx4 v[18:19], v[10:13], off
	v_lshlrev_b32_e32 v20, 16, v10
	v_lshlrev_b32_e32 v21, 16, v11
	v_and_b32_e32 v10, 0xffff0000, v10
	v_and_b32_e32 v11, 0xffff0000, v11
	v_lshlrev_b32_e32 v22, 16, v12
	v_and_b32_e32 v12, 0xffff0000, v12
	v_lshlrev_b32_e32 v23, 16, v13
	v_and_b32_e32 v13, 0xffff0000, v13
	v_mul_f32_e32 v10, v10, v10
	v_mul_f32_e32 v11, v11, v11
	v_mul_f32_e32 v12, v12, v12
	v_mul_f32_e32 v13, v13, v13
	v_fmac_f32_e32 v10, v20, v20
	v_fmac_f32_e32 v11, v21, v21
	v_fmac_f32_e32 v12, v22, v22
	v_fmac_f32_e32 v13, v23, v23
	v_add_f32_e32 v10, v10, v11
	v_add_f32_e32 v11, v12, v13
	v_add_f32_e32 v10, v10, v11
	s_waitcnt vmcnt(2)
	v_lshlrev_b32_e32 v11, 16, v14
	v_and_b32_e32 v12, 0xffff0000, v14
	v_lshlrev_b32_e32 v13, 16, v15
	v_and_b32_e32 v14, 0xffff0000, v15
	v_lshlrev_b32_e32 v15, 16, v16
	v_and_b32_e32 v16, 0xffff0000, v16
	v_lshlrev_b32_e32 v20, 16, v17
	v_and_b32_e32 v17, 0xffff0000, v17
	v_fmac_f32_e32 v11, 0.5, v6
	v_fmac_f32_e32 v15, 0.5, v2
	v_fmac_f32_e32 v12, 0.5, v7
	v_fmac_f32_e32 v16, 0.5, v3
	v_fmac_f32_e32 v13, 0.5, v8
	v_fmac_f32_e32 v20, 0.5, v4
	v_fmac_f32_e32 v14, 0.5, v9
	v_fmac_f32_e32 v17, 0.5, v5
	v_cvt_pk_bf16_f32 v2, v11, v12
	v_cvt_pk_bf16_f32 v3, v13, v14
	v_cvt_pk_bf16_f32 v4, v15, v16
	v_cvt_pk_bf16_f32 v5, v20, v17
	global_store_dwordx4 v[24:25], v[2:5], off offset:256
	global_store_dwordx4 v[18:19], v[2:5], off offset:256
	v_lshlrev_b32_e32 v6, 16, v2
	v_lshlrev_b32_e32 v7, 16, v3
	v_and_b32_e32 v2, 0xffff0000, v2
	v_and_b32_e32 v3, 0xffff0000, v3
	v_lshlrev_b32_e32 v8, 16, v4
	v_and_b32_e32 v4, 0xffff0000, v4
	v_lshlrev_b32_e32 v9, 16, v5
	v_and_b32_e32 v5, 0xffff0000, v5
	v_mul_f32_e32 v2, v2, v2
	v_mul_f32_e32 v3, v3, v3
	v_mul_f32_e32 v4, v4, v4
	v_mul_f32_e32 v5, v5, v5
	v_fmac_f32_e32 v2, v6, v6
	v_fmac_f32_e32 v3, v7, v7
	v_fmac_f32_e32 v4, v8, v8
	v_fmac_f32_e32 v5, v9, v9
	v_add_f32_e32 v2, v2, v3
	v_add_f32_e32 v3, v4, v5
	v_add_f32_e32 v2, v2, v3
	v_add_f32_e32 v2, v10, v2
	v_mov_b32_e32 v3, v2
	s_nop 1
	v_permlane16_swap_b32_e32 v2, v3
	v_add_f32_e32 v2, v2, v3
	v_mov_b32_e32 v3, v2
	s_nop 1
	v_permlane32_swap_b32_e32 v2, v3
	s_and_saveexec_b64 s[2:3], s[4:5]
	s_cbranch_execz .LBB0_1533
	v_add_f32_e32 v2, v2, v3
	s_mov_b32 s1, 0x49800000
	v_fma_f32 v2, v2, s1, 0.5
	v_trunc_f32_e32 v2, v2
	v_mul_f32_e32 v3, 0x2f800000, v2
	v_floor_f32_e32 v3, v3
	v_fmac_f32_e32 v2, 0xcf800000, v3
	v_cvt_u32_f32_e32 v2, v2
	v_cvt_u32_f32_e32 v3, v3
	global_atomic_add_x2 v[114:115], v[2:3], off offset:1408
